# speedup vs baseline: 1.0066x; 1.0066x over previous
; #define PG8_STAGE(bufoff, gbase, voff) do { _Pragma("unroll") for (int _i = 0; _i < 2; ++_i) \
;         __builtin_amdgcn_global_load_lds((const unsigned*)((const char*)(gbase) + (voff)[_i]), (PG8_LAS unsigned*)(lds + (bufoff) + ldsw + _i * 8192), 16, 0, 0); } while (0)
; #define PG8_LDA(dst, b, h) do { _Pragma("unroll") for (int m = 0; m < 4; ++m) _Pragma("unroll") for (int k = 0; k < 2; ++k) dst[m][k] = *(const PG8_LAS bf16x8*)(lds + PG8_SA(b, h) + aoff + m * 2048 + k * 1024); } while (0)
; #define PG8_LDB(dst, b, h) do { _Pragma("unroll") for (int n = 0; n < 2; ++n) _Pragma("unroll") for (int k = 0; k < 2; ++k) dst[n][k] = *(const PG8_LAS bf16x8*)(lds + PG8_SB(b, h) + boff + n * 2048 + k * 1024); } while (0)
; #define PG8_MMA(ai, bj, At, Bt) do { __builtin_amdgcn_s_setprio(1); _Pragma("unroll") for (int m = 0; m < 4; ++m) _Pragma("unroll") for (int n = 0; n < 2; ++n) _Pragma("unroll") for (int k = 0; k < 2; ++k) \
;         acc[ai][bj][m][n] = __builtin_amdgcn_mfma_f32_16x16x32_bf16(Bt[n][k], At[m][k], acc[ai][bj][m][n], 0, 0, 0); __builtin_amdgcn_s_setprio(0); } while (0)
; #define PG8_WAIT_V(n) asm volatile("s_waitcnt vmcnt(" #n ")" ::: "memory")
; #define PG8_BAR __builtin_amdgcn_s_barrier()
; template <class Epi, class Sched, bool ALIGN_EPI = false, bool SP2 = false>
; __device__ __forceinline__ void gemm_phase(PG8_LAS unsigned char* lds, const Gemm g, const Sched& S, const Epi& E, int wave_s) {
;     ...
;         for (int t = 0; t < nt; t += 2) {
;             const bool last = (t == nt - 2);
;             const char* a1 = cA + (size_t)(t + 1) * kstep;
;             const char* a2 = last ? nA : cA + (size_t)(t + 2) * kstep; const char* b2 = last ? nB : cB + (size_t)(t + 2) * kstep;
;             const char* a3 = a2 + kstep; const char* b3 = b2 + kstep;
;             if (last && has_next) S.a_ready(nxt);
;             if constexpr (SP2) {
;             PG8_LDB(B0, 0, 0); PG8_LDB(B1, 0, 1); PG8_SCHED; PG8_LDA(At, 0, 0); PG8_STAGE(PG8_SA(1, 1), a1 + hstep, voffA);
;             PG8_WAIT_V(8); PG8_WAIT_L(0); PG8_BAR; PG8_MMA(0, 0, At, B0); PG8_MMA(0, 1, At, B1); PG8_BAR; PG8_SCHED;
;             PG8_LDA(At, 0, 1); PG8_STAGE(PG8_SB(0, 0), b2, voffB); PG8_STAGE(PG8_SB(0, 1), b2 + hstep, voffB); PG8_STAGE(PG8_SA(0, 0), a2, voffA);
;             PG8_WAIT_V(8); PG8_WAIT_L(0); PG8_BAR; PG8_MMA(1, 0, At, B0); PG8_MMA(1, 1, At, B1); PG8_BAR; PG8_SCHED;
.LBB0_53:
	s_add_u32 s62, s60, 0x100
	s_addc_u32 s63, s61, 0
	s_add_i32 s3, 0, 0x10000
	s_cmpk_eq_i32 s23, 0x54
	s_cselect_b32 s67, s45, s63
	s_cselect_b32 s66, s44, s62
	v_add_u32_e32 v146, s3, v143
	s_cselect_b32 s65, s59, s22
	s_cselect_b32 s64, s58, s5
	s_add_i32 s26, 0, 0x14000
	ds_read_b128 v[134:137], v146
	ds_read_b128 v[138:141], v146 offset:1024
	ds_read_b128 v[150:153], v146 offset:2048
	ds_read_b128 v[156:159], v146 offset:3072
	v_add_u32_e32 v146, s26, v143
	ds_read_b128 v[160:163], v146
	ds_read_b128 v[164:167], v146 offset:1024
	ds_read_b128 v[168:171], v146 offset:2048
	ds_read_b128 v[172:175], v146 offset:3072
	v_lshl_add_u64 v[146:147], s[60:61], 0, v[130:131]
	s_add_i32 m0, s25, 0xc000
	ds_read_b128 v[176:179], v145
	ds_read_b128 v[180:183], v145 offset:1024
	ds_read_b128 v[184:187], v145 offset:2048
	ds_read_b128 v[188:191], v145 offset:3072
	ds_read_b128 v[206:209], v145 offset:4096
	ds_read_b128 v[210:213], v145 offset:5120
	ds_read_b128 v[214:217], v145 offset:6144
	ds_read_b128 v[218:221], v145 offset:7168
	global_load_lds_dwordx4 v[146:147], off
	v_lshl_add_u64 v[146:147], s[60:61], 0, v[132:133]
	s_add_i32 m0, s25, 0xe000
	s_nop 0
	global_load_lds_dwordx4 v[146:147], off
	s_waitcnt vmcnt(8)
	s_waitcnt lgkmcnt(0)
	s_barrier
	s_setprio 1
	s_waitcnt lgkmcnt(0)
	v_mfma_f32_16x16x32_bf16 v[124:127], v[134:137], v[176:179], v[124:127]
	v_mfma_f32_16x16x32_bf16 v[120:123], v[150:153], v[176:179], v[120:123]
	v_mfma_f32_16x16x32_bf16 v[108:111], v[134:137], v[184:187], v[108:111]
	v_mfma_f32_16x16x32_bf16 v[104:107], v[150:153], v[184:187], v[104:107]
	v_mfma_f32_16x16x32_bf16 v[92:95], v[134:137], v[206:209], v[92:95]
	v_mfma_f32_16x16x32_bf16 v[88:91], v[150:153], v[206:209], v[88:91]
	v_mfma_f32_16x16x32_bf16 v[76:79], v[134:137], v[214:217], v[76:79]
	v_mfma_f32_16x16x32_bf16 v[72:75], v[150:153], v[214:217], v[72:75]
	v_mfma_f32_16x16x32_bf16 v[124:127], v[138:141], v[180:183], v[124:127]
	v_mfma_f32_16x16x32_bf16 v[120:123], v[156:159], v[180:183], v[120:123]
	v_mfma_f32_16x16x32_bf16 v[108:111], v[138:141], v[188:191], v[108:111]
	v_mfma_f32_16x16x32_bf16 v[104:107], v[156:159], v[188:191], v[104:107]
	v_mfma_f32_16x16x32_bf16 v[92:95], v[138:141], v[210:213], v[92:95]
	v_mfma_f32_16x16x32_bf16 v[88:91], v[156:159], v[210:213], v[88:91]
	v_mfma_f32_16x16x32_bf16 v[76:79], v[138:141], v[218:221], v[76:79]
	v_mfma_f32_16x16x32_bf16 v[72:75], v[156:159], v[218:221], v[72:75]
	v_mfma_f32_16x16x32_bf16 v[116:119], v[160:163], v[176:179], v[116:119]
	v_mfma_f32_16x16x32_bf16 v[112:115], v[168:171], v[176:179], v[112:115]
	v_mfma_f32_16x16x32_bf16 v[100:103], v[160:163], v[184:187], v[100:103]
	v_mfma_f32_16x16x32_bf16 v[96:99], v[168:171], v[184:187], v[96:99]
	v_mfma_f32_16x16x32_bf16 v[84:87], v[160:163], v[206:209], v[84:87]
	v_mfma_f32_16x16x32_bf16 v[80:83], v[168:171], v[206:209], v[80:83]
	v_mfma_f32_16x16x32_bf16 v[68:71], v[160:163], v[214:217], v[68:71]
	v_mfma_f32_16x16x32_bf16 v[64:67], v[168:171], v[214:217], v[64:67]
	v_mfma_f32_16x16x32_bf16 v[116:119], v[164:167], v[180:183], v[116:119]
	v_mfma_f32_16x16x32_bf16 v[112:115], v[172:175], v[180:183], v[112:115]
	v_mfma_f32_16x16x32_bf16 v[100:103], v[164:167], v[188:191], v[100:103]
	v_mfma_f32_16x16x32_bf16 v[96:99], v[172:175], v[188:191], v[96:99]
	v_mfma_f32_16x16x32_bf16 v[84:87], v[164:167], v[210:213], v[84:87]
	v_mfma_f32_16x16x32_bf16 v[80:83], v[172:175], v[210:213], v[80:83]
	v_mfma_f32_16x16x32_bf16 v[68:71], v[164:167], v[218:221], v[68:71]
	v_mfma_f32_16x16x32_bf16 v[64:67], v[172:175], v[218:221], v[64:67]
	s_setprio 0
	s_barrier
	s_add_i32 s3, s3, s9
	v_lshl_add_u64 v[146:147], s[64:65], 0, v[148:149]
	s_mov_b32 m0, s3
	ds_read_b128 v[176:179], v145 offset:16384
	ds_read_b128 v[180:183], v145 offset:17408
	ds_read_b128 v[184:187], v145 offset:18432
	ds_read_b128 v[188:191], v145 offset:19456
	ds_read_b128 v[206:209], v145 offset:20480
	ds_read_b128 v[210:213], v145 offset:21504
	ds_read_b128 v[214:217], v145 offset:22528
	ds_read_b128 v[218:221], v145 offset:23552
	global_load_lds_dwordx4 v[146:147], off
	s_add_i32 m0, s3, 0x2000
	s_add_u32 s28, s64, 0x160000
	v_lshl_add_u64 v[222:223], s[64:65], 0, v[128:129]
	s_addc_u32 s29, s65, 0
	s_add_i32 s3, s26, s9
	global_load_lds_dwordx4 v[222:223], off
	v_lshl_add_u64 v[224:225], s[28:29], 0, v[148:149]
	s_mov_b32 m0, s3
	v_lshl_add_u64 v[226:227], s[66:67], 0, v[128:129]
	global_load_lds_dwordx4 v[224:225], off
	v_lshl_add_u64 v[224:225], s[28:29], 0, v[128:129]
	s_add_i32 m0, s3, 0x2000
	s_nop 0
	global_load_lds_dwordx4 v[224:225], off
	v_lshl_add_u64 v[224:225], s[66:67], 0, v[148:149]
	s_mov_b32 m0, s25
	s_nop 0
	global_load_lds_dwordx4 v[224:225], off
	s_mov_b32 m0, s73
	s_nop 0
	global_load_lds_dwordx4 v[226:227], off
	s_waitcnt vmcnt(8)
	s_waitcnt lgkmcnt(0)
	s_barrier
; #define PG8_STAGE(bufoff, gbase, voff) do { _Pragma("unroll") for (int _i = 0; _i < 2; ++_i) \
;         __builtin_amdgcn_global_load_lds((const unsigned*)((const char*)(gbase) + (voff)[_i]), (PG8_LAS unsigned*)(lds + (bufoff) + ldsw + _i * 8192), 16, 0, 0); } while (0)
; #define PG8_LDA(dst, b, h) do { _Pragma("unroll") for (int m = 0; m < 4; ++m) _Pragma("unroll") for (int k = 0; k < 2; ++k) dst[m][k] = *(const PG8_LAS bf16x8*)(lds + PG8_SA(b, h) + aoff + m * 2048 + k * 1024); } while (0)
; #define PG8_LDB(dst, b, h) do { _Pragma("unroll") for (int n = 0; n < 2; ++n) _Pragma("unroll") for (int k = 0; k < 2; ++k) dst[n][k] = *(const PG8_LAS bf16x8*)(lds + PG8_SB(b, h) + boff + n * 2048 + k * 1024); } while (0)
; #define PG8_MMA(ai, bj, At, Bt) do { __builtin_amdgcn_s_setprio(1); _Pragma("unroll") for (int m = 0; m < 4; ++m) _Pragma("unroll") for (int n = 0; n < 2; ++n) _Pragma("unroll") for (int k = 0; k < 2; ++k) \
;         acc[ai][bj][m][n] = __builtin_amdgcn_mfma_f32_16x16x32_bf16(Bt[n][k], At[m][k], acc[ai][bj][m][n], 0, 0, 0); __builtin_amdgcn_s_setprio(0); } while (0)
; #define PG8_WAIT_V(n) asm volatile("s_waitcnt vmcnt(" #n ")" ::: "memory")
; #define PG8_WAIT_L(n) asm volatile("s_waitcnt lgkmcnt(" #n ")" ::: "memory")
; #define PG8_BAR __builtin_amdgcn_s_barrier()
; #define PG8_SCHED __builtin_amdgcn_sched_barrier(0)
; template <class Epi, class Sched, bool ALIGN_EPI = false, bool SP2 = false>
; __device__ __forceinline__ void gemm_phase(PG8_LAS unsigned char* lds, const Gemm g, const Sched& S, const Epi& E, int wave_s) {
;     ...
;             PG8_WAIT_V(8); PG8_WAIT_L(0); PG8_BAR; PG8_MMA(1, 0, At, B0); PG8_MMA(1, 1, At, B1); PG8_BAR; PG8_SCHED;
;             PG8_LDB(B0, 1, 0); PG8_LDB(B1, 1, 1); PG8_SCHED; PG8_LDA(At, 1, 0); PG8_STAGE(PG8_SA(0, 1), a2 + hstep, voffA);
;             PG8_WAIT_V(8); PG8_WAIT_L(0); PG8_BAR; PG8_MMA(0, 0, At, B0); PG8_MMA(0, 1, At, B1); PG8_BAR; PG8_SCHED;
	s_setprio 1
	s_waitcnt lgkmcnt(0)
	v_mfma_f32_16x16x32_bf16 v[60:63], v[134:137], v[176:179], v[60:63]
	v_mfma_f32_16x16x32_bf16 v[56:59], v[150:153], v[176:179], v[56:59]
	v_mfma_f32_16x16x32_bf16 v[44:47], v[134:137], v[184:187], v[44:47]
	v_mfma_f32_16x16x32_bf16 v[40:43], v[150:153], v[184:187], v[40:43]
	v_mfma_f32_16x16x32_bf16 v[28:31], v[134:137], v[206:209], v[28:31]
	v_mfma_f32_16x16x32_bf16 v[24:27], v[150:153], v[206:209], v[24:27]
	v_mfma_f32_16x16x32_bf16 v[12:15], v[134:137], v[214:217], v[12:15]
	v_mfma_f32_16x16x32_bf16 v[8:11], v[150:153], v[214:217], v[8:11]
	v_mfma_f32_16x16x32_bf16 v[60:63], v[138:141], v[180:183], v[60:63]
	v_mfma_f32_16x16x32_bf16 v[56:59], v[156:159], v[180:183], v[56:59]
	v_mfma_f32_16x16x32_bf16 v[44:47], v[138:141], v[188:191], v[44:47]
	v_mfma_f32_16x16x32_bf16 v[40:43], v[156:159], v[188:191], v[40:43]
	v_mfma_f32_16x16x32_bf16 v[28:31], v[138:141], v[210:213], v[28:31]
	v_mfma_f32_16x16x32_bf16 v[24:27], v[156:159], v[210:213], v[24:27]
	v_mfma_f32_16x16x32_bf16 v[12:15], v[138:141], v[218:221], v[12:15]
	v_mfma_f32_16x16x32_bf16 v[8:11], v[156:159], v[218:221], v[8:11]
	v_mfma_f32_16x16x32_bf16 v[52:55], v[160:163], v[176:179], v[52:55]
	v_mfma_f32_16x16x32_bf16 v[48:51], v[168:171], v[176:179], v[48:51]
	v_mfma_f32_16x16x32_bf16 v[36:39], v[160:163], v[184:187], v[36:39]
	v_mfma_f32_16x16x32_bf16 v[32:35], v[168:171], v[184:187], v[32:35]
	v_mfma_f32_16x16x32_bf16 v[20:23], v[160:163], v[206:209], v[20:23]
	v_mfma_f32_16x16x32_bf16 v[16:19], v[168:171], v[206:209], v[16:19]
	v_mfma_f32_16x16x32_bf16 v[4:7], v[160:163], v[214:217], v[4:7]
	v_mfma_f32_16x16x32_bf16 v[0:3], v[168:171], v[214:217], v[0:3]
	v_mfma_f32_16x16x32_bf16 v[52:55], v[164:167], v[180:183], v[52:55]
	v_mfma_f32_16x16x32_bf16 v[48:51], v[172:175], v[180:183], v[48:51]
	v_mfma_f32_16x16x32_bf16 v[36:39], v[164:167], v[188:191], v[36:39]
	v_mfma_f32_16x16x32_bf16 v[32:35], v[172:175], v[188:191], v[32:35]
	v_mfma_f32_16x16x32_bf16 v[20:23], v[164:167], v[210:213], v[20:23]
	v_mfma_f32_16x16x32_bf16 v[16:19], v[172:175], v[210:213], v[16:19]
	v_mfma_f32_16x16x32_bf16 v[4:7], v[164:167], v[218:221], v[4:7]
	v_mfma_f32_16x16x32_bf16 v[0:3], v[172:175], v[218:221], v[0:3]
	s_setprio 0
	s_barrier
	s_add_i32 s3, 0, 0x18000
	s_add_i32 s26, 0, 0x1c000
	v_add_u32_e32 v156, s3, v143
	v_add_u32_e32 v172, s26, v143
	ds_read_b128 v[134:137], v156
	ds_read_b128 v[138:141], v156 offset:1024
	ds_read_b128 v[150:153], v156 offset:2048
	ds_read_b128 v[156:159], v156 offset:3072
	ds_read_b128 v[160:163], v172
	ds_read_b128 v[164:167], v172 offset:1024
	ds_read_b128 v[168:171], v172 offset:2048
	ds_read_b128 v[172:175], v172 offset:3072
	s_add_u32 s28, s66, 0x160000
	s_addc_u32 s29, s67, 0
	s_mov_b32 m0, s74
	v_lshl_add_u64 v[228:229], s[28:29], 0, v[148:149]
	ds_read_b128 v[176:179], v145 offset:32768
	ds_read_b128 v[180:183], v145 offset:33792
	ds_read_b128 v[184:187], v145 offset:34816
	ds_read_b128 v[188:191], v145 offset:35840
	ds_read_b128 v[206:209], v145 offset:36864
	ds_read_b128 v[210:213], v145 offset:37888
	ds_read_b128 v[214:217], v145 offset:38912
	ds_read_b128 v[218:221], v145 offset:39936
	global_load_lds_dwordx4 v[228:229], off
	v_lshl_add_u64 v[228:229], s[28:29], 0, v[128:129]
	s_mov_b32 m0, s75
	s_nop 0
	global_load_lds_dwordx4 v[228:229], off
	s_waitcnt vmcnt(8)
	s_waitcnt lgkmcnt(0)
	s_barrier
	s_setprio 1
	s_waitcnt lgkmcnt(0)
	v_mfma_f32_16x16x32_bf16 v[124:127], v[134:137], v[176:179], v[124:127]
	v_mfma_f32_16x16x32_bf16 v[120:123], v[150:153], v[176:179], v[120:123]
	v_mfma_f32_16x16x32_bf16 v[108:111], v[134:137], v[184:187], v[108:111]
	v_mfma_f32_16x16x32_bf16 v[104:107], v[150:153], v[184:187], v[104:107]
	v_mfma_f32_16x16x32_bf16 v[92:95], v[134:137], v[206:209], v[92:95]
	v_mfma_f32_16x16x32_bf16 v[88:91], v[150:153], v[206:209], v[88:91]
	v_mfma_f32_16x16x32_bf16 v[76:79], v[134:137], v[214:217], v[76:79]
	v_mfma_f32_16x16x32_bf16 v[72:75], v[150:153], v[214:217], v[72:75]
	v_mfma_f32_16x16x32_bf16 v[124:127], v[138:141], v[180:183], v[124:127]
	v_mfma_f32_16x16x32_bf16 v[120:123], v[156:159], v[180:183], v[120:123]
	v_mfma_f32_16x16x32_bf16 v[108:111], v[138:141], v[188:191], v[108:111]
	v_mfma_f32_16x16x32_bf16 v[104:107], v[156:159], v[188:191], v[104:107]
	v_mfma_f32_16x16x32_bf16 v[92:95], v[138:141], v[210:213], v[92:95]
	v_mfma_f32_16x16x32_bf16 v[88:91], v[156:159], v[210:213], v[88:91]
	v_mfma_f32_16x16x32_bf16 v[76:79], v[138:141], v[218:221], v[76:79]
	v_mfma_f32_16x16x32_bf16 v[72:75], v[156:159], v[218:221], v[72:75]
	v_mfma_f32_16x16x32_bf16 v[116:119], v[160:163], v[176:179], v[116:119]
	v_mfma_f32_16x16x32_bf16 v[112:115], v[168:171], v[176:179], v[112:115]
	v_mfma_f32_16x16x32_bf16 v[100:103], v[160:163], v[184:187], v[100:103]
	v_mfma_f32_16x16x32_bf16 v[96:99], v[168:171], v[184:187], v[96:99]
	v_mfma_f32_16x16x32_bf16 v[84:87], v[160:163], v[206:209], v[84:87]
	v_mfma_f32_16x16x32_bf16 v[80:83], v[168:171], v[206:209], v[80:83]
	v_mfma_f32_16x16x32_bf16 v[68:71], v[160:163], v[214:217], v[68:71]
	v_mfma_f32_16x16x32_bf16 v[64:67], v[168:171], v[214:217], v[64:67]
	v_mfma_f32_16x16x32_bf16 v[116:119], v[164:167], v[180:183], v[116:119]
	v_mfma_f32_16x16x32_bf16 v[112:115], v[172:175], v[180:183], v[112:115]
	v_mfma_f32_16x16x32_bf16 v[100:103], v[164:167], v[188:191], v[100:103]
	v_mfma_f32_16x16x32_bf16 v[96:99], v[172:175], v[188:191], v[96:99]
	v_mfma_f32_16x16x32_bf16 v[84:87], v[164:167], v[210:213], v[84:87]
	v_mfma_f32_16x16x32_bf16 v[80:83], v[172:175], v[210:213], v[80:83]
	v_mfma_f32_16x16x32_bf16 v[68:71], v[164:167], v[218:221], v[68:71]
	v_mfma_f32_16x16x32_bf16 v[64:67], v[172:175], v[218:221], v[64:67]
	s_setprio 0
	s_barrier
; #define PG8_STAGE(bufoff, gbase, voff) do { _Pragma("unroll") for (int _i = 0; _i < 2; ++_i) \
;         __builtin_amdgcn_global_load_lds((const unsigned*)((const char*)(gbase) + (voff)[_i]), (PG8_LAS unsigned*)(lds + (bufoff) + ldsw + _i * 8192), 16, 0, 0); } while (0)
; #define PG8_LDA(dst, b, h) do { _Pragma("unroll") for (int m = 0; m < 4; ++m) _Pragma("unroll") for (int k = 0; k < 2; ++k) dst[m][k] = *(const PG8_LAS bf16x8*)(lds + PG8_SA(b, h) + aoff + m * 2048 + k * 1024); } while (0)
; #define PG8_MMA(ai, bj, At, Bt) do { __builtin_amdgcn_s_setprio(1); _Pragma("unroll") for (int m = 0; m < 4; ++m) _Pragma("unroll") for (int n = 0; n < 2; ++n) _Pragma("unroll") for (int k = 0; k < 2; ++k) \
;         acc[ai][bj][m][n] = __builtin_amdgcn_mfma_f32_16x16x32_bf16(Bt[n][k], At[m][k], acc[ai][bj][m][n], 0, 0, 0); __builtin_amdgcn_s_setprio(0); } while (0)
; #define PG8_WAIT_V(n) asm volatile("s_waitcnt vmcnt(" #n ")" ::: "memory")
; #define PG8_WAIT_L(n) asm volatile("s_waitcnt lgkmcnt(" #n ")" ::: "memory")
; #define PG8_BAR __builtin_amdgcn_s_barrier()
; #define PG8_SCHED __builtin_amdgcn_sched_barrier(0)
; template <class Epi, class Sched, bool ALIGN_EPI = false, bool SP2 = false>
; __device__ __forceinline__ void gemm_phase(PG8_LAS unsigned char* lds, const Gemm g, const Sched& S, const Epi& E, int wave_s) {
;     ...
;         for (int t = 0; t < nt; t += 2) {
;             const bool last = (t == nt - 2);
;             const char* a1 = cA + (size_t)(t + 1) * kstep;
;             const char* a2 = last ? nA : cA + (size_t)(t + 2) * kstep; const char* b2 = last ? nB : cB + (size_t)(t + 2) * kstep;
;             const char* a3 = a2 + kstep; const char* b3 = b2 + kstep;
;             if (last && has_next) S.a_ready(nxt);
;     ...
;             PG8_LDA(At, 1, 1); PG8_STAGE(PG8_SB(1, 0), b3, voffB); PG8_STAGE(PG8_SB(1, 1), b3 + hstep, voffB); PG8_STAGE(PG8_SA(1, 0), a3, voffA);
;             PG8_WAIT_V(8); PG8_WAIT_L(0); PG8_BAR; PG8_MMA(1, 0, At, B0); PG8_MMA(1, 1, At, B1); PG8_BAR; PG8_SCHED;
	s_add_i32 s3, s3, s9
	v_lshl_add_u64 v[146:147], v[146:147], 0, s[34:35]
	s_mov_b32 m0, s3
	ds_read_b128 v[176:179], v145 offset:49152
	ds_read_b128 v[180:183], v145 offset:50176
	ds_read_b128 v[184:187], v145 offset:51200
	ds_read_b128 v[188:191], v145 offset:52224
	ds_read_b128 v[206:209], v145 offset:53248
	ds_read_b128 v[210:213], v145 offset:54272
	ds_read_b128 v[214:217], v145 offset:55296
	ds_read_b128 v[218:221], v145 offset:56320
	global_load_lds_dwordx4 v[146:147], off
	s_add_i32 m0, s3, 0x2000
	s_add_u32 s28, s64, 0x160080
	v_lshl_add_u64 v[146:147], v[222:223], 0, s[34:35]
	s_addc_u32 s29, s65, 0
	s_add_i32 s3, s26, s9
	global_load_lds_dwordx4 v[146:147], off
	v_lshl_add_u64 v[146:147], s[28:29], 0, v[148:149]
	s_mov_b32 m0, s3
	s_nop 0
	global_load_lds_dwordx4 v[146:147], off
	v_lshl_add_u64 v[146:147], s[28:29], 0, v[128:129]
	s_add_i32 m0, s3, 0x2000
	s_nop 0
	global_load_lds_dwordx4 v[146:147], off
	v_lshl_add_u64 v[146:147], v[224:225], 0, s[34:35]
	s_mov_b32 m0, s79
	s_nop 0
	global_load_lds_dwordx4 v[146:147], off
	v_lshl_add_u64 v[146:147], v[226:227], 0, s[34:35]
	s_mov_b32 m0, s20
	s_nop 0
	global_load_lds_dwordx4 v[146:147], off
	s_waitcnt vmcnt(8)
	s_waitcnt lgkmcnt(0)
	s_barrier
	s_setprio 1
	s_waitcnt lgkmcnt(0)
	v_mfma_f32_16x16x32_bf16 v[60:63], v[134:137], v[176:179], v[60:63]
	v_mfma_f32_16x16x32_bf16 v[56:59], v[150:153], v[176:179], v[56:59]
	v_mfma_f32_16x16x32_bf16 v[44:47], v[134:137], v[184:187], v[44:47]
	v_mfma_f32_16x16x32_bf16 v[40:43], v[150:153], v[184:187], v[40:43]
	v_mfma_f32_16x16x32_bf16 v[28:31], v[134:137], v[206:209], v[28:31]
	v_mfma_f32_16x16x32_bf16 v[24:27], v[150:153], v[206:209], v[24:27]
	v_mfma_f32_16x16x32_bf16 v[12:15], v[134:137], v[214:217], v[12:15]
	v_mfma_f32_16x16x32_bf16 v[8:11], v[150:153], v[214:217], v[8:11]
	v_mfma_f32_16x16x32_bf16 v[60:63], v[138:141], v[180:183], v[60:63]
	v_mfma_f32_16x16x32_bf16 v[56:59], v[156:159], v[180:183], v[56:59]
	v_mfma_f32_16x16x32_bf16 v[44:47], v[138:141], v[188:191], v[44:47]
	v_mfma_f32_16x16x32_bf16 v[40:43], v[156:159], v[188:191], v[40:43]
	v_mfma_f32_16x16x32_bf16 v[28:31], v[138:141], v[210:213], v[28:31]
	v_mfma_f32_16x16x32_bf16 v[24:27], v[156:159], v[210:213], v[24:27]
	v_mfma_f32_16x16x32_bf16 v[12:15], v[138:141], v[218:221], v[12:15]
	v_mfma_f32_16x16x32_bf16 v[8:11], v[156:159], v[218:221], v[8:11]
	v_mfma_f32_16x16x32_bf16 v[52:55], v[160:163], v[176:179], v[52:55]
	v_mfma_f32_16x16x32_bf16 v[48:51], v[168:171], v[176:179], v[48:51]
	v_mfma_f32_16x16x32_bf16 v[36:39], v[160:163], v[184:187], v[36:39]
	v_mfma_f32_16x16x32_bf16 v[32:35], v[168:171], v[184:187], v[32:35]
	v_mfma_f32_16x16x32_bf16 v[20:23], v[160:163], v[206:209], v[20:23]
	v_mfma_f32_16x16x32_bf16 v[16:19], v[168:171], v[206:209], v[16:19]
	v_mfma_f32_16x16x32_bf16 v[4:7], v[160:163], v[214:217], v[4:7]
	v_mfma_f32_16x16x32_bf16 v[0:3], v[168:171], v[214:217], v[0:3]
	v_mfma_f32_16x16x32_bf16 v[52:55], v[164:167], v[180:183], v[52:55]
	v_mfma_f32_16x16x32_bf16 v[48:51], v[172:175], v[180:183], v[48:51]
	v_mfma_f32_16x16x32_bf16 v[36:39], v[164:167], v[188:191], v[36:39]
	v_mfma_f32_16x16x32_bf16 v[32:35], v[172:175], v[188:191], v[32:35]
	v_mfma_f32_16x16x32_bf16 v[20:23], v[164:167], v[210:213], v[20:23]
	v_mfma_f32_16x16x32_bf16 v[16:19], v[172:175], v[210:213], v[16:19]
	v_mfma_f32_16x16x32_bf16 v[4:7], v[164:167], v[218:221], v[4:7]
	v_mfma_f32_16x16x32_bf16 v[0:3], v[172:175], v[218:221], v[0:3]
	s_setprio 0
	s_barrier
	s_add_i32 s23, s23, 2
	s_add_u32 s5, s5, 0x100
	s_addc_u32 s22, s22, 0
	s_cmpk_gt_u32 s23, 0x55
	s_mov_b64 s[60:61], s[62:63]
	s_cbranch_scc0 .LBB0_53
	s_and_b64 vcc, exec, s[56:57]
	s_cbranch_vccz .LBB0_56
	s_barrier

; #define PG8_STAGE(bufoff, gbase, voff) do { _Pragma("unroll") for (int _i = 0; _i < 2; ++_i) \
;         __builtin_amdgcn_global_load_lds((const unsigned*)((const char*)(gbase) + (voff)[_i]), (PG8_LAS unsigned*)(lds + (bufoff) + ldsw + _i * 8192), 16, 0, 0); } while (0)
; #define PG8_LDA(dst, b, h) do { _Pragma("unroll") for (int m = 0; m < 4; ++m) _Pragma("unroll") for (int k = 0; k < 2; ++k) dst[m][k] = *(const PG8_LAS bf16x8*)(lds + PG8_SA(b, h) + aoff + m * 2048 + k * 1024); } while (0)
; #define PG8_LDB(dst, b, h) do { _Pragma("unroll") for (int n = 0; n < 2; ++n) _Pragma("unroll") for (int k = 0; k < 2; ++k) dst[n][k] = *(const PG8_LAS bf16x8*)(lds + PG8_SB(b, h) + boff + n * 2048 + k * 1024); } while (0)
; #define PG8_MMA(ai, bj, At, Bt) do { __builtin_amdgcn_s_setprio(1); _Pragma("unroll") for (int m = 0; m < 4; ++m) _Pragma("unroll") for (int n = 0; n < 2; ++n) _Pragma("unroll") for (int k = 0; k < 2; ++k) \
;         acc[ai][bj][m][n] = __builtin_amdgcn_mfma_f32_16x16x32_bf16(Bt[n][k], At[m][k], acc[ai][bj][m][n], 0, 0, 0); __builtin_amdgcn_s_setprio(0); } while (0)
; #define PG8_WAIT_V(n) asm volatile("s_waitcnt vmcnt(" #n ")" ::: "memory")
; #define PG8_BAR __builtin_amdgcn_s_barrier()
; template <class Epi, class Sched, bool ALIGN_EPI = false, bool SP2 = false>
; __device__ __forceinline__ void gemm_phase(PG8_LAS unsigned char* lds, const Gemm g, const Sched& S, const Epi& E, int wave_s) {
;     ...
;         for (int t = 0; t < nt; t += 2) {
;             const bool last = (t == nt - 2);
;             const char* a1 = cA + (size_t)(t + 1) * kstep;
;             const char* a2 = last ? nA : cA + (size_t)(t + 2) * kstep; const char* b2 = last ? nB : cB + (size_t)(t + 2) * kstep;
;             const char* a3 = a2 + kstep; const char* b3 = b2 + kstep;
;             if (last && has_next) S.a_ready(nxt);
;             if constexpr (SP2) {
;             PG8_LDB(B0, 0, 0); PG8_LDB(B1, 0, 1); PG8_SCHED; PG8_LDA(At, 0, 0); PG8_STAGE(PG8_SA(1, 1), a1 + hstep, voffA);
;             PG8_WAIT_V(8); PG8_WAIT_L(0); PG8_BAR; PG8_MMA(0, 0, At, B0); PG8_MMA(0, 1, At, B1); PG8_BAR; PG8_SCHED;
;             PG8_LDA(At, 0, 1); PG8_STAGE(PG8_SB(0, 0), b2, voffB); PG8_STAGE(PG8_SB(0, 1), b2 + hstep, voffB); PG8_STAGE(PG8_SA(0, 0), a2, voffA);
;             PG8_WAIT_V(8); PG8_WAIT_L(0); PG8_BAR; PG8_MMA(1, 0, At, B0); PG8_MMA(1, 1, At, B1); PG8_BAR; PG8_SCHED;
.LBB0_82:
	s_add_u32 s3, s62, 0xfff80080
	s_addc_u32 s26, s63, -1
	s_add_i32 s36, 0, 0x10000
	s_cmp_eq_u32 s38, 28
	s_cselect_b32 s67, s19, s26
	s_cselect_b32 s66, s22, s3
	v_add_u32_e32 v146, s36, v139
	s_cselect_b32 s65, s5, s29
	s_cselect_b32 s64, s23, s28
	s_add_i32 s3, 0, 0x14000
	ds_read_b128 v[142:145], v146
	ds_read_b128 v[150:153], v146 offset:1024
	ds_read_b128 v[156:159], v146 offset:2048
	ds_read_b128 v[160:163], v146 offset:3072
	v_add_u32_e32 v146, s3, v139
	ds_read_b128 v[164:167], v146
	ds_read_b128 v[168:171], v146 offset:1024
	ds_read_b128 v[172:175], v146 offset:2048
	ds_read_b128 v[176:179], v146 offset:3072
	v_lshl_add_u64 v[146:147], s[62:63], 0, v[134:135]
	s_add_i32 m0, s61, 0xc000
	ds_read_b128 v[180:183], v141
	ds_read_b128 v[184:187], v141 offset:1024
	ds_read_b128 v[188:191], v141 offset:2048
	ds_read_b128 v[206:209], v141 offset:3072
	ds_read_b128 v[210:213], v141 offset:4096
	ds_read_b128 v[214:217], v141 offset:5120
	ds_read_b128 v[218:221], v141 offset:6144
	ds_read_b128 v[222:225], v141 offset:7168
	global_load_lds_dwordx4 v[146:147], off
	v_lshl_add_u64 v[146:147], s[62:63], 0, v[136:137]
	s_add_i32 m0, s61, 0xe000
	s_nop 0
	global_load_lds_dwordx4 v[146:147], off
	s_waitcnt vmcnt(8)
	s_waitcnt lgkmcnt(0)
	s_barrier
	s_setprio 1
	s_waitcnt lgkmcnt(0)
	v_mfma_f32_16x16x32_bf16 v[124:127], v[142:145], v[180:183], v[124:127]
	v_mfma_f32_16x16x32_bf16 v[116:119], v[156:159], v[180:183], v[116:119]
	v_mfma_f32_16x16x32_bf16 v[108:111], v[142:145], v[188:191], v[108:111]
	v_mfma_f32_16x16x32_bf16 v[100:103], v[156:159], v[188:191], v[100:103]
	v_mfma_f32_16x16x32_bf16 v[92:95], v[142:145], v[210:213], v[92:95]
	v_mfma_f32_16x16x32_bf16 v[84:87], v[156:159], v[210:213], v[84:87]
	v_mfma_f32_16x16x32_bf16 v[76:79], v[142:145], v[218:221], v[76:79]
	v_mfma_f32_16x16x32_bf16 v[68:71], v[156:159], v[218:221], v[68:71]
	v_mfma_f32_16x16x32_bf16 v[124:127], v[150:153], v[184:187], v[124:127]
	v_mfma_f32_16x16x32_bf16 v[116:119], v[160:163], v[184:187], v[116:119]
	v_mfma_f32_16x16x32_bf16 v[108:111], v[150:153], v[206:209], v[108:111]
	v_mfma_f32_16x16x32_bf16 v[100:103], v[160:163], v[206:209], v[100:103]
	v_mfma_f32_16x16x32_bf16 v[92:95], v[150:153], v[214:217], v[92:95]
	v_mfma_f32_16x16x32_bf16 v[84:87], v[160:163], v[214:217], v[84:87]
	v_mfma_f32_16x16x32_bf16 v[76:79], v[150:153], v[222:225], v[76:79]
	v_mfma_f32_16x16x32_bf16 v[68:71], v[160:163], v[222:225], v[68:71]
	v_mfma_f32_16x16x32_bf16 v[120:123], v[164:167], v[180:183], v[120:123]
	v_mfma_f32_16x16x32_bf16 v[112:115], v[172:175], v[180:183], v[112:115]
	v_mfma_f32_16x16x32_bf16 v[104:107], v[164:167], v[188:191], v[104:107]
	v_mfma_f32_16x16x32_bf16 v[96:99], v[172:175], v[188:191], v[96:99]
	v_mfma_f32_16x16x32_bf16 v[88:91], v[164:167], v[210:213], v[88:91]
	v_mfma_f32_16x16x32_bf16 v[80:83], v[172:175], v[210:213], v[80:83]
	v_mfma_f32_16x16x32_bf16 v[72:75], v[164:167], v[218:221], v[72:75]
	v_mfma_f32_16x16x32_bf16 v[64:67], v[172:175], v[218:221], v[64:67]
	v_mfma_f32_16x16x32_bf16 v[120:123], v[168:171], v[184:187], v[120:123]
	v_mfma_f32_16x16x32_bf16 v[112:115], v[176:179], v[184:187], v[112:115]
	v_mfma_f32_16x16x32_bf16 v[104:107], v[168:171], v[206:209], v[104:107]
	v_mfma_f32_16x16x32_bf16 v[96:99], v[176:179], v[206:209], v[96:99]
	v_mfma_f32_16x16x32_bf16 v[88:91], v[168:171], v[214:217], v[88:91]
	v_mfma_f32_16x16x32_bf16 v[80:83], v[176:179], v[214:217], v[80:83]
	v_mfma_f32_16x16x32_bf16 v[72:75], v[168:171], v[222:225], v[72:75]
	v_mfma_f32_16x16x32_bf16 v[64:67], v[176:179], v[222:225], v[64:67]
	s_setprio 0
	s_barrier
	s_add_i32 s26, s36, s25
	v_lshl_add_u64 v[146:147], s[64:65], 0, v[148:149]
	s_mov_b32 m0, s26
	ds_read_b128 v[180:183], v141 offset:16384
	ds_read_b128 v[184:187], v141 offset:17408
	ds_read_b128 v[188:191], v141 offset:18432
	ds_read_b128 v[206:209], v141 offset:19456
	ds_read_b128 v[210:213], v141 offset:20480
	ds_read_b128 v[214:217], v141 offset:21504
	ds_read_b128 v[218:221], v141 offset:22528
	ds_read_b128 v[222:225], v141 offset:23552
	global_load_lds_dwordx4 v[146:147], off
	s_add_i32 m0, s26, 0x2000
	s_add_u32 s36, s64, 0x80000
	v_lshl_add_u64 v[226:227], s[64:65], 0, v[128:129]
	s_addc_u32 s37, s65, 0
	s_add_i32 s3, s3, s25
	global_load_lds_dwordx4 v[226:227], off
	v_lshl_add_u64 v[228:229], s[36:37], 0, v[148:149]
	s_mov_b32 m0, s3
	v_lshl_add_u64 v[230:231], s[66:67], 0, v[130:131]
	global_load_lds_dwordx4 v[228:229], off
	v_lshl_add_u64 v[228:229], s[36:37], 0, v[128:129]
	s_add_i32 m0, s3, 0x2000
	s_nop 0
	global_load_lds_dwordx4 v[228:229], off
	v_lshl_add_u64 v[228:229], s[66:67], 0, v[132:133]
	s_mov_b32 m0, s61
	s_nop 0
	global_load_lds_dwordx4 v[228:229], off
	s_mov_b32 m0, s73
	s_nop 0
	global_load_lds_dwordx4 v[230:231], off
	s_waitcnt vmcnt(8)
	s_waitcnt lgkmcnt(0)
	s_barrier
; #define PG8_STAGE(bufoff, gbase, voff) do { _Pragma("unroll") for (int _i = 0; _i < 2; ++_i) \
;         __builtin_amdgcn_global_load_lds((const unsigned*)((const char*)(gbase) + (voff)[_i]), (PG8_LAS unsigned*)(lds + (bufoff) + ldsw + _i * 8192), 16, 0, 0); } while (0)
; #define PG8_LDA(dst, b, h) do { _Pragma("unroll") for (int m = 0; m < 4; ++m) _Pragma("unroll") for (int k = 0; k < 2; ++k) dst[m][k] = *(const PG8_LAS bf16x8*)(lds + PG8_SA(b, h) + aoff + m * 2048 + k * 1024); } while (0)
; #define PG8_LDB(dst, b, h) do { _Pragma("unroll") for (int n = 0; n < 2; ++n) _Pragma("unroll") for (int k = 0; k < 2; ++k) dst[n][k] = *(const PG8_LAS bf16x8*)(lds + PG8_SB(b, h) + boff + n * 2048 + k * 1024); } while (0)
; #define PG8_MMA(ai, bj, At, Bt) do { __builtin_amdgcn_s_setprio(1); _Pragma("unroll") for (int m = 0; m < 4; ++m) _Pragma("unroll") for (int n = 0; n < 2; ++n) _Pragma("unroll") for (int k = 0; k < 2; ++k) \
;         acc[ai][bj][m][n] = __builtin_amdgcn_mfma_f32_16x16x32_bf16(Bt[n][k], At[m][k], acc[ai][bj][m][n], 0, 0, 0); __builtin_amdgcn_s_setprio(0); } while (0)
; #define PG8_WAIT_V(n) asm volatile("s_waitcnt vmcnt(" #n ")" ::: "memory")
; #define PG8_WAIT_L(n) asm volatile("s_waitcnt lgkmcnt(" #n ")" ::: "memory")
; #define PG8_BAR __builtin_amdgcn_s_barrier()
; #define PG8_SCHED __builtin_amdgcn_sched_barrier(0)
; template <class Epi, class Sched, bool ALIGN_EPI = false, bool SP2 = false>
; __device__ __forceinline__ void gemm_phase(PG8_LAS unsigned char* lds, const Gemm g, const Sched& S, const Epi& E, int wave_s) {
;     ...
;             PG8_WAIT_V(8); PG8_WAIT_L(0); PG8_BAR; PG8_MMA(1, 0, At, B0); PG8_MMA(1, 1, At, B1); PG8_BAR; PG8_SCHED;
;             PG8_LDB(B0, 1, 0); PG8_LDB(B1, 1, 1); PG8_SCHED; PG8_LDA(At, 1, 0); PG8_STAGE(PG8_SA(0, 1), a2 + hstep, voffA);
;             PG8_WAIT_V(8); PG8_WAIT_L(0); PG8_BAR; PG8_MMA(0, 0, At, B0); PG8_MMA(0, 1, At, B1); PG8_BAR; PG8_SCHED;
	s_setprio 1
	s_waitcnt lgkmcnt(0)
	v_mfma_f32_16x16x32_bf16 v[60:63], v[142:145], v[180:183], v[60:63]
	v_mfma_f32_16x16x32_bf16 v[52:55], v[156:159], v[180:183], v[52:55]
	v_mfma_f32_16x16x32_bf16 v[44:47], v[142:145], v[188:191], v[44:47]
	v_mfma_f32_16x16x32_bf16 v[36:39], v[156:159], v[188:191], v[36:39]
	v_mfma_f32_16x16x32_bf16 v[28:31], v[142:145], v[210:213], v[28:31]
	v_mfma_f32_16x16x32_bf16 v[20:23], v[156:159], v[210:213], v[20:23]
	v_mfma_f32_16x16x32_bf16 v[12:15], v[142:145], v[218:221], v[12:15]
	v_mfma_f32_16x16x32_bf16 v[4:7], v[156:159], v[218:221], v[4:7]
	v_mfma_f32_16x16x32_bf16 v[60:63], v[150:153], v[184:187], v[60:63]
	v_mfma_f32_16x16x32_bf16 v[52:55], v[160:163], v[184:187], v[52:55]
	v_mfma_f32_16x16x32_bf16 v[44:47], v[150:153], v[206:209], v[44:47]
	v_mfma_f32_16x16x32_bf16 v[36:39], v[160:163], v[206:209], v[36:39]
	v_mfma_f32_16x16x32_bf16 v[28:31], v[150:153], v[214:217], v[28:31]
	v_mfma_f32_16x16x32_bf16 v[20:23], v[160:163], v[214:217], v[20:23]
	v_mfma_f32_16x16x32_bf16 v[12:15], v[150:153], v[222:225], v[12:15]
	v_mfma_f32_16x16x32_bf16 v[4:7], v[160:163], v[222:225], v[4:7]
	v_mfma_f32_16x16x32_bf16 v[56:59], v[164:167], v[180:183], v[56:59]
	v_mfma_f32_16x16x32_bf16 v[48:51], v[172:175], v[180:183], v[48:51]
	v_mfma_f32_16x16x32_bf16 v[40:43], v[164:167], v[188:191], v[40:43]
	v_mfma_f32_16x16x32_bf16 v[32:35], v[172:175], v[188:191], v[32:35]
	v_mfma_f32_16x16x32_bf16 v[24:27], v[164:167], v[210:213], v[24:27]
	v_mfma_f32_16x16x32_bf16 v[16:19], v[172:175], v[210:213], v[16:19]
	v_mfma_f32_16x16x32_bf16 v[8:11], v[164:167], v[218:221], v[8:11]
	v_mfma_f32_16x16x32_bf16 v[0:3], v[172:175], v[218:221], v[0:3]
	v_mfma_f32_16x16x32_bf16 v[56:59], v[168:171], v[184:187], v[56:59]
	v_mfma_f32_16x16x32_bf16 v[48:51], v[176:179], v[184:187], v[48:51]
	v_mfma_f32_16x16x32_bf16 v[40:43], v[168:171], v[206:209], v[40:43]
	v_mfma_f32_16x16x32_bf16 v[32:35], v[176:179], v[206:209], v[32:35]
	v_mfma_f32_16x16x32_bf16 v[24:27], v[168:171], v[214:217], v[24:27]
	v_mfma_f32_16x16x32_bf16 v[16:19], v[176:179], v[214:217], v[16:19]
	v_mfma_f32_16x16x32_bf16 v[8:11], v[168:171], v[222:225], v[8:11]
	v_mfma_f32_16x16x32_bf16 v[0:3], v[176:179], v[222:225], v[0:3]
	s_setprio 0
	s_barrier
	s_add_i32 s3, 0, 0x18000
	s_add_i32 s26, 0, 0x1c000
	v_add_u32_e32 v160, s3, v139
	v_add_u32_e32 v176, s26, v139
	ds_read_b128 v[142:145], v160
	ds_read_b128 v[150:153], v160 offset:1024
	ds_read_b128 v[156:159], v160 offset:2048
	ds_read_b128 v[160:163], v160 offset:3072
	ds_read_b128 v[164:167], v176
	ds_read_b128 v[168:171], v176 offset:1024
	ds_read_b128 v[172:175], v176 offset:2048
	ds_read_b128 v[176:179], v176 offset:3072
	s_add_u32 s36, s66, 0x80000
	s_addc_u32 s37, s67, 0
	s_mov_b32 m0, s74
	v_lshl_add_u64 v[232:233], s[36:37], 0, v[132:133]
	ds_read_b128 v[180:183], v141 offset:32768
	ds_read_b128 v[184:187], v141 offset:33792
	ds_read_b128 v[188:191], v141 offset:34816
	ds_read_b128 v[206:209], v141 offset:35840
	ds_read_b128 v[210:213], v141 offset:36864
	ds_read_b128 v[214:217], v141 offset:37888
	ds_read_b128 v[218:221], v141 offset:38912
	ds_read_b128 v[222:225], v141 offset:39936
	global_load_lds_dwordx4 v[232:233], off
	v_lshl_add_u64 v[232:233], s[36:37], 0, v[130:131]
	s_mov_b32 m0, s75
	s_nop 0
	global_load_lds_dwordx4 v[232:233], off
	s_waitcnt vmcnt(8)
	s_waitcnt lgkmcnt(0)
	s_barrier
	s_setprio 1
	s_waitcnt lgkmcnt(0)
	v_mfma_f32_16x16x32_bf16 v[124:127], v[142:145], v[180:183], v[124:127]
	v_mfma_f32_16x16x32_bf16 v[116:119], v[156:159], v[180:183], v[116:119]
	v_mfma_f32_16x16x32_bf16 v[108:111], v[142:145], v[188:191], v[108:111]
	v_mfma_f32_16x16x32_bf16 v[100:103], v[156:159], v[188:191], v[100:103]
	v_mfma_f32_16x16x32_bf16 v[92:95], v[142:145], v[210:213], v[92:95]
	v_mfma_f32_16x16x32_bf16 v[84:87], v[156:159], v[210:213], v[84:87]
	v_mfma_f32_16x16x32_bf16 v[76:79], v[142:145], v[218:221], v[76:79]
	v_mfma_f32_16x16x32_bf16 v[68:71], v[156:159], v[218:221], v[68:71]
	v_mfma_f32_16x16x32_bf16 v[124:127], v[150:153], v[184:187], v[124:127]
	v_mfma_f32_16x16x32_bf16 v[116:119], v[160:163], v[184:187], v[116:119]
	v_mfma_f32_16x16x32_bf16 v[108:111], v[150:153], v[206:209], v[108:111]
	v_mfma_f32_16x16x32_bf16 v[100:103], v[160:163], v[206:209], v[100:103]
	v_mfma_f32_16x16x32_bf16 v[92:95], v[150:153], v[214:217], v[92:95]
	v_mfma_f32_16x16x32_bf16 v[84:87], v[160:163], v[214:217], v[84:87]
	v_mfma_f32_16x16x32_bf16 v[76:79], v[150:153], v[222:225], v[76:79]
	v_mfma_f32_16x16x32_bf16 v[68:71], v[160:163], v[222:225], v[68:71]
	v_mfma_f32_16x16x32_bf16 v[120:123], v[164:167], v[180:183], v[120:123]
	v_mfma_f32_16x16x32_bf16 v[112:115], v[172:175], v[180:183], v[112:115]
	v_mfma_f32_16x16x32_bf16 v[104:107], v[164:167], v[188:191], v[104:107]
	v_mfma_f32_16x16x32_bf16 v[96:99], v[172:175], v[188:191], v[96:99]
	v_mfma_f32_16x16x32_bf16 v[88:91], v[164:167], v[210:213], v[88:91]
	v_mfma_f32_16x16x32_bf16 v[80:83], v[172:175], v[210:213], v[80:83]
	v_mfma_f32_16x16x32_bf16 v[72:75], v[164:167], v[218:221], v[72:75]
	v_mfma_f32_16x16x32_bf16 v[64:67], v[172:175], v[218:221], v[64:67]
	v_mfma_f32_16x16x32_bf16 v[120:123], v[168:171], v[184:187], v[120:123]
	v_mfma_f32_16x16x32_bf16 v[112:115], v[176:179], v[184:187], v[112:115]
	v_mfma_f32_16x16x32_bf16 v[104:107], v[168:171], v[206:209], v[104:107]
	v_mfma_f32_16x16x32_bf16 v[96:99], v[176:179], v[206:209], v[96:99]
	v_mfma_f32_16x16x32_bf16 v[88:91], v[168:171], v[214:217], v[88:91]
	v_mfma_f32_16x16x32_bf16 v[80:83], v[176:179], v[214:217], v[80:83]
	v_mfma_f32_16x16x32_bf16 v[72:75], v[168:171], v[222:225], v[72:75]
	v_mfma_f32_16x16x32_bf16 v[64:67], v[176:179], v[222:225], v[64:67]
	s_setprio 0
	s_barrier
; #define PG8_STAGE(bufoff, gbase, voff) do { _Pragma("unroll") for (int _i = 0; _i < 2; ++_i) \
;         __builtin_amdgcn_global_load_lds((const unsigned*)((const char*)(gbase) + (voff)[_i]), (PG8_LAS unsigned*)(lds + (bufoff) + ldsw + _i * 8192), 16, 0, 0); } while (0)
; #define PG8_LDA(dst, b, h) do { _Pragma("unroll") for (int m = 0; m < 4; ++m) _Pragma("unroll") for (int k = 0; k < 2; ++k) dst[m][k] = *(const PG8_LAS bf16x8*)(lds + PG8_SA(b, h) + aoff + m * 2048 + k * 1024); } while (0)
; #define PG8_MMA(ai, bj, At, Bt) do { __builtin_amdgcn_s_setprio(1); _Pragma("unroll") for (int m = 0; m < 4; ++m) _Pragma("unroll") for (int n = 0; n < 2; ++n) _Pragma("unroll") for (int k = 0; k < 2; ++k) \
;         acc[ai][bj][m][n] = __builtin_amdgcn_mfma_f32_16x16x32_bf16(Bt[n][k], At[m][k], acc[ai][bj][m][n], 0, 0, 0); __builtin_amdgcn_s_setprio(0); } while (0)
; #define PG8_WAIT_V(n) asm volatile("s_waitcnt vmcnt(" #n ")" ::: "memory")
; #define PG8_WAIT_L(n) asm volatile("s_waitcnt lgkmcnt(" #n ")" ::: "memory")
; #define PG8_BAR __builtin_amdgcn_s_barrier()
; #define PG8_SCHED __builtin_amdgcn_sched_barrier(0)
; template <class Epi, class Sched, bool ALIGN_EPI = false, bool SP2 = false>
; __device__ __forceinline__ void gemm_phase(PG8_LAS unsigned char* lds, const Gemm g, const Sched& S, const Epi& E, int wave_s) {
;     ...
;         for (int t = 0; t < nt; t += 2) {
;             const bool last = (t == nt - 2);
;             const char* a1 = cA + (size_t)(t + 1) * kstep;
;             const char* a2 = last ? nA : cA + (size_t)(t + 2) * kstep; const char* b2 = last ? nB : cB + (size_t)(t + 2) * kstep;
;             const char* a3 = a2 + kstep; const char* b3 = b2 + kstep;
;             if (last && has_next) S.a_ready(nxt);
;     ...
;             PG8_LDA(At, 1, 1); PG8_STAGE(PG8_SB(1, 0), b3, voffB); PG8_STAGE(PG8_SB(1, 1), b3 + hstep, voffB); PG8_STAGE(PG8_SA(1, 0), a3, voffA);
;             PG8_WAIT_V(8); PG8_WAIT_L(0); PG8_BAR; PG8_MMA(1, 0, At, B0); PG8_MMA(1, 1, At, B1); PG8_BAR; PG8_SCHED;
	s_add_i32 s3, s3, s25
	v_lshl_add_u64 v[146:147], v[146:147], 0, s[34:35]
	s_mov_b32 m0, s3
	ds_read_b128 v[180:183], v141 offset:49152
	ds_read_b128 v[184:187], v141 offset:50176
	ds_read_b128 v[188:191], v141 offset:51200
	ds_read_b128 v[206:209], v141 offset:52224
	ds_read_b128 v[210:213], v141 offset:53248
	ds_read_b128 v[214:217], v141 offset:54272
	ds_read_b128 v[218:221], v141 offset:55296
	ds_read_b128 v[222:225], v141 offset:56320
	global_load_lds_dwordx4 v[146:147], off
	s_add_i32 m0, s3, 0x2000
	s_add_u32 s36, s64, 0x80080
	v_lshl_add_u64 v[146:147], v[226:227], 0, s[34:35]
	s_addc_u32 s37, s65, 0
	s_add_i32 s3, s26, s25
	global_load_lds_dwordx4 v[146:147], off
	v_lshl_add_u64 v[146:147], s[36:37], 0, v[148:149]
	s_mov_b32 m0, s3
	s_nop 0
	global_load_lds_dwordx4 v[146:147], off
	v_lshl_add_u64 v[146:147], s[36:37], 0, v[128:129]
	s_add_i32 m0, s3, 0x2000
	s_nop 0
	global_load_lds_dwordx4 v[146:147], off
	v_lshl_add_u64 v[146:147], v[228:229], 0, s[34:35]
	s_mov_b32 m0, s77
	s_nop 0
	global_load_lds_dwordx4 v[146:147], off
	v_lshl_add_u64 v[146:147], v[230:231], 0, s[34:35]
	s_mov_b32 m0, s78
	s_nop 0
	global_load_lds_dwordx4 v[146:147], off
	s_waitcnt vmcnt(8)
	s_waitcnt lgkmcnt(0)
	s_barrier
	s_setprio 1
	s_waitcnt lgkmcnt(0)
	v_mfma_f32_16x16x32_bf16 v[60:63], v[142:145], v[180:183], v[60:63]
	v_mfma_f32_16x16x32_bf16 v[52:55], v[156:159], v[180:183], v[52:55]
	v_mfma_f32_16x16x32_bf16 v[44:47], v[142:145], v[188:191], v[44:47]
	v_mfma_f32_16x16x32_bf16 v[36:39], v[156:159], v[188:191], v[36:39]
	v_mfma_f32_16x16x32_bf16 v[28:31], v[142:145], v[210:213], v[28:31]
	v_mfma_f32_16x16x32_bf16 v[20:23], v[156:159], v[210:213], v[20:23]
	v_mfma_f32_16x16x32_bf16 v[12:15], v[142:145], v[218:221], v[12:15]
	v_mfma_f32_16x16x32_bf16 v[4:7], v[156:159], v[218:221], v[4:7]
	v_mfma_f32_16x16x32_bf16 v[60:63], v[150:153], v[184:187], v[60:63]
	v_mfma_f32_16x16x32_bf16 v[52:55], v[160:163], v[184:187], v[52:55]
	v_mfma_f32_16x16x32_bf16 v[44:47], v[150:153], v[206:209], v[44:47]
	v_mfma_f32_16x16x32_bf16 v[36:39], v[160:163], v[206:209], v[36:39]
	v_mfma_f32_16x16x32_bf16 v[28:31], v[150:153], v[214:217], v[28:31]
	v_mfma_f32_16x16x32_bf16 v[20:23], v[160:163], v[214:217], v[20:23]
	v_mfma_f32_16x16x32_bf16 v[12:15], v[150:153], v[222:225], v[12:15]
	v_mfma_f32_16x16x32_bf16 v[4:7], v[160:163], v[222:225], v[4:7]
	v_mfma_f32_16x16x32_bf16 v[56:59], v[164:167], v[180:183], v[56:59]
	v_mfma_f32_16x16x32_bf16 v[48:51], v[172:175], v[180:183], v[48:51]
	v_mfma_f32_16x16x32_bf16 v[40:43], v[164:167], v[188:191], v[40:43]
	v_mfma_f32_16x16x32_bf16 v[32:35], v[172:175], v[188:191], v[32:35]
	v_mfma_f32_16x16x32_bf16 v[24:27], v[164:167], v[210:213], v[24:27]
	v_mfma_f32_16x16x32_bf16 v[16:19], v[172:175], v[210:213], v[16:19]
	v_mfma_f32_16x16x32_bf16 v[8:11], v[164:167], v[218:221], v[8:11]
	v_mfma_f32_16x16x32_bf16 v[0:3], v[172:175], v[218:221], v[0:3]
	v_mfma_f32_16x16x32_bf16 v[56:59], v[168:171], v[184:187], v[56:59]
	v_mfma_f32_16x16x32_bf16 v[48:51], v[176:179], v[184:187], v[48:51]
	v_mfma_f32_16x16x32_bf16 v[40:43], v[168:171], v[206:209], v[40:43]
	v_mfma_f32_16x16x32_bf16 v[32:35], v[176:179], v[206:209], v[32:35]
	v_mfma_f32_16x16x32_bf16 v[24:27], v[168:171], v[214:217], v[24:27]
	v_mfma_f32_16x16x32_bf16 v[16:19], v[176:179], v[214:217], v[16:19]
	v_mfma_f32_16x16x32_bf16 v[8:11], v[168:171], v[222:225], v[8:11]
	v_mfma_f32_16x16x32_bf16 v[0:3], v[176:179], v[222:225], v[0:3]
	s_setprio 0
	s_barrier
	s_add_i32 s38, s38, 2
	s_add_u32 s62, s62, 0x100
	s_addc_u32 s63, s63, 0
	s_add_u32 s28, s28, 0x100
	s_addc_u32 s29, s29, 0
	s_cmp_gt_u32 s38, 29
	s_cbranch_scc0 .LBB0_82
	s_and_b64 vcc, exec, s[48:49]
	s_cbranch_vccz .LBB0_85
	s_barrier

; #define PG8_STAGE(bufoff, gbase, voff) do { _Pragma("unroll") for (int _i = 0; _i < 2; ++_i) \
;         __builtin_amdgcn_global_load_lds((const unsigned*)((const char*)(gbase) + (voff)[_i]), (PG8_LAS unsigned*)(lds + (bufoff) + ldsw + _i * 8192), 16, 0, 0); } while (0)
; #define PG8_LDA(dst, b, h) do { _Pragma("unroll") for (int m = 0; m < 4; ++m) _Pragma("unroll") for (int k = 0; k < 2; ++k) dst[m][k] = *(const PG8_LAS bf16x8*)(lds + PG8_SA(b, h) + aoff + m * 2048 + k * 1024); } while (0)
; #define PG8_LDB(dst, b, h) do { _Pragma("unroll") for (int n = 0; n < 2; ++n) _Pragma("unroll") for (int k = 0; k < 2; ++k) dst[n][k] = *(const PG8_LAS bf16x8*)(lds + PG8_SB(b, h) + boff + n * 2048 + k * 1024); } while (0)
; #define PG8_MMA(ai, bj, At, Bt) do { __builtin_amdgcn_s_setprio(1); _Pragma("unroll") for (int m = 0; m < 4; ++m) _Pragma("unroll") for (int n = 0; n < 2; ++n) _Pragma("unroll") for (int k = 0; k < 2; ++k) \
;         acc[ai][bj][m][n] = __builtin_amdgcn_mfma_f32_16x16x32_bf16(Bt[n][k], At[m][k], acc[ai][bj][m][n], 0, 0, 0); __builtin_amdgcn_s_setprio(0); } while (0)
; #define PG8_WAIT_V(n) asm volatile("s_waitcnt vmcnt(" #n ")" ::: "memory")
; #define PG8_BAR __builtin_amdgcn_s_barrier()
; template <class Epi, class Sched, bool ALIGN_EPI = false, bool SP2 = false>
; __device__ __forceinline__ void gemm_phase(PG8_LAS unsigned char* lds, const Gemm g, const Sched& S, const Epi& E, int wave_s) {
;     ...
;         for (int t = 0; t < nt; t += 2) {
;             const bool last = (t == nt - 2);
;             const char* a1 = cA + (size_t)(t + 1) * kstep;
;             const char* a2 = last ? nA : cA + (size_t)(t + 2) * kstep; const char* b2 = last ? nB : cB + (size_t)(t + 2) * kstep;
;             const char* a3 = a2 + kstep; const char* b3 = b2 + kstep;
;             if (last && has_next) S.a_ready(nxt);
;             if constexpr (SP2) {
;             PG8_LDB(B0, 0, 0); PG8_LDB(B1, 0, 1); PG8_SCHED; PG8_LDA(At, 0, 0); PG8_STAGE(PG8_SA(1, 1), a1 + hstep, voffA);
;             PG8_WAIT_V(8); PG8_WAIT_L(0); PG8_BAR; PG8_MMA(0, 0, At, B0); PG8_MMA(0, 1, At, B1); PG8_BAR; PG8_SCHED;
;             PG8_LDA(At, 0, 1); PG8_STAGE(PG8_SB(0, 0), b2, voffB); PG8_STAGE(PG8_SB(0, 1), b2 + hstep, voffB); PG8_STAGE(PG8_SA(0, 0), a2, voffA);
;             PG8_WAIT_V(8); PG8_WAIT_L(0); PG8_BAR; PG8_MMA(1, 0, At, B0); PG8_MMA(1, 1, At, B1); PG8_BAR; PG8_SCHED;
.LBB0_115:
	s_add_u32 s64, s62, 0x100
	s_addc_u32 s65, s63, 0
	s_add_i32 s3, 0, 0x10000
	s_cmp_eq_u32 s53, 28
	s_cselect_b32 s75, s22, s65
	s_cselect_b32 s74, s23, s64
	v_add_u32_e32 v134, s3, v137
	s_cselect_b32 s67, s5, s39
	s_cselect_b32 s66, s28, s29
	s_add_i32 s26, 0, 0x14000
	ds_read_b128 v[140:143], v134
	ds_read_b128 v[144:147], v134 offset:1024
	ds_read_b128 v[150:153], v134 offset:2048
	ds_read_b128 v[156:159], v134 offset:3072
	v_add_u32_e32 v134, s26, v137
	ds_read_b128 v[160:163], v134
	ds_read_b128 v[164:167], v134 offset:1024
	ds_read_b128 v[168:171], v134 offset:2048
	ds_read_b128 v[172:175], v134 offset:3072
	v_lshl_add_u64 v[134:135], s[62:63], 0, v[130:131]
	s_add_i32 m0, s61, 0xc000
	ds_read_b128 v[176:179], v139
	ds_read_b128 v[180:183], v139 offset:1024
	ds_read_b128 v[184:187], v139 offset:2048
	ds_read_b128 v[188:191], v139 offset:3072
	ds_read_b128 v[206:209], v139 offset:4096
	ds_read_b128 v[210:213], v139 offset:5120
	ds_read_b128 v[214:217], v139 offset:6144
	ds_read_b128 v[218:221], v139 offset:7168
	global_load_lds_dwordx4 v[134:135], off
	v_lshl_add_u64 v[134:135], s[62:63], 0, v[132:133]
	s_add_i32 m0, s61, 0xe000
	s_nop 0
	global_load_lds_dwordx4 v[134:135], off
	s_waitcnt vmcnt(8)
	s_waitcnt lgkmcnt(0)
	s_barrier
	s_setprio 1
	s_waitcnt lgkmcnt(0)
	v_mfma_f32_16x16x32_bf16 v[124:127], v[140:143], v[176:179], v[124:127]
	v_mfma_f32_16x16x32_bf16 v[120:123], v[150:153], v[176:179], v[120:123]
	v_mfma_f32_16x16x32_bf16 v[108:111], v[140:143], v[184:187], v[108:111]
	v_mfma_f32_16x16x32_bf16 v[104:107], v[150:153], v[184:187], v[104:107]
	v_mfma_f32_16x16x32_bf16 v[92:95], v[140:143], v[206:209], v[92:95]
	v_mfma_f32_16x16x32_bf16 v[88:91], v[150:153], v[206:209], v[88:91]
	v_mfma_f32_16x16x32_bf16 v[76:79], v[140:143], v[214:217], v[76:79]
	v_mfma_f32_16x16x32_bf16 v[72:75], v[150:153], v[214:217], v[72:75]
	v_mfma_f32_16x16x32_bf16 v[124:127], v[144:147], v[180:183], v[124:127]
	v_mfma_f32_16x16x32_bf16 v[120:123], v[156:159], v[180:183], v[120:123]
	v_mfma_f32_16x16x32_bf16 v[108:111], v[144:147], v[188:191], v[108:111]
	v_mfma_f32_16x16x32_bf16 v[104:107], v[156:159], v[188:191], v[104:107]
	v_mfma_f32_16x16x32_bf16 v[92:95], v[144:147], v[210:213], v[92:95]
	v_mfma_f32_16x16x32_bf16 v[88:91], v[156:159], v[210:213], v[88:91]
	v_mfma_f32_16x16x32_bf16 v[76:79], v[144:147], v[218:221], v[76:79]
	v_mfma_f32_16x16x32_bf16 v[72:75], v[156:159], v[218:221], v[72:75]
	v_mfma_f32_16x16x32_bf16 v[116:119], v[160:163], v[176:179], v[116:119]
	v_mfma_f32_16x16x32_bf16 v[112:115], v[168:171], v[176:179], v[112:115]
	v_mfma_f32_16x16x32_bf16 v[100:103], v[160:163], v[184:187], v[100:103]
	v_mfma_f32_16x16x32_bf16 v[96:99], v[168:171], v[184:187], v[96:99]
	v_mfma_f32_16x16x32_bf16 v[84:87], v[160:163], v[206:209], v[84:87]
	v_mfma_f32_16x16x32_bf16 v[80:83], v[168:171], v[206:209], v[80:83]
	v_mfma_f32_16x16x32_bf16 v[68:71], v[160:163], v[214:217], v[68:71]
	v_mfma_f32_16x16x32_bf16 v[64:67], v[168:171], v[214:217], v[64:67]
	v_mfma_f32_16x16x32_bf16 v[116:119], v[164:167], v[180:183], v[116:119]
	v_mfma_f32_16x16x32_bf16 v[112:115], v[172:175], v[180:183], v[112:115]
	v_mfma_f32_16x16x32_bf16 v[100:103], v[164:167], v[188:191], v[100:103]
	v_mfma_f32_16x16x32_bf16 v[96:99], v[172:175], v[188:191], v[96:99]
	v_mfma_f32_16x16x32_bf16 v[84:87], v[164:167], v[210:213], v[84:87]
	v_mfma_f32_16x16x32_bf16 v[80:83], v[172:175], v[210:213], v[80:83]
	v_mfma_f32_16x16x32_bf16 v[68:71], v[164:167], v[218:221], v[68:71]
	v_mfma_f32_16x16x32_bf16 v[64:67], v[172:175], v[218:221], v[64:67]
	s_setprio 0
	s_barrier
	s_add_i32 s3, s3, s25
	v_lshl_add_u64 v[134:135], s[66:67], 0, v[148:149]
	s_mov_b32 m0, s3
	ds_read_b128 v[176:179], v139 offset:16384
	ds_read_b128 v[180:183], v139 offset:17408
	ds_read_b128 v[184:187], v139 offset:18432
	ds_read_b128 v[188:191], v139 offset:19456
	ds_read_b128 v[206:209], v139 offset:20480
	ds_read_b128 v[210:213], v139 offset:21504
	ds_read_b128 v[214:217], v139 offset:22528
	ds_read_b128 v[218:221], v139 offset:23552
	global_load_lds_dwordx4 v[134:135], off
	s_add_i32 m0, s3, 0x2000
	s_add_u32 s36, s66, 0x80000
	v_lshl_add_u64 v[222:223], s[66:67], 0, v[128:129]
	s_addc_u32 s37, s67, 0
	s_add_i32 s3, s26, s25
	global_load_lds_dwordx4 v[222:223], off
	v_lshl_add_u64 v[224:225], s[36:37], 0, v[148:149]
	s_mov_b32 m0, s3
	v_lshl_add_u64 v[226:227], s[74:75], 0, v[128:129]
	global_load_lds_dwordx4 v[224:225], off
	v_lshl_add_u64 v[224:225], s[36:37], 0, v[128:129]
	s_add_i32 m0, s3, 0x2000
	s_nop 0
	global_load_lds_dwordx4 v[224:225], off
	v_lshl_add_u64 v[224:225], s[74:75], 0, v[148:149]
	s_mov_b32 m0, s61
	s_nop 0
	global_load_lds_dwordx4 v[224:225], off
	s_mov_b32 m0, s73
	s_nop 0
	global_load_lds_dwordx4 v[226:227], off
	s_waitcnt vmcnt(8)
	s_waitcnt lgkmcnt(0)
	s_barrier
; #define PG8_STAGE(bufoff, gbase, voff) do { _Pragma("unroll") for (int _i = 0; _i < 2; ++_i) \
;         __builtin_amdgcn_global_load_lds((const unsigned*)((const char*)(gbase) + (voff)[_i]), (PG8_LAS unsigned*)(lds + (bufoff) + ldsw + _i * 8192), 16, 0, 0); } while (0)
; #define PG8_LDA(dst, b, h) do { _Pragma("unroll") for (int m = 0; m < 4; ++m) _Pragma("unroll") for (int k = 0; k < 2; ++k) dst[m][k] = *(const PG8_LAS bf16x8*)(lds + PG8_SA(b, h) + aoff + m * 2048 + k * 1024); } while (0)
; #define PG8_LDB(dst, b, h) do { _Pragma("unroll") for (int n = 0; n < 2; ++n) _Pragma("unroll") for (int k = 0; k < 2; ++k) dst[n][k] = *(const PG8_LAS bf16x8*)(lds + PG8_SB(b, h) + boff + n * 2048 + k * 1024); } while (0)
; #define PG8_MMA(ai, bj, At, Bt) do { __builtin_amdgcn_s_setprio(1); _Pragma("unroll") for (int m = 0; m < 4; ++m) _Pragma("unroll") for (int n = 0; n < 2; ++n) _Pragma("unroll") for (int k = 0; k < 2; ++k) \
;         acc[ai][bj][m][n] = __builtin_amdgcn_mfma_f32_16x16x32_bf16(Bt[n][k], At[m][k], acc[ai][bj][m][n], 0, 0, 0); __builtin_amdgcn_s_setprio(0); } while (0)
; #define PG8_WAIT_V(n) asm volatile("s_waitcnt vmcnt(" #n ")" ::: "memory")
; #define PG8_WAIT_L(n) asm volatile("s_waitcnt lgkmcnt(" #n ")" ::: "memory")
; #define PG8_BAR __builtin_amdgcn_s_barrier()
; #define PG8_SCHED __builtin_amdgcn_sched_barrier(0)
; template <class Epi, class Sched, bool ALIGN_EPI = false, bool SP2 = false>
; __device__ __forceinline__ void gemm_phase(PG8_LAS unsigned char* lds, const Gemm g, const Sched& S, const Epi& E, int wave_s) {
;     ...
;             PG8_WAIT_V(8); PG8_WAIT_L(0); PG8_BAR; PG8_MMA(1, 0, At, B0); PG8_MMA(1, 1, At, B1); PG8_BAR; PG8_SCHED;
;             PG8_LDB(B0, 1, 0); PG8_LDB(B1, 1, 1); PG8_SCHED; PG8_LDA(At, 1, 0); PG8_STAGE(PG8_SA(0, 1), a2 + hstep, voffA);
;             PG8_WAIT_V(8); PG8_WAIT_L(0); PG8_BAR; PG8_MMA(0, 0, At, B0); PG8_MMA(0, 1, At, B1); PG8_BAR; PG8_SCHED;
	s_setprio 1
	s_waitcnt lgkmcnt(0)
	v_mfma_f32_16x16x32_bf16 v[60:63], v[140:143], v[176:179], v[60:63]
	v_mfma_f32_16x16x32_bf16 v[56:59], v[150:153], v[176:179], v[56:59]
	v_mfma_f32_16x16x32_bf16 v[44:47], v[140:143], v[184:187], v[44:47]
	v_mfma_f32_16x16x32_bf16 v[40:43], v[150:153], v[184:187], v[40:43]
	v_mfma_f32_16x16x32_bf16 v[28:31], v[140:143], v[206:209], v[28:31]
	v_mfma_f32_16x16x32_bf16 v[24:27], v[150:153], v[206:209], v[24:27]
	v_mfma_f32_16x16x32_bf16 v[12:15], v[140:143], v[214:217], v[12:15]
	v_mfma_f32_16x16x32_bf16 v[8:11], v[150:153], v[214:217], v[8:11]
	v_mfma_f32_16x16x32_bf16 v[60:63], v[144:147], v[180:183], v[60:63]
	v_mfma_f32_16x16x32_bf16 v[56:59], v[156:159], v[180:183], v[56:59]
	v_mfma_f32_16x16x32_bf16 v[44:47], v[144:147], v[188:191], v[44:47]
	v_mfma_f32_16x16x32_bf16 v[40:43], v[156:159], v[188:191], v[40:43]
	v_mfma_f32_16x16x32_bf16 v[28:31], v[144:147], v[210:213], v[28:31]
	v_mfma_f32_16x16x32_bf16 v[24:27], v[156:159], v[210:213], v[24:27]
	v_mfma_f32_16x16x32_bf16 v[12:15], v[144:147], v[218:221], v[12:15]
	v_mfma_f32_16x16x32_bf16 v[8:11], v[156:159], v[218:221], v[8:11]
	v_mfma_f32_16x16x32_bf16 v[52:55], v[160:163], v[176:179], v[52:55]
	v_mfma_f32_16x16x32_bf16 v[48:51], v[168:171], v[176:179], v[48:51]
	v_mfma_f32_16x16x32_bf16 v[36:39], v[160:163], v[184:187], v[36:39]
	v_mfma_f32_16x16x32_bf16 v[32:35], v[168:171], v[184:187], v[32:35]
	v_mfma_f32_16x16x32_bf16 v[20:23], v[160:163], v[206:209], v[20:23]
	v_mfma_f32_16x16x32_bf16 v[16:19], v[168:171], v[206:209], v[16:19]
	v_mfma_f32_16x16x32_bf16 v[4:7], v[160:163], v[214:217], v[4:7]
	v_mfma_f32_16x16x32_bf16 v[0:3], v[168:171], v[214:217], v[0:3]
	v_mfma_f32_16x16x32_bf16 v[52:55], v[164:167], v[180:183], v[52:55]
	v_mfma_f32_16x16x32_bf16 v[48:51], v[172:175], v[180:183], v[48:51]
	v_mfma_f32_16x16x32_bf16 v[36:39], v[164:167], v[188:191], v[36:39]
	v_mfma_f32_16x16x32_bf16 v[32:35], v[172:175], v[188:191], v[32:35]
	v_mfma_f32_16x16x32_bf16 v[20:23], v[164:167], v[210:213], v[20:23]
	v_mfma_f32_16x16x32_bf16 v[16:19], v[172:175], v[210:213], v[16:19]
	v_mfma_f32_16x16x32_bf16 v[4:7], v[164:167], v[218:221], v[4:7]
	v_mfma_f32_16x16x32_bf16 v[0:3], v[172:175], v[218:221], v[0:3]
	s_setprio 0
	s_barrier
	s_add_i32 s3, 0, 0x18000
	s_add_i32 s26, 0, 0x1c000
	v_add_u32_e32 v156, s3, v137
	v_add_u32_e32 v172, s26, v137
	ds_read_b128 v[140:143], v156
	ds_read_b128 v[144:147], v156 offset:1024
	ds_read_b128 v[150:153], v156 offset:2048
	ds_read_b128 v[156:159], v156 offset:3072
	ds_read_b128 v[160:163], v172
	ds_read_b128 v[164:167], v172 offset:1024
	ds_read_b128 v[168:171], v172 offset:2048
	ds_read_b128 v[172:175], v172 offset:3072
	s_add_u32 s36, s74, 0x80000
	s_addc_u32 s37, s75, 0
	s_mov_b32 m0, s76
	v_lshl_add_u64 v[228:229], s[36:37], 0, v[148:149]
	ds_read_b128 v[176:179], v139 offset:32768
	ds_read_b128 v[180:183], v139 offset:33792
	ds_read_b128 v[184:187], v139 offset:34816
	ds_read_b128 v[188:191], v139 offset:35840
	ds_read_b128 v[206:209], v139 offset:36864
	ds_read_b128 v[210:213], v139 offset:37888
	ds_read_b128 v[214:217], v139 offset:38912
	ds_read_b128 v[218:221], v139 offset:39936
	global_load_lds_dwordx4 v[228:229], off
	v_lshl_add_u64 v[228:229], s[36:37], 0, v[128:129]
	s_mov_b32 m0, s77
	s_nop 0
	global_load_lds_dwordx4 v[228:229], off
	s_waitcnt vmcnt(8)
	s_waitcnt lgkmcnt(0)
	s_barrier
	s_setprio 1
	s_waitcnt lgkmcnt(0)
	v_mfma_f32_16x16x32_bf16 v[124:127], v[140:143], v[176:179], v[124:127]
	v_mfma_f32_16x16x32_bf16 v[120:123], v[150:153], v[176:179], v[120:123]
	v_mfma_f32_16x16x32_bf16 v[108:111], v[140:143], v[184:187], v[108:111]
	v_mfma_f32_16x16x32_bf16 v[104:107], v[150:153], v[184:187], v[104:107]
	v_mfma_f32_16x16x32_bf16 v[92:95], v[140:143], v[206:209], v[92:95]
	v_mfma_f32_16x16x32_bf16 v[88:91], v[150:153], v[206:209], v[88:91]
	v_mfma_f32_16x16x32_bf16 v[76:79], v[140:143], v[214:217], v[76:79]
	v_mfma_f32_16x16x32_bf16 v[72:75], v[150:153], v[214:217], v[72:75]
	v_mfma_f32_16x16x32_bf16 v[124:127], v[144:147], v[180:183], v[124:127]
	v_mfma_f32_16x16x32_bf16 v[120:123], v[156:159], v[180:183], v[120:123]
	v_mfma_f32_16x16x32_bf16 v[108:111], v[144:147], v[188:191], v[108:111]
	v_mfma_f32_16x16x32_bf16 v[104:107], v[156:159], v[188:191], v[104:107]
	v_mfma_f32_16x16x32_bf16 v[92:95], v[144:147], v[210:213], v[92:95]
	v_mfma_f32_16x16x32_bf16 v[88:91], v[156:159], v[210:213], v[88:91]
	v_mfma_f32_16x16x32_bf16 v[76:79], v[144:147], v[218:221], v[76:79]
	v_mfma_f32_16x16x32_bf16 v[72:75], v[156:159], v[218:221], v[72:75]
	v_mfma_f32_16x16x32_bf16 v[116:119], v[160:163], v[176:179], v[116:119]
	v_mfma_f32_16x16x32_bf16 v[112:115], v[168:171], v[176:179], v[112:115]
	v_mfma_f32_16x16x32_bf16 v[100:103], v[160:163], v[184:187], v[100:103]
	v_mfma_f32_16x16x32_bf16 v[96:99], v[168:171], v[184:187], v[96:99]
	v_mfma_f32_16x16x32_bf16 v[84:87], v[160:163], v[206:209], v[84:87]
	v_mfma_f32_16x16x32_bf16 v[80:83], v[168:171], v[206:209], v[80:83]
	v_mfma_f32_16x16x32_bf16 v[68:71], v[160:163], v[214:217], v[68:71]
	v_mfma_f32_16x16x32_bf16 v[64:67], v[168:171], v[214:217], v[64:67]
	v_mfma_f32_16x16x32_bf16 v[116:119], v[164:167], v[180:183], v[116:119]
	v_mfma_f32_16x16x32_bf16 v[112:115], v[172:175], v[180:183], v[112:115]
	v_mfma_f32_16x16x32_bf16 v[100:103], v[164:167], v[188:191], v[100:103]
	v_mfma_f32_16x16x32_bf16 v[96:99], v[172:175], v[188:191], v[96:99]
	v_mfma_f32_16x16x32_bf16 v[84:87], v[164:167], v[210:213], v[84:87]
	v_mfma_f32_16x16x32_bf16 v[80:83], v[172:175], v[210:213], v[80:83]
	v_mfma_f32_16x16x32_bf16 v[68:71], v[164:167], v[218:221], v[68:71]
	v_mfma_f32_16x16x32_bf16 v[64:67], v[172:175], v[218:221], v[64:67]
	s_setprio 0
	s_barrier
; #define PG8_STAGE(bufoff, gbase, voff) do { _Pragma("unroll") for (int _i = 0; _i < 2; ++_i) \
;         __builtin_amdgcn_global_load_lds((const unsigned*)((const char*)(gbase) + (voff)[_i]), (PG8_LAS unsigned*)(lds + (bufoff) + ldsw + _i * 8192), 16, 0, 0); } while (0)
; #define PG8_LDA(dst, b, h) do { _Pragma("unroll") for (int m = 0; m < 4; ++m) _Pragma("unroll") for (int k = 0; k < 2; ++k) dst[m][k] = *(const PG8_LAS bf16x8*)(lds + PG8_SA(b, h) + aoff + m * 2048 + k * 1024); } while (0)
; #define PG8_MMA(ai, bj, At, Bt) do { __builtin_amdgcn_s_setprio(1); _Pragma("unroll") for (int m = 0; m < 4; ++m) _Pragma("unroll") for (int n = 0; n < 2; ++n) _Pragma("unroll") for (int k = 0; k < 2; ++k) \
;         acc[ai][bj][m][n] = __builtin_amdgcn_mfma_f32_16x16x32_bf16(Bt[n][k], At[m][k], acc[ai][bj][m][n], 0, 0, 0); __builtin_amdgcn_s_setprio(0); } while (0)
; #define PG8_WAIT_V(n) asm volatile("s_waitcnt vmcnt(" #n ")" ::: "memory")
; #define PG8_WAIT_L(n) asm volatile("s_waitcnt lgkmcnt(" #n ")" ::: "memory")
; #define PG8_BAR __builtin_amdgcn_s_barrier()
; #define PG8_SCHED __builtin_amdgcn_sched_barrier(0)
; template <class Epi, class Sched, bool ALIGN_EPI = false, bool SP2 = false>
; __device__ __forceinline__ void gemm_phase(PG8_LAS unsigned char* lds, const Gemm g, const Sched& S, const Epi& E, int wave_s) {
;     ...
;         for (int t = 0; t < nt; t += 2) {
;             const bool last = (t == nt - 2);
;             const char* a1 = cA + (size_t)(t + 1) * kstep;
;             const char* a2 = last ? nA : cA + (size_t)(t + 2) * kstep; const char* b2 = last ? nB : cB + (size_t)(t + 2) * kstep;
;             const char* a3 = a2 + kstep; const char* b3 = b2 + kstep;
;             if (last && has_next) S.a_ready(nxt);
;     ...
;             PG8_LDA(At, 1, 1); PG8_STAGE(PG8_SB(1, 0), b3, voffB); PG8_STAGE(PG8_SB(1, 1), b3 + hstep, voffB); PG8_STAGE(PG8_SA(1, 0), a3, voffA);
;             PG8_WAIT_V(8); PG8_WAIT_L(0); PG8_BAR; PG8_MMA(1, 0, At, B0); PG8_MMA(1, 1, At, B1); PG8_BAR; PG8_SCHED;
	s_add_i32 s3, s3, s25
	v_lshl_add_u64 v[134:135], v[134:135], 0, s[34:35]
	s_mov_b32 m0, s3
	ds_read_b128 v[176:179], v139 offset:49152
	ds_read_b128 v[180:183], v139 offset:50176
	ds_read_b128 v[184:187], v139 offset:51200
	ds_read_b128 v[188:191], v139 offset:52224
	ds_read_b128 v[206:209], v139 offset:53248
	ds_read_b128 v[210:213], v139 offset:54272
	ds_read_b128 v[214:217], v139 offset:55296
	ds_read_b128 v[218:221], v139 offset:56320
	global_load_lds_dwordx4 v[134:135], off
	s_add_i32 m0, s3, 0x2000
	s_add_u32 s36, s66, 0x80080
	v_lshl_add_u64 v[134:135], v[222:223], 0, s[34:35]
	s_addc_u32 s37, s67, 0
	s_add_i32 s3, s26, s25
	global_load_lds_dwordx4 v[134:135], off
	v_lshl_add_u64 v[134:135], s[36:37], 0, v[148:149]
	s_mov_b32 m0, s3
	s_nop 0
	global_load_lds_dwordx4 v[134:135], off
	v_lshl_add_u64 v[134:135], s[36:37], 0, v[128:129]
	s_add_i32 m0, s3, 0x2000
	s_nop 0
	global_load_lds_dwordx4 v[134:135], off
	v_lshl_add_u64 v[134:135], v[224:225], 0, s[34:35]
	s_mov_b32 m0, s79
	s_nop 0
	global_load_lds_dwordx4 v[134:135], off
	v_lshl_add_u64 v[134:135], v[226:227], 0, s[34:35]
	s_mov_b32 m0, s18
	s_nop 0
	global_load_lds_dwordx4 v[134:135], off
	s_waitcnt vmcnt(8)
	s_waitcnt lgkmcnt(0)
	s_barrier
	s_setprio 1
	s_waitcnt lgkmcnt(0)
	v_mfma_f32_16x16x32_bf16 v[60:63], v[140:143], v[176:179], v[60:63]
	v_mfma_f32_16x16x32_bf16 v[56:59], v[150:153], v[176:179], v[56:59]
	v_mfma_f32_16x16x32_bf16 v[44:47], v[140:143], v[184:187], v[44:47]
	v_mfma_f32_16x16x32_bf16 v[40:43], v[150:153], v[184:187], v[40:43]
	v_mfma_f32_16x16x32_bf16 v[28:31], v[140:143], v[206:209], v[28:31]
	v_mfma_f32_16x16x32_bf16 v[24:27], v[150:153], v[206:209], v[24:27]
	v_mfma_f32_16x16x32_bf16 v[12:15], v[140:143], v[214:217], v[12:15]
	v_mfma_f32_16x16x32_bf16 v[8:11], v[150:153], v[214:217], v[8:11]
	v_mfma_f32_16x16x32_bf16 v[60:63], v[144:147], v[180:183], v[60:63]
	v_mfma_f32_16x16x32_bf16 v[56:59], v[156:159], v[180:183], v[56:59]
	v_mfma_f32_16x16x32_bf16 v[44:47], v[144:147], v[188:191], v[44:47]
	v_mfma_f32_16x16x32_bf16 v[40:43], v[156:159], v[188:191], v[40:43]
	v_mfma_f32_16x16x32_bf16 v[28:31], v[144:147], v[210:213], v[28:31]
	v_mfma_f32_16x16x32_bf16 v[24:27], v[156:159], v[210:213], v[24:27]
	v_mfma_f32_16x16x32_bf16 v[12:15], v[144:147], v[218:221], v[12:15]
	v_mfma_f32_16x16x32_bf16 v[8:11], v[156:159], v[218:221], v[8:11]
	v_mfma_f32_16x16x32_bf16 v[52:55], v[160:163], v[176:179], v[52:55]
	v_mfma_f32_16x16x32_bf16 v[48:51], v[168:171], v[176:179], v[48:51]
	v_mfma_f32_16x16x32_bf16 v[36:39], v[160:163], v[184:187], v[36:39]
	v_mfma_f32_16x16x32_bf16 v[32:35], v[168:171], v[184:187], v[32:35]
	v_mfma_f32_16x16x32_bf16 v[20:23], v[160:163], v[206:209], v[20:23]
	v_mfma_f32_16x16x32_bf16 v[16:19], v[168:171], v[206:209], v[16:19]
	v_mfma_f32_16x16x32_bf16 v[4:7], v[160:163], v[214:217], v[4:7]
	v_mfma_f32_16x16x32_bf16 v[0:3], v[168:171], v[214:217], v[0:3]
	v_mfma_f32_16x16x32_bf16 v[52:55], v[164:167], v[180:183], v[52:55]
	v_mfma_f32_16x16x32_bf16 v[48:51], v[172:175], v[180:183], v[48:51]
	v_mfma_f32_16x16x32_bf16 v[36:39], v[164:167], v[188:191], v[36:39]
	v_mfma_f32_16x16x32_bf16 v[32:35], v[172:175], v[188:191], v[32:35]
	v_mfma_f32_16x16x32_bf16 v[20:23], v[164:167], v[210:213], v[20:23]
	v_mfma_f32_16x16x32_bf16 v[16:19], v[172:175], v[210:213], v[16:19]
	v_mfma_f32_16x16x32_bf16 v[4:7], v[164:167], v[218:221], v[4:7]
	v_mfma_f32_16x16x32_bf16 v[0:3], v[172:175], v[218:221], v[0:3]
	s_setprio 0
	s_barrier
	s_add_i32 s53, s53, 2
	s_add_u32 s29, s29, 0x100
	s_addc_u32 s39, s39, 0
	s_cmp_gt_u32 s53, 29
	s_mov_b64 s[62:63], s[64:65]
	s_cbranch_scc0 .LBB0_115
	s_and_b64 vcc, exec, s[48:49]
	s_cbranch_vccz .LBB0_118
	s_barrier

; #define PG8_STAGE(bufoff, gbase, voff) do { _Pragma("unroll") for (int _i = 0; _i < 2; ++_i) \
;         __builtin_amdgcn_global_load_lds((const unsigned*)((const char*)(gbase) + (voff)[_i]), (PG8_LAS unsigned*)(lds + (bufoff) + ldsw + _i * 8192), 16, 0, 0); } while (0)
; #define PG8_LDA(dst, b, h) do { _Pragma("unroll") for (int m = 0; m < 4; ++m) _Pragma("unroll") for (int k = 0; k < 2; ++k) dst[m][k] = *(const PG8_LAS bf16x8*)(lds + PG8_SA(b, h) + aoff + m * 2048 + k * 1024); } while (0)
; #define PG8_LDB(dst, b, h) do { _Pragma("unroll") for (int n = 0; n < 2; ++n) _Pragma("unroll") for (int k = 0; k < 2; ++k) dst[n][k] = *(const PG8_LAS bf16x8*)(lds + PG8_SB(b, h) + boff + n * 2048 + k * 1024); } while (0)
; #define PG8_MMA(ai, bj, At, Bt) do { __builtin_amdgcn_s_setprio(1); _Pragma("unroll") for (int m = 0; m < 4; ++m) _Pragma("unroll") for (int n = 0; n < 2; ++n) _Pragma("unroll") for (int k = 0; k < 2; ++k) \
;         acc[ai][bj][m][n] = __builtin_amdgcn_mfma_f32_16x16x32_bf16(Bt[n][k], At[m][k], acc[ai][bj][m][n], 0, 0, 0); __builtin_amdgcn_s_setprio(0); } while (0)
; #define PG8_WAIT_V(n) asm volatile("s_waitcnt vmcnt(" #n ")" ::: "memory")
; #define PG8_WAIT_L(n) asm volatile("s_waitcnt lgkmcnt(" #n ")" ::: "memory")
; template <class Epi, class Sched, bool ALIGN_EPI = false, bool SP2 = false>
; __device__ __forceinline__ void gemm_phase(PG8_LAS unsigned char* lds, const Gemm g, const Sched& S, const Epi& E, int wave_s) {
;     ...
;             const bool last = (t == nt - 2);
;             const char* a1 = cA + (size_t)(t + 1) * kstep;
;             const char* a2 = last ? nA : cA + (size_t)(t + 2) * kstep; const char* b2 = last ? nB : cB + (size_t)(t + 2) * kstep;
;             const char* a3 = a2 + kstep; const char* b3 = b2 + kstep;
;             if (last && has_next) S.a_ready(nxt);
;             if constexpr (SP2) {
;             PG8_LDB(B0, 0, 0); PG8_LDB(B1, 0, 1); PG8_SCHED; PG8_LDA(At, 0, 0); PG8_STAGE(PG8_SA(1, 1), a1 + hstep, voffA);
;             PG8_WAIT_V(8); PG8_WAIT_L(0); PG8_BAR; PG8_MMA(0, 0, At, B0); PG8_MMA(0, 1, At, B1); PG8_BAR; PG8_SCHED;
;             PG8_LDA(At, 0, 1); PG8_STAGE(PG8_SB(0, 0), b2, voffB); PG8_STAGE(PG8_SB(0, 1), b2 + hstep, voffB); PG8_STAGE(PG8_SA(0, 0), a2, voffA);
;             PG8_WAIT_V(8); PG8_WAIT_L(0); PG8_BAR; PG8_MMA(1, 0, At, B0); PG8_MMA(1, 1, At, B1); PG8_BAR; PG8_SCHED;
.LBB0_387:
	s_add_u32 s36, s60, 0xfffe0080
	s_addc_u32 s37, s61, -1
	s_add_i32 s75, 0, 0x10000
	s_cmp_eq_u32 s74, 4
	s_cselect_b32 s65, s22, s37
	s_cselect_b32 s64, s23, s36
	v_add_u32_e32 v138, s75, v141
	s_cselect_b32 s63, s5, s53
	s_cselect_b32 s62, s29, s49
	s_add_i32 s36, 0, 0x14000
	ds_read_b128 v[144:147], v138
	ds_read_b128 v[156:159], v138 offset:1024
	ds_read_b128 v[160:163], v138 offset:2048
	ds_read_b128 v[164:167], v138 offset:3072
	v_add_u32_e32 v138, s36, v141
	ds_read_b128 v[168:171], v138
	ds_read_b128 v[172:175], v138 offset:1024
	ds_read_b128 v[176:179], v138 offset:2048
	ds_read_b128 v[180:183], v138 offset:3072
	v_lshl_add_u64 v[138:139], s[60:61], 0, v[134:135]
	s_add_i32 m0, s25, 0xc000
	ds_read_b128 v[184:187], v143
	ds_read_b128 v[188:191], v143 offset:1024
	ds_read_b128 v[206:209], v143 offset:2048
	ds_read_b128 v[210:213], v143 offset:3072
	ds_read_b128 v[214:217], v143 offset:4096
	ds_read_b128 v[218:221], v143 offset:5120
	ds_read_b128 v[222:225], v143 offset:6144
	ds_read_b128 v[226:229], v143 offset:7168
	global_load_lds_dwordx4 v[138:139], off
	v_lshl_add_u64 v[138:139], s[60:61], 0, v[136:137]
	s_add_i32 m0, s25, 0xe000
	s_nop 0
	global_load_lds_dwordx4 v[138:139], off
	s_waitcnt vmcnt(8)
	s_waitcnt lgkmcnt(0)
	s_barrier
	s_setprio 1
	s_waitcnt lgkmcnt(0)
	v_mfma_f32_16x16x32_bf16 v[124:127], v[144:147], v[184:187], v[124:127]
	v_mfma_f32_16x16x32_bf16 v[120:123], v[160:163], v[184:187], v[120:123]
	v_mfma_f32_16x16x32_bf16 v[108:111], v[144:147], v[206:209], v[108:111]
	v_mfma_f32_16x16x32_bf16 v[104:107], v[160:163], v[206:209], v[104:107]
	v_mfma_f32_16x16x32_bf16 v[92:95], v[144:147], v[214:217], v[92:95]
	v_mfma_f32_16x16x32_bf16 v[88:91], v[160:163], v[214:217], v[88:91]
	v_mfma_f32_16x16x32_bf16 v[76:79], v[144:147], v[222:225], v[76:79]
	v_mfma_f32_16x16x32_bf16 v[72:75], v[160:163], v[222:225], v[72:75]
	v_mfma_f32_16x16x32_bf16 v[124:127], v[156:159], v[188:191], v[124:127]
	v_mfma_f32_16x16x32_bf16 v[120:123], v[164:167], v[188:191], v[120:123]
	v_mfma_f32_16x16x32_bf16 v[108:111], v[156:159], v[210:213], v[108:111]
	v_mfma_f32_16x16x32_bf16 v[104:107], v[164:167], v[210:213], v[104:107]
	v_mfma_f32_16x16x32_bf16 v[92:95], v[156:159], v[218:221], v[92:95]
	v_mfma_f32_16x16x32_bf16 v[88:91], v[164:167], v[218:221], v[88:91]
	v_mfma_f32_16x16x32_bf16 v[76:79], v[156:159], v[226:229], v[76:79]
	v_mfma_f32_16x16x32_bf16 v[72:75], v[164:167], v[226:229], v[72:75]
	v_mfma_f32_16x16x32_bf16 v[116:119], v[168:171], v[184:187], v[116:119]
	v_mfma_f32_16x16x32_bf16 v[112:115], v[176:179], v[184:187], v[112:115]
	v_mfma_f32_16x16x32_bf16 v[100:103], v[168:171], v[206:209], v[100:103]
	v_mfma_f32_16x16x32_bf16 v[96:99], v[176:179], v[206:209], v[96:99]
	v_mfma_f32_16x16x32_bf16 v[84:87], v[168:171], v[214:217], v[84:87]
	v_mfma_f32_16x16x32_bf16 v[80:83], v[176:179], v[214:217], v[80:83]
	v_mfma_f32_16x16x32_bf16 v[68:71], v[168:171], v[222:225], v[68:71]
	v_mfma_f32_16x16x32_bf16 v[64:67], v[176:179], v[222:225], v[64:67]
	v_mfma_f32_16x16x32_bf16 v[116:119], v[172:175], v[188:191], v[116:119]
	v_mfma_f32_16x16x32_bf16 v[112:115], v[180:183], v[188:191], v[112:115]
	v_mfma_f32_16x16x32_bf16 v[100:103], v[172:175], v[210:213], v[100:103]
	v_mfma_f32_16x16x32_bf16 v[96:99], v[180:183], v[210:213], v[96:99]
	v_mfma_f32_16x16x32_bf16 v[84:87], v[172:175], v[218:221], v[84:87]
	v_mfma_f32_16x16x32_bf16 v[80:83], v[180:183], v[218:221], v[80:83]
	v_mfma_f32_16x16x32_bf16 v[68:71], v[172:175], v[226:229], v[68:71]
	v_mfma_f32_16x16x32_bf16 v[64:67], v[180:183], v[226:229], v[64:67]
	s_setprio 0
	s_barrier
	s_add_i32 s37, s75, s21
	v_lshl_add_u64 v[138:139], s[62:63], 0, v[148:149]
	s_mov_b32 m0, s37
	ds_read_b128 v[184:187], v143 offset:16384
	ds_read_b128 v[188:191], v143 offset:17408
	ds_read_b128 v[206:209], v143 offset:18432
	ds_read_b128 v[210:213], v143 offset:19456
	ds_read_b128 v[214:217], v143 offset:20480
	ds_read_b128 v[218:221], v143 offset:21504
	ds_read_b128 v[222:225], v143 offset:22528
	ds_read_b128 v[226:229], v143 offset:23552
	global_load_lds_dwordx4 v[138:139], off
	s_add_i32 m0, s37, 0x2000
	s_add_u32 s76, s62, 0x20000
	v_lshl_add_u64 v[150:151], s[62:63], 0, v[128:129]
	s_addc_u32 s77, s63, 0
	s_add_i32 s36, s36, s21
	global_load_lds_dwordx4 v[150:151], off
	v_lshl_add_u64 v[152:153], s[76:77], 0, v[148:149]
	s_mov_b32 m0, s36
	v_lshl_add_u64 v[230:231], s[64:65], 0, v[130:131]
	global_load_lds_dwordx4 v[152:153], off
	v_lshl_add_u64 v[152:153], s[76:77], 0, v[128:129]
	s_add_i32 m0, s36, 0x2000
	s_nop 0
	global_load_lds_dwordx4 v[152:153], off
	v_lshl_add_u64 v[152:153], s[64:65], 0, v[132:133]
	s_mov_b32 m0, s25
	s_nop 0
	global_load_lds_dwordx4 v[152:153], off
	s_mov_b32 m0, s38
	s_nop 0
	global_load_lds_dwordx4 v[230:231], off
	s_waitcnt vmcnt(8)
	s_waitcnt lgkmcnt(0)
	s_barrier
; #define PG8_STAGE(bufoff, gbase, voff) do { _Pragma("unroll") for (int _i = 0; _i < 2; ++_i) \
;         __builtin_amdgcn_global_load_lds((const unsigned*)((const char*)(gbase) + (voff)[_i]), (PG8_LAS unsigned*)(lds + (bufoff) + ldsw + _i * 8192), 16, 0, 0); } while (0)
; #define PG8_LDA(dst, b, h) do { _Pragma("unroll") for (int m = 0; m < 4; ++m) _Pragma("unroll") for (int k = 0; k < 2; ++k) dst[m][k] = *(const PG8_LAS bf16x8*)(lds + PG8_SA(b, h) + aoff + m * 2048 + k * 1024); } while (0)
; #define PG8_LDB(dst, b, h) do { _Pragma("unroll") for (int n = 0; n < 2; ++n) _Pragma("unroll") for (int k = 0; k < 2; ++k) dst[n][k] = *(const PG8_LAS bf16x8*)(lds + PG8_SB(b, h) + boff + n * 2048 + k * 1024); } while (0)
; #define PG8_MMA(ai, bj, At, Bt) do { __builtin_amdgcn_s_setprio(1); _Pragma("unroll") for (int m = 0; m < 4; ++m) _Pragma("unroll") for (int n = 0; n < 2; ++n) _Pragma("unroll") for (int k = 0; k < 2; ++k) \
;         acc[ai][bj][m][n] = __builtin_amdgcn_mfma_f32_16x16x32_bf16(Bt[n][k], At[m][k], acc[ai][bj][m][n], 0, 0, 0); __builtin_amdgcn_s_setprio(0); } while (0)
; #define PG8_WAIT_V(n) asm volatile("s_waitcnt vmcnt(" #n ")" ::: "memory")
; #define PG8_WAIT_L(n) asm volatile("s_waitcnt lgkmcnt(" #n ")" ::: "memory")
; #define PG8_BAR __builtin_amdgcn_s_barrier()
; #define PG8_SCHED __builtin_amdgcn_sched_barrier(0)
; template <class Epi, class Sched, bool ALIGN_EPI = false, bool SP2 = false>
; __device__ __forceinline__ void gemm_phase(PG8_LAS unsigned char* lds, const Gemm g, const Sched& S, const Epi& E, int wave_s) {
;     ...
;             PG8_WAIT_V(8); PG8_WAIT_L(0); PG8_BAR; PG8_MMA(1, 0, At, B0); PG8_MMA(1, 1, At, B1); PG8_BAR; PG8_SCHED;
;             PG8_LDB(B0, 1, 0); PG8_LDB(B1, 1, 1); PG8_SCHED; PG8_LDA(At, 1, 0); PG8_STAGE(PG8_SA(0, 1), a2 + hstep, voffA);
;             PG8_WAIT_V(8); PG8_WAIT_L(0); PG8_BAR; PG8_MMA(0, 0, At, B0); PG8_MMA(0, 1, At, B1); PG8_BAR; PG8_SCHED;
	s_setprio 1
	s_waitcnt lgkmcnt(0)
	v_mfma_f32_16x16x32_bf16 v[60:63], v[144:147], v[184:187], v[60:63]
	v_mfma_f32_16x16x32_bf16 v[56:59], v[160:163], v[184:187], v[56:59]
	v_mfma_f32_16x16x32_bf16 v[44:47], v[144:147], v[206:209], v[44:47]
	v_mfma_f32_16x16x32_bf16 v[40:43], v[160:163], v[206:209], v[40:43]
	v_mfma_f32_16x16x32_bf16 v[28:31], v[144:147], v[214:217], v[28:31]
	v_mfma_f32_16x16x32_bf16 v[24:27], v[160:163], v[214:217], v[24:27]
	v_mfma_f32_16x16x32_bf16 v[12:15], v[144:147], v[222:225], v[12:15]
	v_mfma_f32_16x16x32_bf16 v[8:11], v[160:163], v[222:225], v[8:11]
	v_mfma_f32_16x16x32_bf16 v[60:63], v[156:159], v[188:191], v[60:63]
	v_mfma_f32_16x16x32_bf16 v[56:59], v[164:167], v[188:191], v[56:59]
	v_mfma_f32_16x16x32_bf16 v[44:47], v[156:159], v[210:213], v[44:47]
	v_mfma_f32_16x16x32_bf16 v[40:43], v[164:167], v[210:213], v[40:43]
	v_mfma_f32_16x16x32_bf16 v[28:31], v[156:159], v[218:221], v[28:31]
	v_mfma_f32_16x16x32_bf16 v[24:27], v[164:167], v[218:221], v[24:27]
	v_mfma_f32_16x16x32_bf16 v[12:15], v[156:159], v[226:229], v[12:15]
	v_mfma_f32_16x16x32_bf16 v[8:11], v[164:167], v[226:229], v[8:11]
	v_mfma_f32_16x16x32_bf16 v[52:55], v[168:171], v[184:187], v[52:55]
	v_mfma_f32_16x16x32_bf16 v[48:51], v[176:179], v[184:187], v[48:51]
	v_mfma_f32_16x16x32_bf16 v[36:39], v[168:171], v[206:209], v[36:39]
	v_mfma_f32_16x16x32_bf16 v[32:35], v[176:179], v[206:209], v[32:35]
	v_mfma_f32_16x16x32_bf16 v[20:23], v[168:171], v[214:217], v[20:23]
	v_mfma_f32_16x16x32_bf16 v[16:19], v[176:179], v[214:217], v[16:19]
	v_mfma_f32_16x16x32_bf16 v[4:7], v[168:171], v[222:225], v[4:7]
	v_mfma_f32_16x16x32_bf16 v[0:3], v[176:179], v[222:225], v[0:3]
	v_mfma_f32_16x16x32_bf16 v[52:55], v[172:175], v[188:191], v[52:55]
	v_mfma_f32_16x16x32_bf16 v[48:51], v[180:183], v[188:191], v[48:51]
	v_mfma_f32_16x16x32_bf16 v[36:39], v[172:175], v[210:213], v[36:39]
	v_mfma_f32_16x16x32_bf16 v[32:35], v[180:183], v[210:213], v[32:35]
	v_mfma_f32_16x16x32_bf16 v[20:23], v[172:175], v[218:221], v[20:23]
	v_mfma_f32_16x16x32_bf16 v[16:19], v[180:183], v[218:221], v[16:19]
	v_mfma_f32_16x16x32_bf16 v[4:7], v[172:175], v[226:229], v[4:7]
	v_mfma_f32_16x16x32_bf16 v[0:3], v[180:183], v[226:229], v[0:3]
	s_setprio 0
	s_barrier
	s_add_i32 s36, 0, 0x18000
	s_add_i32 s37, 0, 0x1c000
	v_add_u32_e32 v164, s36, v141
	v_add_u32_e32 v180, s37, v141
	ds_read_b128 v[144:147], v164
	ds_read_b128 v[156:159], v164 offset:1024
	ds_read_b128 v[160:163], v164 offset:2048
	ds_read_b128 v[164:167], v164 offset:3072
	ds_read_b128 v[168:171], v180
	ds_read_b128 v[172:175], v180 offset:1024
	ds_read_b128 v[176:179], v180 offset:2048
	ds_read_b128 v[180:183], v180 offset:3072
	s_add_u32 s64, s64, 0x20000
	s_addc_u32 s65, s65, 0
	s_mov_b32 m0, s39
	v_lshl_add_u64 v[232:233], s[64:65], 0, v[132:133]
	ds_read_b128 v[184:187], v143 offset:32768
	ds_read_b128 v[188:191], v143 offset:33792
	ds_read_b128 v[206:209], v143 offset:34816
	ds_read_b128 v[210:213], v143 offset:35840
	ds_read_b128 v[214:217], v143 offset:36864
	ds_read_b128 v[218:221], v143 offset:37888
	ds_read_b128 v[222:225], v143 offset:38912
	ds_read_b128 v[226:229], v143 offset:39936
	global_load_lds_dwordx4 v[232:233], off
	v_lshl_add_u64 v[232:233], s[64:65], 0, v[130:131]
	s_mov_b32 m0, s59
	s_nop 0
	global_load_lds_dwordx4 v[232:233], off
	s_waitcnt vmcnt(8)
	s_waitcnt lgkmcnt(0)
	s_barrier
	s_setprio 1
	s_waitcnt lgkmcnt(0)
	v_mfma_f32_16x16x32_bf16 v[124:127], v[144:147], v[184:187], v[124:127]
	v_mfma_f32_16x16x32_bf16 v[120:123], v[160:163], v[184:187], v[120:123]
	v_mfma_f32_16x16x32_bf16 v[108:111], v[144:147], v[206:209], v[108:111]
	v_mfma_f32_16x16x32_bf16 v[104:107], v[160:163], v[206:209], v[104:107]
	v_mfma_f32_16x16x32_bf16 v[92:95], v[144:147], v[214:217], v[92:95]
	v_mfma_f32_16x16x32_bf16 v[88:91], v[160:163], v[214:217], v[88:91]
	v_mfma_f32_16x16x32_bf16 v[76:79], v[144:147], v[222:225], v[76:79]
	v_mfma_f32_16x16x32_bf16 v[72:75], v[160:163], v[222:225], v[72:75]
	v_mfma_f32_16x16x32_bf16 v[124:127], v[156:159], v[188:191], v[124:127]
	v_mfma_f32_16x16x32_bf16 v[120:123], v[164:167], v[188:191], v[120:123]
	v_mfma_f32_16x16x32_bf16 v[108:111], v[156:159], v[210:213], v[108:111]
	v_mfma_f32_16x16x32_bf16 v[104:107], v[164:167], v[210:213], v[104:107]
	v_mfma_f32_16x16x32_bf16 v[92:95], v[156:159], v[218:221], v[92:95]
	v_mfma_f32_16x16x32_bf16 v[88:91], v[164:167], v[218:221], v[88:91]
	v_mfma_f32_16x16x32_bf16 v[76:79], v[156:159], v[226:229], v[76:79]
	v_mfma_f32_16x16x32_bf16 v[72:75], v[164:167], v[226:229], v[72:75]
	v_mfma_f32_16x16x32_bf16 v[116:119], v[168:171], v[184:187], v[116:119]
	v_mfma_f32_16x16x32_bf16 v[112:115], v[176:179], v[184:187], v[112:115]
	v_mfma_f32_16x16x32_bf16 v[100:103], v[168:171], v[206:209], v[100:103]
	v_mfma_f32_16x16x32_bf16 v[96:99], v[176:179], v[206:209], v[96:99]
	v_mfma_f32_16x16x32_bf16 v[84:87], v[168:171], v[214:217], v[84:87]
	v_mfma_f32_16x16x32_bf16 v[80:83], v[176:179], v[214:217], v[80:83]
	v_mfma_f32_16x16x32_bf16 v[68:71], v[168:171], v[222:225], v[68:71]
	v_mfma_f32_16x16x32_bf16 v[64:67], v[176:179], v[222:225], v[64:67]
	v_mfma_f32_16x16x32_bf16 v[116:119], v[172:175], v[188:191], v[116:119]
	v_mfma_f32_16x16x32_bf16 v[112:115], v[180:183], v[188:191], v[112:115]
	v_mfma_f32_16x16x32_bf16 v[100:103], v[172:175], v[210:213], v[100:103]
	v_mfma_f32_16x16x32_bf16 v[96:99], v[180:183], v[210:213], v[96:99]
	v_mfma_f32_16x16x32_bf16 v[84:87], v[172:175], v[218:221], v[84:87]
	v_mfma_f32_16x16x32_bf16 v[80:83], v[180:183], v[218:221], v[80:83]
	v_mfma_f32_16x16x32_bf16 v[68:71], v[172:175], v[226:229], v[68:71]
	v_mfma_f32_16x16x32_bf16 v[64:67], v[180:183], v[226:229], v[64:67]
	s_setprio 0
	s_barrier
; #define PG8_STAGE(bufoff, gbase, voff) do { _Pragma("unroll") for (int _i = 0; _i < 2; ++_i) \
;         __builtin_amdgcn_global_load_lds((const unsigned*)((const char*)(gbase) + (voff)[_i]), (PG8_LAS unsigned*)(lds + (bufoff) + ldsw + _i * 8192), 16, 0, 0); } while (0)
; #define PG8_LDA(dst, b, h) do { _Pragma("unroll") for (int m = 0; m < 4; ++m) _Pragma("unroll") for (int k = 0; k < 2; ++k) dst[m][k] = *(const PG8_LAS bf16x8*)(lds + PG8_SA(b, h) + aoff + m * 2048 + k * 1024); } while (0)
; #define PG8_MMA(ai, bj, At, Bt) do { __builtin_amdgcn_s_setprio(1); _Pragma("unroll") for (int m = 0; m < 4; ++m) _Pragma("unroll") for (int n = 0; n < 2; ++n) _Pragma("unroll") for (int k = 0; k < 2; ++k) \
;         acc[ai][bj][m][n] = __builtin_amdgcn_mfma_f32_16x16x32_bf16(Bt[n][k], At[m][k], acc[ai][bj][m][n], 0, 0, 0); __builtin_amdgcn_s_setprio(0); } while (0)
; #define PG8_WAIT_V(n) asm volatile("s_waitcnt vmcnt(" #n ")" ::: "memory")
; #define PG8_WAIT_L(n) asm volatile("s_waitcnt lgkmcnt(" #n ")" ::: "memory")
; #define PG8_BAR __builtin_amdgcn_s_barrier()
; #define PG8_SCHED __builtin_amdgcn_sched_barrier(0)
; template <class Epi, class Sched, bool ALIGN_EPI = false, bool SP2 = false>
; __device__ __forceinline__ void gemm_phase(PG8_LAS unsigned char* lds, const Gemm g, const Sched& S, const Epi& E, int wave_s) {
;     ...
;         for (int t = 0; t < nt; t += 2) {
;             const bool last = (t == nt - 2);
;             const char* a1 = cA + (size_t)(t + 1) * kstep;
;             const char* a2 = last ? nA : cA + (size_t)(t + 2) * kstep; const char* b2 = last ? nB : cB + (size_t)(t + 2) * kstep;
;     ...
;             PG8_LDA(At, 1, 1); PG8_STAGE(PG8_SB(1, 0), b3, voffB); PG8_STAGE(PG8_SB(1, 1), b3 + hstep, voffB); PG8_STAGE(PG8_SA(1, 0), a3, voffA);
;             PG8_WAIT_V(8); PG8_WAIT_L(0); PG8_BAR; PG8_MMA(1, 0, At, B0); PG8_MMA(1, 1, At, B1); PG8_BAR; PG8_SCHED;
	s_add_i32 s36, s36, s21
	v_lshl_add_u64 v[138:139], v[138:139], 0, s[34:35]
	s_mov_b32 m0, s36
	ds_read_b128 v[184:187], v143 offset:49152
	ds_read_b128 v[188:191], v143 offset:50176
	ds_read_b128 v[206:209], v143 offset:51200
	ds_read_b128 v[210:213], v143 offset:52224
	ds_read_b128 v[214:217], v143 offset:53248
	ds_read_b128 v[218:221], v143 offset:54272
	ds_read_b128 v[222:225], v143 offset:55296
	ds_read_b128 v[226:229], v143 offset:56320
	global_load_lds_dwordx4 v[138:139], off
	s_add_i32 m0, s36, 0x2000
	s_add_u32 s62, s62, 0x20080
	v_lshl_add_u64 v[138:139], v[150:151], 0, s[34:35]
	s_addc_u32 s63, s63, 0
	s_add_i32 s36, s37, s21
	global_load_lds_dwordx4 v[138:139], off
	v_lshl_add_u64 v[138:139], s[62:63], 0, v[148:149]
	s_mov_b32 m0, s36
	s_nop 0
	global_load_lds_dwordx4 v[138:139], off
	v_lshl_add_u64 v[138:139], s[62:63], 0, v[128:129]
	s_add_i32 m0, s36, 0x2000
	s_nop 0
	global_load_lds_dwordx4 v[138:139], off
	v_lshl_add_u64 v[138:139], v[152:153], 0, s[34:35]
	s_mov_b32 m0, s66
	s_nop 0
	global_load_lds_dwordx4 v[138:139], off
	v_lshl_add_u64 v[138:139], v[230:231], 0, s[34:35]
	s_mov_b32 m0, s67
	s_nop 0
	global_load_lds_dwordx4 v[138:139], off
	s_waitcnt vmcnt(8)
	s_waitcnt lgkmcnt(0)
	s_barrier
	s_setprio 1
	s_waitcnt lgkmcnt(0)
	v_mfma_f32_16x16x32_bf16 v[60:63], v[144:147], v[184:187], v[60:63]
	v_mfma_f32_16x16x32_bf16 v[56:59], v[160:163], v[184:187], v[56:59]
	v_mfma_f32_16x16x32_bf16 v[44:47], v[144:147], v[206:209], v[44:47]
	v_mfma_f32_16x16x32_bf16 v[40:43], v[160:163], v[206:209], v[40:43]
	v_mfma_f32_16x16x32_bf16 v[28:31], v[144:147], v[214:217], v[28:31]
	v_mfma_f32_16x16x32_bf16 v[24:27], v[160:163], v[214:217], v[24:27]
	v_mfma_f32_16x16x32_bf16 v[12:15], v[144:147], v[222:225], v[12:15]
	v_mfma_f32_16x16x32_bf16 v[8:11], v[160:163], v[222:225], v[8:11]
	v_mfma_f32_16x16x32_bf16 v[60:63], v[156:159], v[188:191], v[60:63]
	v_mfma_f32_16x16x32_bf16 v[56:59], v[164:167], v[188:191], v[56:59]
	v_mfma_f32_16x16x32_bf16 v[44:47], v[156:159], v[210:213], v[44:47]
	v_mfma_f32_16x16x32_bf16 v[40:43], v[164:167], v[210:213], v[40:43]
	v_mfma_f32_16x16x32_bf16 v[28:31], v[156:159], v[218:221], v[28:31]
	v_mfma_f32_16x16x32_bf16 v[24:27], v[164:167], v[218:221], v[24:27]
	v_mfma_f32_16x16x32_bf16 v[12:15], v[156:159], v[226:229], v[12:15]
	v_mfma_f32_16x16x32_bf16 v[8:11], v[164:167], v[226:229], v[8:11]
	v_mfma_f32_16x16x32_bf16 v[52:55], v[168:171], v[184:187], v[52:55]
	v_mfma_f32_16x16x32_bf16 v[48:51], v[176:179], v[184:187], v[48:51]
	v_mfma_f32_16x16x32_bf16 v[36:39], v[168:171], v[206:209], v[36:39]
	v_mfma_f32_16x16x32_bf16 v[32:35], v[176:179], v[206:209], v[32:35]
	v_mfma_f32_16x16x32_bf16 v[20:23], v[168:171], v[214:217], v[20:23]
	v_mfma_f32_16x16x32_bf16 v[16:19], v[176:179], v[214:217], v[16:19]
	v_mfma_f32_16x16x32_bf16 v[4:7], v[168:171], v[222:225], v[4:7]
	v_mfma_f32_16x16x32_bf16 v[0:3], v[176:179], v[222:225], v[0:3]
	v_mfma_f32_16x16x32_bf16 v[52:55], v[172:175], v[188:191], v[52:55]
	v_mfma_f32_16x16x32_bf16 v[48:51], v[180:183], v[188:191], v[48:51]
	v_mfma_f32_16x16x32_bf16 v[36:39], v[172:175], v[210:213], v[36:39]
	v_mfma_f32_16x16x32_bf16 v[32:35], v[180:183], v[210:213], v[32:35]
	v_mfma_f32_16x16x32_bf16 v[20:23], v[172:175], v[218:221], v[20:23]
	v_mfma_f32_16x16x32_bf16 v[16:19], v[180:183], v[218:221], v[16:19]
	v_mfma_f32_16x16x32_bf16 v[4:7], v[172:175], v[226:229], v[4:7]
	v_mfma_f32_16x16x32_bf16 v[0:3], v[180:183], v[226:229], v[0:3]
	s_setprio 0
	s_barrier
	s_add_i32 s74, s74, 2
	s_add_u32 s60, s60, 0x100
	s_addc_u32 s61, s61, 0
	s_add_u32 s49, s49, 0x100
	s_addc_u32 s53, s53, 0
	s_cmp_gt_u32 s74, 5
	s_cbranch_scc0 .LBB0_387
	s_and_b64 vcc, exec, s[46:47]
	s_cbranch_vccz .LBB0_390
	s_barrier

; #define PG8_STAGE(bufoff, gbase, voff) do { _Pragma("unroll") for (int _i = 0; _i < 2; ++_i) \
;         __builtin_amdgcn_global_load_lds((const unsigned*)((const char*)(gbase) + (voff)[_i]), (PG8_LAS unsigned*)(lds + (bufoff) + ldsw + _i * 8192), 16, 0, 0); } while (0)
; #define PG8_LDA(dst, b, h) do { _Pragma("unroll") for (int m = 0; m < 4; ++m) _Pragma("unroll") for (int k = 0; k < 2; ++k) dst[m][k] = *(const PG8_LAS bf16x8*)(lds + PG8_SA(b, h) + aoff + m * 2048 + k * 1024); } while (0)
; #define PG8_LDB(dst, b, h) do { _Pragma("unroll") for (int n = 0; n < 2; ++n) _Pragma("unroll") for (int k = 0; k < 2; ++k) dst[n][k] = *(const PG8_LAS bf16x8*)(lds + PG8_SB(b, h) + boff + n * 2048 + k * 1024); } while (0)
; #define PG8_WAIT_V(n) asm volatile("s_waitcnt vmcnt(" #n ")" ::: "memory")
; #define PG8_WAIT_L(n) asm volatile("s_waitcnt lgkmcnt(" #n ")" ::: "memory")
; #define PG8_BAR __builtin_amdgcn_s_barrier()
; #define PG8_SCHED __builtin_amdgcn_sched_barrier(0)
; template <class Epi, class Sched, bool ALIGN_EPI = false, bool SP2 = false>
; __device__ __forceinline__ void gemm_phase(PG8_LAS unsigned char* lds, const Gemm g, const Sched& S, const Epi& E, int wave_s) {
;     ...
;         const bool has_next = S.next(ui + 1, nxt);
;         const char* nA = has_next ? (const char*)g.A + (size_t)nxt.pm * tstep : cA; const char* nB = has_next ? (const char*)g.Bt + (size_t)nxt.pn * tstep : cB;
;         for (int t = 0; t < nt; t += 2) {
;             const bool last = (t == nt - 2);
;             const char* a1 = cA + (size_t)(t + 1) * kstep;
;             const char* a2 = last ? nA : cA + (size_t)(t + 2) * kstep; const char* b2 = last ? nB : cB + (size_t)(t + 2) * kstep;
;             const char* a3 = a2 + kstep; const char* b3 = b2 + kstep;
;             if (last && has_next) S.a_ready(nxt);
;             if constexpr (SP2) {
;             PG8_LDB(B0, 0, 0); PG8_LDB(B1, 0, 1); PG8_SCHED; PG8_LDA(At, 0, 0); PG8_STAGE(PG8_SA(1, 1), a1 + hstep, voffA);
;             PG8_WAIT_V(8); PG8_WAIT_L(0); PG8_BAR; PG8_MMA(0, 0, At, B0); PG8_MMA(0, 1, At, B1); PG8_BAR; PG8_SCHED;
;             PG8_LDA(At, 0, 1); PG8_STAGE(PG8_SB(0, 0), b2, voffB); PG8_STAGE(PG8_SB(0, 1), b2 + hstep, voffB); PG8_STAGE(PG8_SA(0, 0), a2, voffA);
;             PG8_WAIT_V(8); PG8_WAIT_L(0); PG8_BAR; PG8_MMA(1, 0, At, B0); PG8_MMA(1, 1, At, B1); PG8_BAR; PG8_SCHED;
.LBB0_407:
	s_add_u32 s36, s64, s74
	s_addc_u32 s37, s65, 0
	s_add_u32 s75, s36, 0x100
	s_addc_u32 s78, s37, 0
	s_and_b64 s[22:23], s[24:25], exec
	s_cselect_b32 s23, s29, s78
	s_cselect_b32 s22, s55, s75
	s_add_u32 s74, s62, s74
	s_addc_u32 s75, s63, 0
	s_add_u32 s74, s74, 0x100
	s_addc_u32 s75, s75, 0
	s_add_i32 s81, 0, 0x10000
	s_and_b64 s[24:25], s[24:25], exec
	s_cselect_b32 s25, s53, s75
	s_cselect_b32 s24, s5, s74
	s_add_i32 s75, 0, 0x14000
	s_add_u32 s36, s36, 0x10080
	s_addc_u32 s37, s37, 0
	s_add_i32 s51, s81, s76
	s_add_i32 m0, s26, 0xc000
	s_add_i32 s61, s26, 0xe000
	s_add_i32 s3, s51, 0x2000
	v_add_u32_e32 v134, s81, v137
	s_add_u32 s78, s24, 0x10000
	ds_read_b128 v[140:143], v134
	ds_read_b128 v[144:147], v134 offset:1024
	ds_read_b128 v[156:159], v134 offset:2048
	ds_read_b128 v[160:163], v134 offset:3072
	v_add_u32_e32 v134, s75, v137
	s_addc_u32 s79, s25, 0
	s_add_i32 s7, s75, s76
	ds_read_b128 v[164:167], v134
	ds_read_b128 v[168:171], v134 offset:1024
	ds_read_b128 v[172:175], v134 offset:2048
	ds_read_b128 v[176:179], v134 offset:3072
	s_add_i32 s9, s7, 0x2000
	s_add_i32 s87, 0, 0x18000
	s_add_i32 s47, 0, 0x1c000
	s_add_u32 vcc_lo, s22, 0x10000
	s_addc_u32 vcc_hi, s23, 0
	s_add_i32 s97, s87, s76
	s_add_i32 s46, s97, 0x2000
	s_add_u32 s74, s24, 0x10080
	s_addc_u32 s75, s25, 0
	s_add_i32 s89, s47, s76
	s_add_i32 s81, s89, 0x2000
	v_lshl_add_u64 v[134:135], s[36:37], 0, v[132:133]
	ds_read_b128 v[180:183], v139
	ds_read_b128 v[184:187], v139 offset:1024
	ds_read_b128 v[188:191], v139 offset:2048
	ds_read_b128 v[206:209], v139 offset:3072
	ds_read_b128 v[210:213], v139 offset:4096
	ds_read_b128 v[214:217], v139 offset:5120
	ds_read_b128 v[218:221], v139 offset:6144
	ds_read_b128 v[222:225], v139 offset:7168
	global_load_lds_dwordx4 v[134:135], off
	v_lshl_add_u64 v[134:135], s[36:37], 0, v[130:131]
	s_mov_b32 m0, s61
	s_nop 0
	global_load_lds_dwordx4 v[134:135], off
	s_waitcnt vmcnt(8)
	s_waitcnt lgkmcnt(0)
	s_barrier
	s_setprio 1
	s_waitcnt lgkmcnt(0)
	v_mfma_f32_16x16x32_bf16 v[124:127], v[140:143], v[180:183], v[124:127]
	v_mfma_f32_16x16x32_bf16 v[120:123], v[156:159], v[180:183], v[120:123]
	v_mfma_f32_16x16x32_bf16 v[108:111], v[140:143], v[188:191], v[108:111]
	v_mfma_f32_16x16x32_bf16 v[104:107], v[156:159], v[188:191], v[104:107]
	v_mfma_f32_16x16x32_bf16 v[92:95], v[140:143], v[210:213], v[92:95]
	v_mfma_f32_16x16x32_bf16 v[88:91], v[156:159], v[210:213], v[88:91]
	v_mfma_f32_16x16x32_bf16 v[76:79], v[140:143], v[218:221], v[76:79]
	v_mfma_f32_16x16x32_bf16 v[72:75], v[156:159], v[218:221], v[72:75]
	v_mfma_f32_16x16x32_bf16 v[124:127], v[144:147], v[184:187], v[124:127]
	v_mfma_f32_16x16x32_bf16 v[120:123], v[160:163], v[184:187], v[120:123]
	v_mfma_f32_16x16x32_bf16 v[108:111], v[144:147], v[206:209], v[108:111]
	v_mfma_f32_16x16x32_bf16 v[104:107], v[160:163], v[206:209], v[104:107]
	v_mfma_f32_16x16x32_bf16 v[92:95], v[144:147], v[214:217], v[92:95]
	v_mfma_f32_16x16x32_bf16 v[88:91], v[160:163], v[214:217], v[88:91]
	v_mfma_f32_16x16x32_bf16 v[76:79], v[144:147], v[222:225], v[76:79]
	v_mfma_f32_16x16x32_bf16 v[72:75], v[160:163], v[222:225], v[72:75]
	v_mfma_f32_16x16x32_bf16 v[116:119], v[164:167], v[180:183], v[116:119]
	v_mfma_f32_16x16x32_bf16 v[112:115], v[172:175], v[180:183], v[112:115]
	v_mfma_f32_16x16x32_bf16 v[100:103], v[164:167], v[188:191], v[100:103]
	v_mfma_f32_16x16x32_bf16 v[96:99], v[172:175], v[188:191], v[96:99]
	v_mfma_f32_16x16x32_bf16 v[84:87], v[164:167], v[210:213], v[84:87]
	v_mfma_f32_16x16x32_bf16 v[80:83], v[172:175], v[210:213], v[80:83]
	v_mfma_f32_16x16x32_bf16 v[68:71], v[164:167], v[218:221], v[68:71]
	v_mfma_f32_16x16x32_bf16 v[64:67], v[172:175], v[218:221], v[64:67]
	v_mfma_f32_16x16x32_bf16 v[116:119], v[168:171], v[184:187], v[116:119]
	v_mfma_f32_16x16x32_bf16 v[112:115], v[176:179], v[184:187], v[112:115]
	v_mfma_f32_16x16x32_bf16 v[100:103], v[168:171], v[206:209], v[100:103]
	v_mfma_f32_16x16x32_bf16 v[96:99], v[176:179], v[206:209], v[96:99]
	v_mfma_f32_16x16x32_bf16 v[84:87], v[168:171], v[214:217], v[84:87]
	v_mfma_f32_16x16x32_bf16 v[80:83], v[176:179], v[214:217], v[80:83]
	v_mfma_f32_16x16x32_bf16 v[68:71], v[168:171], v[222:225], v[68:71]
	v_mfma_f32_16x16x32_bf16 v[64:67], v[176:179], v[222:225], v[64:67]
	s_setprio 0
	s_barrier
	s_mov_b32 m0, s51
	v_lshl_add_u64 v[134:135], s[24:25], 0, v[148:149]
	ds_read_b128 v[180:183], v139 offset:16384
	ds_read_b128 v[184:187], v139 offset:17408
	ds_read_b128 v[188:191], v139 offset:18432
	ds_read_b128 v[206:209], v139 offset:19456
	ds_read_b128 v[210:213], v139 offset:20480
	ds_read_b128 v[214:217], v139 offset:21504
	ds_read_b128 v[218:221], v139 offset:22528
	ds_read_b128 v[222:225], v139 offset:23552
	global_load_lds_dwordx4 v[134:135], off
	v_lshl_add_u64 v[150:151], s[24:25], 0, v[128:129]
	s_mov_b32 m0, s3
	v_lshl_add_u64 v[152:153], s[78:79], 0, v[148:149]
	global_load_lds_dwordx4 v[150:151], off
	s_mov_b32 m0, s7
	v_lshl_add_u64 v[226:227], s[22:23], 0, v[130:131]
	global_load_lds_dwordx4 v[152:153], off
	v_lshl_add_u64 v[152:153], s[78:79], 0, v[128:129]
	s_mov_b32 m0, s9
	s_nop 0
	global_load_lds_dwordx4 v[152:153], off
	v_lshl_add_u64 v[152:153], s[22:23], 0, v[132:133]
	s_mov_b32 m0, s26
	s_nop 0
	global_load_lds_dwordx4 v[152:153], off
	s_mov_b32 m0, s38
	s_nop 0
	global_load_lds_dwordx4 v[226:227], off
	s_waitcnt vmcnt(8)
	s_waitcnt lgkmcnt(0)
	s_barrier
; #define PG8_STAGE(bufoff, gbase, voff) do { _Pragma("unroll") for (int _i = 0; _i < 2; ++_i) \
;         __builtin_amdgcn_global_load_lds((const unsigned*)((const char*)(gbase) + (voff)[_i]), (PG8_LAS unsigned*)(lds + (bufoff) + ldsw + _i * 8192), 16, 0, 0); } while (0)
; #define PG8_LDA(dst, b, h) do { _Pragma("unroll") for (int m = 0; m < 4; ++m) _Pragma("unroll") for (int k = 0; k < 2; ++k) dst[m][k] = *(const PG8_LAS bf16x8*)(lds + PG8_SA(b, h) + aoff + m * 2048 + k * 1024); } while (0)
; #define PG8_LDB(dst, b, h) do { _Pragma("unroll") for (int n = 0; n < 2; ++n) _Pragma("unroll") for (int k = 0; k < 2; ++k) dst[n][k] = *(const PG8_LAS bf16x8*)(lds + PG8_SB(b, h) + boff + n * 2048 + k * 1024); } while (0)
; #define PG8_MMA(ai, bj, At, Bt) do { __builtin_amdgcn_s_setprio(1); _Pragma("unroll") for (int m = 0; m < 4; ++m) _Pragma("unroll") for (int n = 0; n < 2; ++n) _Pragma("unroll") for (int k = 0; k < 2; ++k) \
;         acc[ai][bj][m][n] = __builtin_amdgcn_mfma_f32_16x16x32_bf16(Bt[n][k], At[m][k], acc[ai][bj][m][n], 0, 0, 0); __builtin_amdgcn_s_setprio(0); } while (0)
; #define PG8_WAIT_V(n) asm volatile("s_waitcnt vmcnt(" #n ")" ::: "memory")
; #define PG8_WAIT_L(n) asm volatile("s_waitcnt lgkmcnt(" #n ")" ::: "memory")
; #define PG8_BAR __builtin_amdgcn_s_barrier()
; #define PG8_SCHED __builtin_amdgcn_sched_barrier(0)
; template <class Epi, class Sched, bool ALIGN_EPI = false, bool SP2 = false>
; __device__ __forceinline__ void gemm_phase(PG8_LAS unsigned char* lds, const Gemm g, const Sched& S, const Epi& E, int wave_s) {
;     ...
;             PG8_WAIT_V(8); PG8_WAIT_L(0); PG8_BAR; PG8_MMA(1, 0, At, B0); PG8_MMA(1, 1, At, B1); PG8_BAR; PG8_SCHED;
;             PG8_LDB(B0, 1, 0); PG8_LDB(B1, 1, 1); PG8_SCHED; PG8_LDA(At, 1, 0); PG8_STAGE(PG8_SA(0, 1), a2 + hstep, voffA);
;             PG8_WAIT_V(8); PG8_WAIT_L(0); PG8_BAR; PG8_MMA(0, 0, At, B0); PG8_MMA(0, 1, At, B1); PG8_BAR; PG8_SCHED;
	s_setprio 1
	s_waitcnt lgkmcnt(0)
	v_mfma_f32_16x16x32_bf16 v[60:63], v[140:143], v[180:183], v[60:63]
	v_mfma_f32_16x16x32_bf16 v[56:59], v[156:159], v[180:183], v[56:59]
	v_mfma_f32_16x16x32_bf16 v[44:47], v[140:143], v[188:191], v[44:47]
	v_mfma_f32_16x16x32_bf16 v[40:43], v[156:159], v[188:191], v[40:43]
	v_mfma_f32_16x16x32_bf16 v[28:31], v[140:143], v[210:213], v[28:31]
	v_mfma_f32_16x16x32_bf16 v[24:27], v[156:159], v[210:213], v[24:27]
	v_mfma_f32_16x16x32_bf16 v[12:15], v[140:143], v[218:221], v[12:15]
	v_mfma_f32_16x16x32_bf16 v[8:11], v[156:159], v[218:221], v[8:11]
	v_mfma_f32_16x16x32_bf16 v[60:63], v[144:147], v[184:187], v[60:63]
	v_mfma_f32_16x16x32_bf16 v[56:59], v[160:163], v[184:187], v[56:59]
	v_mfma_f32_16x16x32_bf16 v[44:47], v[144:147], v[206:209], v[44:47]
	v_mfma_f32_16x16x32_bf16 v[40:43], v[160:163], v[206:209], v[40:43]
	v_mfma_f32_16x16x32_bf16 v[28:31], v[144:147], v[214:217], v[28:31]
	v_mfma_f32_16x16x32_bf16 v[24:27], v[160:163], v[214:217], v[24:27]
	v_mfma_f32_16x16x32_bf16 v[12:15], v[144:147], v[222:225], v[12:15]
	v_mfma_f32_16x16x32_bf16 v[8:11], v[160:163], v[222:225], v[8:11]
	v_mfma_f32_16x16x32_bf16 v[52:55], v[164:167], v[180:183], v[52:55]
	v_mfma_f32_16x16x32_bf16 v[48:51], v[172:175], v[180:183], v[48:51]
	v_mfma_f32_16x16x32_bf16 v[36:39], v[164:167], v[188:191], v[36:39]
	v_mfma_f32_16x16x32_bf16 v[32:35], v[172:175], v[188:191], v[32:35]
	v_mfma_f32_16x16x32_bf16 v[20:23], v[164:167], v[210:213], v[20:23]
	v_mfma_f32_16x16x32_bf16 v[16:19], v[172:175], v[210:213], v[16:19]
	v_mfma_f32_16x16x32_bf16 v[4:7], v[164:167], v[218:221], v[4:7]
	v_mfma_f32_16x16x32_bf16 v[0:3], v[172:175], v[218:221], v[0:3]
	v_mfma_f32_16x16x32_bf16 v[52:55], v[168:171], v[184:187], v[52:55]
	v_mfma_f32_16x16x32_bf16 v[48:51], v[176:179], v[184:187], v[48:51]
	v_mfma_f32_16x16x32_bf16 v[36:39], v[168:171], v[206:209], v[36:39]
	v_mfma_f32_16x16x32_bf16 v[32:35], v[176:179], v[206:209], v[32:35]
	v_mfma_f32_16x16x32_bf16 v[20:23], v[168:171], v[214:217], v[20:23]
	v_mfma_f32_16x16x32_bf16 v[16:19], v[176:179], v[214:217], v[16:19]
	v_mfma_f32_16x16x32_bf16 v[4:7], v[168:171], v[222:225], v[4:7]
	v_mfma_f32_16x16x32_bf16 v[0:3], v[176:179], v[222:225], v[0:3]
	s_setprio 0
	s_barrier
	v_add_u32_e32 v160, s87, v137
	v_add_u32_e32 v176, s47, v137
	ds_read_b128 v[140:143], v160
	ds_read_b128 v[144:147], v160 offset:1024
	ds_read_b128 v[156:159], v160 offset:2048
	ds_read_b128 v[160:163], v160 offset:3072
	ds_read_b128 v[164:167], v176
	ds_read_b128 v[168:171], v176 offset:1024
	ds_read_b128 v[172:175], v176 offset:2048
	ds_read_b128 v[176:179], v176 offset:3072
	s_mov_b32 m0, s39
	v_lshl_add_u64 v[228:229], vcc, 0, v[132:133]
	ds_read_b128 v[180:183], v139 offset:32768
	ds_read_b128 v[184:187], v139 offset:33792
	ds_read_b128 v[188:191], v139 offset:34816
	ds_read_b128 v[206:209], v139 offset:35840
	ds_read_b128 v[210:213], v139 offset:36864
	ds_read_b128 v[214:217], v139 offset:37888
	ds_read_b128 v[218:221], v139 offset:38912
	ds_read_b128 v[222:225], v139 offset:39936
	global_load_lds_dwordx4 v[228:229], off
	v_lshl_add_u64 v[228:229], vcc, 0, v[130:131]
	s_mov_b32 m0, s84
	s_nop 0
	global_load_lds_dwordx4 v[228:229], off
	s_waitcnt vmcnt(8)
	s_waitcnt lgkmcnt(0)
	s_barrier
	s_setprio 1
	s_waitcnt lgkmcnt(0)
	v_mfma_f32_16x16x32_bf16 v[124:127], v[140:143], v[180:183], v[124:127]
	v_mfma_f32_16x16x32_bf16 v[120:123], v[156:159], v[180:183], v[120:123]
	v_mfma_f32_16x16x32_bf16 v[108:111], v[140:143], v[188:191], v[108:111]
	v_mfma_f32_16x16x32_bf16 v[104:107], v[156:159], v[188:191], v[104:107]
	v_mfma_f32_16x16x32_bf16 v[92:95], v[140:143], v[210:213], v[92:95]
	v_mfma_f32_16x16x32_bf16 v[88:91], v[156:159], v[210:213], v[88:91]
	v_mfma_f32_16x16x32_bf16 v[76:79], v[140:143], v[218:221], v[76:79]
	v_mfma_f32_16x16x32_bf16 v[72:75], v[156:159], v[218:221], v[72:75]
	v_mfma_f32_16x16x32_bf16 v[124:127], v[144:147], v[184:187], v[124:127]
	v_mfma_f32_16x16x32_bf16 v[120:123], v[160:163], v[184:187], v[120:123]
	v_mfma_f32_16x16x32_bf16 v[108:111], v[144:147], v[206:209], v[108:111]
	v_mfma_f32_16x16x32_bf16 v[104:107], v[160:163], v[206:209], v[104:107]
	v_mfma_f32_16x16x32_bf16 v[92:95], v[144:147], v[214:217], v[92:95]
	v_mfma_f32_16x16x32_bf16 v[88:91], v[160:163], v[214:217], v[88:91]
	v_mfma_f32_16x16x32_bf16 v[76:79], v[144:147], v[222:225], v[76:79]
	v_mfma_f32_16x16x32_bf16 v[72:75], v[160:163], v[222:225], v[72:75]
	v_mfma_f32_16x16x32_bf16 v[116:119], v[164:167], v[180:183], v[116:119]
	v_mfma_f32_16x16x32_bf16 v[112:115], v[172:175], v[180:183], v[112:115]
	v_mfma_f32_16x16x32_bf16 v[100:103], v[164:167], v[188:191], v[100:103]
	v_mfma_f32_16x16x32_bf16 v[96:99], v[172:175], v[188:191], v[96:99]
	v_mfma_f32_16x16x32_bf16 v[84:87], v[164:167], v[210:213], v[84:87]
	v_mfma_f32_16x16x32_bf16 v[80:83], v[172:175], v[210:213], v[80:83]
	v_mfma_f32_16x16x32_bf16 v[68:71], v[164:167], v[218:221], v[68:71]
	v_mfma_f32_16x16x32_bf16 v[64:67], v[172:175], v[218:221], v[64:67]
	v_mfma_f32_16x16x32_bf16 v[116:119], v[168:171], v[184:187], v[116:119]
	v_mfma_f32_16x16x32_bf16 v[112:115], v[176:179], v[184:187], v[112:115]
	v_mfma_f32_16x16x32_bf16 v[100:103], v[168:171], v[206:209], v[100:103]
	v_mfma_f32_16x16x32_bf16 v[96:99], v[176:179], v[206:209], v[96:99]
	v_mfma_f32_16x16x32_bf16 v[84:87], v[168:171], v[214:217], v[84:87]
	v_mfma_f32_16x16x32_bf16 v[80:83], v[176:179], v[214:217], v[80:83]
	v_mfma_f32_16x16x32_bf16 v[68:71], v[168:171], v[222:225], v[68:71]
	v_mfma_f32_16x16x32_bf16 v[64:67], v[176:179], v[222:225], v[64:67]
	s_setprio 0
	s_barrier
; #define PG8_STAGE(bufoff, gbase, voff) do { _Pragma("unroll") for (int _i = 0; _i < 2; ++_i) \
;         __builtin_amdgcn_global_load_lds((const unsigned*)((const char*)(gbase) + (voff)[_i]), (PG8_LAS unsigned*)(lds + (bufoff) + ldsw + _i * 8192), 16, 0, 0); } while (0)
; #define PG8_LDA(dst, b, h) do { _Pragma("unroll") for (int m = 0; m < 4; ++m) _Pragma("unroll") for (int k = 0; k < 2; ++k) dst[m][k] = *(const PG8_LAS bf16x8*)(lds + PG8_SA(b, h) + aoff + m * 2048 + k * 1024); } while (0)
; #define PG8_MMA(ai, bj, At, Bt) do { __builtin_amdgcn_s_setprio(1); _Pragma("unroll") for (int m = 0; m < 4; ++m) _Pragma("unroll") for (int n = 0; n < 2; ++n) _Pragma("unroll") for (int k = 0; k < 2; ++k) \
;         acc[ai][bj][m][n] = __builtin_amdgcn_mfma_f32_16x16x32_bf16(Bt[n][k], At[m][k], acc[ai][bj][m][n], 0, 0, 0); __builtin_amdgcn_s_setprio(0); } while (0)
; #define PG8_WAIT_V(n) asm volatile("s_waitcnt vmcnt(" #n ")" ::: "memory")
; #define PG8_WAIT_L(n) asm volatile("s_waitcnt lgkmcnt(" #n ")" ::: "memory")
; #define PG8_BAR __builtin_amdgcn_s_barrier()
; #define PG8_SCHED __builtin_amdgcn_sched_barrier(0)
; template <class Epi, class Sched, bool ALIGN_EPI = false, bool SP2 = false>
; __device__ __forceinline__ void gemm_phase(PG8_LAS unsigned char* lds, const Gemm g, const Sched& S, const Epi& E, int wave_s) {
;     ...
;         for (int t = 0; t < nt; t += 2) {
;     ...
;             PG8_LDA(At, 1, 1); PG8_STAGE(PG8_SB(1, 0), b3, voffB); PG8_STAGE(PG8_SB(1, 1), b3 + hstep, voffB); PG8_STAGE(PG8_SA(1, 0), a3, voffA);
;             PG8_WAIT_V(8); PG8_WAIT_L(0); PG8_BAR; PG8_MMA(1, 0, At, B0); PG8_MMA(1, 1, At, B1); PG8_BAR; PG8_SCHED;
	s_mov_b32 m0, s97
	v_lshl_add_u64 v[134:135], v[134:135], 0, s[34:35]
	ds_read_b128 v[180:183], v139 offset:49152
	ds_read_b128 v[184:187], v139 offset:50176
	ds_read_b128 v[188:191], v139 offset:51200
	ds_read_b128 v[206:209], v139 offset:52224
	ds_read_b128 v[210:213], v139 offset:53248
	ds_read_b128 v[214:217], v139 offset:54272
	ds_read_b128 v[218:221], v139 offset:55296
	ds_read_b128 v[222:225], v139 offset:56320
	global_load_lds_dwordx4 v[134:135], off
	v_lshl_add_u64 v[134:135], v[150:151], 0, s[34:35]
	s_mov_b32 m0, s46
	s_nop 0
	global_load_lds_dwordx4 v[134:135], off
	v_lshl_add_u64 v[134:135], s[74:75], 0, v[148:149]
	s_mov_b32 m0, s89
	s_nop 0
	global_load_lds_dwordx4 v[134:135], off
	v_lshl_add_u64 v[134:135], s[74:75], 0, v[128:129]
	s_mov_b32 m0, s81
	s_nop 0
	global_load_lds_dwordx4 v[134:135], off
	v_lshl_add_u64 v[134:135], v[152:153], 0, s[34:35]
	s_mov_b32 m0, s85
	s_nop 0
	global_load_lds_dwordx4 v[134:135], off
	v_lshl_add_u64 v[134:135], v[226:227], 0, s[34:35]
	s_mov_b32 m0, s90
	s_nop 0
	global_load_lds_dwordx4 v[134:135], off
	s_waitcnt vmcnt(8)
	s_waitcnt lgkmcnt(0)
	s_barrier
	s_setprio 1
	s_waitcnt lgkmcnt(0)
	v_mfma_f32_16x16x32_bf16 v[60:63], v[140:143], v[180:183], v[60:63]
	v_mfma_f32_16x16x32_bf16 v[56:59], v[156:159], v[180:183], v[56:59]
	v_mfma_f32_16x16x32_bf16 v[44:47], v[140:143], v[188:191], v[44:47]
	v_mfma_f32_16x16x32_bf16 v[40:43], v[156:159], v[188:191], v[40:43]
	v_mfma_f32_16x16x32_bf16 v[28:31], v[140:143], v[210:213], v[28:31]
	v_mfma_f32_16x16x32_bf16 v[24:27], v[156:159], v[210:213], v[24:27]
	v_mfma_f32_16x16x32_bf16 v[12:15], v[140:143], v[218:221], v[12:15]
	v_mfma_f32_16x16x32_bf16 v[8:11], v[156:159], v[218:221], v[8:11]
	v_mfma_f32_16x16x32_bf16 v[60:63], v[144:147], v[184:187], v[60:63]
	v_mfma_f32_16x16x32_bf16 v[56:59], v[160:163], v[184:187], v[56:59]
	v_mfma_f32_16x16x32_bf16 v[44:47], v[144:147], v[206:209], v[44:47]
	v_mfma_f32_16x16x32_bf16 v[40:43], v[160:163], v[206:209], v[40:43]
	v_mfma_f32_16x16x32_bf16 v[28:31], v[144:147], v[214:217], v[28:31]
	v_mfma_f32_16x16x32_bf16 v[24:27], v[160:163], v[214:217], v[24:27]
	v_mfma_f32_16x16x32_bf16 v[12:15], v[144:147], v[222:225], v[12:15]
	v_mfma_f32_16x16x32_bf16 v[8:11], v[160:163], v[222:225], v[8:11]
	v_mfma_f32_16x16x32_bf16 v[52:55], v[164:167], v[180:183], v[52:55]
	v_mfma_f32_16x16x32_bf16 v[48:51], v[172:175], v[180:183], v[48:51]
	v_mfma_f32_16x16x32_bf16 v[36:39], v[164:167], v[188:191], v[36:39]
	v_mfma_f32_16x16x32_bf16 v[32:35], v[172:175], v[188:191], v[32:35]
	v_mfma_f32_16x16x32_bf16 v[20:23], v[164:167], v[210:213], v[20:23]
	v_mfma_f32_16x16x32_bf16 v[16:19], v[172:175], v[210:213], v[16:19]
	v_mfma_f32_16x16x32_bf16 v[4:7], v[164:167], v[218:221], v[4:7]
	v_mfma_f32_16x16x32_bf16 v[0:3], v[172:175], v[218:221], v[0:3]
	v_mfma_f32_16x16x32_bf16 v[52:55], v[168:171], v[184:187], v[52:55]
	v_mfma_f32_16x16x32_bf16 v[48:51], v[176:179], v[184:187], v[48:51]
	v_mfma_f32_16x16x32_bf16 v[36:39], v[168:171], v[206:209], v[36:39]
	v_mfma_f32_16x16x32_bf16 v[32:35], v[176:179], v[206:209], v[32:35]
	v_mfma_f32_16x16x32_bf16 v[20:23], v[168:171], v[214:217], v[20:23]
	v_mfma_f32_16x16x32_bf16 v[16:19], v[176:179], v[214:217], v[16:19]
	v_mfma_f32_16x16x32_bf16 v[4:7], v[168:171], v[222:225], v[4:7]
	v_mfma_f32_16x16x32_bf16 v[0:3], v[176:179], v[222:225], v[0:3]
	s_setprio 0
	s_barrier
	s_movk_i32 s74, 0x100
	s_andn2_b64 vcc, exec, s[66:67]
	s_mov_b64 s[24:25], -1
	s_mov_b64 s[66:67], 0
	s_cbranch_vccz .LBB0_407
	s_and_b64 vcc, exec, s[48:49]
	v_readlane_b32 s66, v255, 8
	s_cbranch_vccz .LBB0_410
	s_barrier

; #define PG8_STAGE(bufoff, gbase, voff) do { _Pragma("unroll") for (int _i = 0; _i < 2; ++_i) \
;         __builtin_amdgcn_global_load_lds((const unsigned*)((const char*)(gbase) + (voff)[_i]), (PG8_LAS unsigned*)(lds + (bufoff) + ldsw + _i * 8192), 16, 0, 0); } while (0)
; #define PG8_LDA(dst, b, h) do { _Pragma("unroll") for (int m = 0; m < 4; ++m) _Pragma("unroll") for (int k = 0; k < 2; ++k) dst[m][k] = *(const PG8_LAS bf16x8*)(lds + PG8_SA(b, h) + aoff + m * 2048 + k * 1024); } while (0)
; #define PG8_LDB(dst, b, h) do { _Pragma("unroll") for (int n = 0; n < 2; ++n) _Pragma("unroll") for (int k = 0; k < 2; ++k) dst[n][k] = *(const PG8_LAS bf16x8*)(lds + PG8_SB(b, h) + boff + n * 2048 + k * 1024); } while (0)
; #define PG8_MMA(ai, bj, At, Bt) do { __builtin_amdgcn_s_setprio(1); _Pragma("unroll") for (int m = 0; m < 4; ++m) _Pragma("unroll") for (int n = 0; n < 2; ++n) _Pragma("unroll") for (int k = 0; k < 2; ++k) \
;         acc[ai][bj][m][n] = __builtin_amdgcn_mfma_f32_16x16x32_bf16(Bt[n][k], At[m][k], acc[ai][bj][m][n], 0, 0, 0); __builtin_amdgcn_s_setprio(0); } while (0)
; #define PG8_WAIT_V(n) asm volatile("s_waitcnt vmcnt(" #n ")" ::: "memory")
; #define PG8_WAIT_L(n) asm volatile("s_waitcnt lgkmcnt(" #n ")" ::: "memory")
; template <class Epi, class Sched, bool ALIGN_EPI = false, bool SP2 = false>
; __device__ __forceinline__ void gemm_phase(PG8_LAS unsigned char* lds, const Gemm g, const Sched& S, const Epi& E, int wave_s) {
;     ...
;             const bool last = (t == nt - 2);
;             const char* a1 = cA + (size_t)(t + 1) * kstep;
;             const char* a2 = last ? nA : cA + (size_t)(t + 2) * kstep; const char* b2 = last ? nB : cB + (size_t)(t + 2) * kstep;
;             const char* a3 = a2 + kstep; const char* b3 = b2 + kstep;
;             if (last && has_next) S.a_ready(nxt);
;             if constexpr (SP2) {
;             PG8_LDB(B0, 0, 0); PG8_LDB(B1, 0, 1); PG8_SCHED; PG8_LDA(At, 0, 0); PG8_STAGE(PG8_SA(1, 1), a1 + hstep, voffA);
;             PG8_WAIT_V(8); PG8_WAIT_L(0); PG8_BAR; PG8_MMA(0, 0, At, B0); PG8_MMA(0, 1, At, B1); PG8_BAR; PG8_SCHED;
;             PG8_LDA(At, 0, 1); PG8_STAGE(PG8_SB(0, 0), b2, voffB); PG8_STAGE(PG8_SB(0, 1), b2 + hstep, voffB); PG8_STAGE(PG8_SA(0, 0), a2, voffA);
;             PG8_WAIT_V(8); PG8_WAIT_L(0); PG8_BAR; PG8_MMA(1, 0, At, B0); PG8_MMA(1, 1, At, B1); PG8_BAR; PG8_SCHED;
.LBB0_453:
	s_add_u32 s36, s58, 0xfff80080
	s_addc_u32 s37, s59, -1
	s_add_i32 s66, 0, 0x10000
	s_cmp_eq_u32 s49, 28
	s_cselect_b32 s63, s22, s37
	s_cselect_b32 s62, s23, s36
	v_add_u32_e32 v138, s66, v141
	s_cselect_b32 s61, s5, s47
	s_cselect_b32 s60, s28, s29
	s_add_i32 s36, 0, 0x14000
	ds_read_b128 v[144:147], v138
	ds_read_b128 v[156:159], v138 offset:1024
	ds_read_b128 v[160:163], v138 offset:2048
	ds_read_b128 v[164:167], v138 offset:3072
	v_add_u32_e32 v138, s36, v141
	ds_read_b128 v[168:171], v138
	ds_read_b128 v[172:175], v138 offset:1024
	ds_read_b128 v[176:179], v138 offset:2048
	ds_read_b128 v[180:183], v138 offset:3072
	v_lshl_add_u64 v[138:139], s[58:59], 0, v[134:135]
	s_add_i32 m0, s19, 0xc000
	ds_read_b128 v[184:187], v143
	ds_read_b128 v[188:191], v143 offset:1024
	ds_read_b128 v[206:209], v143 offset:2048
	ds_read_b128 v[210:213], v143 offset:3072
	ds_read_b128 v[214:217], v143 offset:4096
	ds_read_b128 v[218:221], v143 offset:5120
	ds_read_b128 v[222:225], v143 offset:6144
	ds_read_b128 v[226:229], v143 offset:7168
	global_load_lds_dwordx4 v[138:139], off
	v_lshl_add_u64 v[138:139], s[58:59], 0, v[136:137]
	s_add_i32 m0, s19, 0xe000
	s_nop 0
	global_load_lds_dwordx4 v[138:139], off
	s_waitcnt vmcnt(8)
	s_waitcnt lgkmcnt(0)
	s_barrier
	s_setprio 1
	s_waitcnt lgkmcnt(0)
	v_mfma_f32_16x16x32_bf16 v[124:127], v[144:147], v[184:187], v[124:127]
	v_mfma_f32_16x16x32_bf16 v[120:123], v[160:163], v[184:187], v[120:123]
	v_mfma_f32_16x16x32_bf16 v[108:111], v[144:147], v[206:209], v[108:111]
	v_mfma_f32_16x16x32_bf16 v[104:107], v[160:163], v[206:209], v[104:107]
	v_mfma_f32_16x16x32_bf16 v[92:95], v[144:147], v[214:217], v[92:95]
	v_mfma_f32_16x16x32_bf16 v[88:91], v[160:163], v[214:217], v[88:91]
	v_mfma_f32_16x16x32_bf16 v[76:79], v[144:147], v[222:225], v[76:79]
	v_mfma_f32_16x16x32_bf16 v[72:75], v[160:163], v[222:225], v[72:75]
	v_mfma_f32_16x16x32_bf16 v[124:127], v[156:159], v[188:191], v[124:127]
	v_mfma_f32_16x16x32_bf16 v[120:123], v[164:167], v[188:191], v[120:123]
	v_mfma_f32_16x16x32_bf16 v[108:111], v[156:159], v[210:213], v[108:111]
	v_mfma_f32_16x16x32_bf16 v[104:107], v[164:167], v[210:213], v[104:107]
	v_mfma_f32_16x16x32_bf16 v[92:95], v[156:159], v[218:221], v[92:95]
	v_mfma_f32_16x16x32_bf16 v[88:91], v[164:167], v[218:221], v[88:91]
	v_mfma_f32_16x16x32_bf16 v[76:79], v[156:159], v[226:229], v[76:79]
	v_mfma_f32_16x16x32_bf16 v[72:75], v[164:167], v[226:229], v[72:75]
	v_mfma_f32_16x16x32_bf16 v[116:119], v[168:171], v[184:187], v[116:119]
	v_mfma_f32_16x16x32_bf16 v[112:115], v[176:179], v[184:187], v[112:115]
	v_mfma_f32_16x16x32_bf16 v[100:103], v[168:171], v[206:209], v[100:103]
	v_mfma_f32_16x16x32_bf16 v[96:99], v[176:179], v[206:209], v[96:99]
	v_mfma_f32_16x16x32_bf16 v[84:87], v[168:171], v[214:217], v[84:87]
	v_mfma_f32_16x16x32_bf16 v[80:83], v[176:179], v[214:217], v[80:83]
	v_mfma_f32_16x16x32_bf16 v[68:71], v[168:171], v[222:225], v[68:71]
	v_mfma_f32_16x16x32_bf16 v[64:67], v[176:179], v[222:225], v[64:67]
	v_mfma_f32_16x16x32_bf16 v[116:119], v[172:175], v[188:191], v[116:119]
	v_mfma_f32_16x16x32_bf16 v[112:115], v[180:183], v[188:191], v[112:115]
	v_mfma_f32_16x16x32_bf16 v[100:103], v[172:175], v[210:213], v[100:103]
	v_mfma_f32_16x16x32_bf16 v[96:99], v[180:183], v[210:213], v[96:99]
	v_mfma_f32_16x16x32_bf16 v[84:87], v[172:175], v[218:221], v[84:87]
	v_mfma_f32_16x16x32_bf16 v[80:83], v[180:183], v[218:221], v[80:83]
	v_mfma_f32_16x16x32_bf16 v[68:71], v[172:175], v[226:229], v[68:71]
	v_mfma_f32_16x16x32_bf16 v[64:67], v[180:183], v[226:229], v[64:67]
	s_setprio 0
	s_barrier
	s_add_i32 s37, s66, s18
	v_lshl_add_u64 v[138:139], s[60:61], 0, v[148:149]
	s_mov_b32 m0, s37
	ds_read_b128 v[184:187], v143 offset:16384
	ds_read_b128 v[188:191], v143 offset:17408
	ds_read_b128 v[206:209], v143 offset:18432
	ds_read_b128 v[210:213], v143 offset:19456
	ds_read_b128 v[214:217], v143 offset:20480
	ds_read_b128 v[218:221], v143 offset:21504
	ds_read_b128 v[222:225], v143 offset:22528
	ds_read_b128 v[226:229], v143 offset:23552
	global_load_lds_dwordx4 v[138:139], off
	s_add_i32 m0, s37, 0x2000
	s_add_u32 s66, s60, 0x80000
	v_lshl_add_u64 v[150:151], s[60:61], 0, v[128:129]
	s_addc_u32 s67, s61, 0
	s_add_i32 s36, s36, s18
	global_load_lds_dwordx4 v[150:151], off
	v_lshl_add_u64 v[152:153], s[66:67], 0, v[148:149]
	s_mov_b32 m0, s36
	v_lshl_add_u64 v[230:231], s[62:63], 0, v[130:131]
	global_load_lds_dwordx4 v[152:153], off
	v_lshl_add_u64 v[152:153], s[66:67], 0, v[128:129]
	s_add_i32 m0, s36, 0x2000
	s_nop 0
	global_load_lds_dwordx4 v[152:153], off
	v_lshl_add_u64 v[152:153], s[62:63], 0, v[132:133]
	s_mov_b32 m0, s19
	s_nop 0
	global_load_lds_dwordx4 v[152:153], off
	s_mov_b32 m0, s24
	s_nop 0
	global_load_lds_dwordx4 v[230:231], off
	s_waitcnt vmcnt(8)
	s_waitcnt lgkmcnt(0)
	s_barrier
; #define PG8_STAGE(bufoff, gbase, voff) do { _Pragma("unroll") for (int _i = 0; _i < 2; ++_i) \
;         __builtin_amdgcn_global_load_lds((const unsigned*)((const char*)(gbase) + (voff)[_i]), (PG8_LAS unsigned*)(lds + (bufoff) + ldsw + _i * 8192), 16, 0, 0); } while (0)
; #define PG8_LDA(dst, b, h) do { _Pragma("unroll") for (int m = 0; m < 4; ++m) _Pragma("unroll") for (int k = 0; k < 2; ++k) dst[m][k] = *(const PG8_LAS bf16x8*)(lds + PG8_SA(b, h) + aoff + m * 2048 + k * 1024); } while (0)
; #define PG8_LDB(dst, b, h) do { _Pragma("unroll") for (int n = 0; n < 2; ++n) _Pragma("unroll") for (int k = 0; k < 2; ++k) dst[n][k] = *(const PG8_LAS bf16x8*)(lds + PG8_SB(b, h) + boff + n * 2048 + k * 1024); } while (0)
; #define PG8_MMA(ai, bj, At, Bt) do { __builtin_amdgcn_s_setprio(1); _Pragma("unroll") for (int m = 0; m < 4; ++m) _Pragma("unroll") for (int n = 0; n < 2; ++n) _Pragma("unroll") for (int k = 0; k < 2; ++k) \
;         acc[ai][bj][m][n] = __builtin_amdgcn_mfma_f32_16x16x32_bf16(Bt[n][k], At[m][k], acc[ai][bj][m][n], 0, 0, 0); __builtin_amdgcn_s_setprio(0); } while (0)
; #define PG8_WAIT_V(n) asm volatile("s_waitcnt vmcnt(" #n ")" ::: "memory")
; #define PG8_WAIT_L(n) asm volatile("s_waitcnt lgkmcnt(" #n ")" ::: "memory")
; #define PG8_BAR __builtin_amdgcn_s_barrier()
; #define PG8_SCHED __builtin_amdgcn_sched_barrier(0)
; template <class Epi, class Sched, bool ALIGN_EPI = false, bool SP2 = false>
; __device__ __forceinline__ void gemm_phase(PG8_LAS unsigned char* lds, const Gemm g, const Sched& S, const Epi& E, int wave_s) {
;     ...
;             PG8_WAIT_V(8); PG8_WAIT_L(0); PG8_BAR; PG8_MMA(1, 0, At, B0); PG8_MMA(1, 1, At, B1); PG8_BAR; PG8_SCHED;
;             PG8_LDB(B0, 1, 0); PG8_LDB(B1, 1, 1); PG8_SCHED; PG8_LDA(At, 1, 0); PG8_STAGE(PG8_SA(0, 1), a2 + hstep, voffA);
;             PG8_WAIT_V(8); PG8_WAIT_L(0); PG8_BAR; PG8_MMA(0, 0, At, B0); PG8_MMA(0, 1, At, B1); PG8_BAR; PG8_SCHED;
	s_setprio 1
	s_waitcnt lgkmcnt(0)
	v_mfma_f32_16x16x32_bf16 v[60:63], v[144:147], v[184:187], v[60:63]
	v_mfma_f32_16x16x32_bf16 v[56:59], v[160:163], v[184:187], v[56:59]
	v_mfma_f32_16x16x32_bf16 v[44:47], v[144:147], v[206:209], v[44:47]
	v_mfma_f32_16x16x32_bf16 v[40:43], v[160:163], v[206:209], v[40:43]
	v_mfma_f32_16x16x32_bf16 v[28:31], v[144:147], v[214:217], v[28:31]
	v_mfma_f32_16x16x32_bf16 v[24:27], v[160:163], v[214:217], v[24:27]
	v_mfma_f32_16x16x32_bf16 v[12:15], v[144:147], v[222:225], v[12:15]
	v_mfma_f32_16x16x32_bf16 v[8:11], v[160:163], v[222:225], v[8:11]
	v_mfma_f32_16x16x32_bf16 v[60:63], v[156:159], v[188:191], v[60:63]
	v_mfma_f32_16x16x32_bf16 v[56:59], v[164:167], v[188:191], v[56:59]
	v_mfma_f32_16x16x32_bf16 v[44:47], v[156:159], v[210:213], v[44:47]
	v_mfma_f32_16x16x32_bf16 v[40:43], v[164:167], v[210:213], v[40:43]
	v_mfma_f32_16x16x32_bf16 v[28:31], v[156:159], v[218:221], v[28:31]
	v_mfma_f32_16x16x32_bf16 v[24:27], v[164:167], v[218:221], v[24:27]
	v_mfma_f32_16x16x32_bf16 v[12:15], v[156:159], v[226:229], v[12:15]
	v_mfma_f32_16x16x32_bf16 v[8:11], v[164:167], v[226:229], v[8:11]
	v_mfma_f32_16x16x32_bf16 v[52:55], v[168:171], v[184:187], v[52:55]
	v_mfma_f32_16x16x32_bf16 v[48:51], v[176:179], v[184:187], v[48:51]
	v_mfma_f32_16x16x32_bf16 v[36:39], v[168:171], v[206:209], v[36:39]
	v_mfma_f32_16x16x32_bf16 v[32:35], v[176:179], v[206:209], v[32:35]
	v_mfma_f32_16x16x32_bf16 v[20:23], v[168:171], v[214:217], v[20:23]
	v_mfma_f32_16x16x32_bf16 v[16:19], v[176:179], v[214:217], v[16:19]
	v_mfma_f32_16x16x32_bf16 v[4:7], v[168:171], v[222:225], v[4:7]
	v_mfma_f32_16x16x32_bf16 v[0:3], v[176:179], v[222:225], v[0:3]
	v_mfma_f32_16x16x32_bf16 v[52:55], v[172:175], v[188:191], v[52:55]
	v_mfma_f32_16x16x32_bf16 v[48:51], v[180:183], v[188:191], v[48:51]
	v_mfma_f32_16x16x32_bf16 v[36:39], v[172:175], v[210:213], v[36:39]
	v_mfma_f32_16x16x32_bf16 v[32:35], v[180:183], v[210:213], v[32:35]
	v_mfma_f32_16x16x32_bf16 v[20:23], v[172:175], v[218:221], v[20:23]
	v_mfma_f32_16x16x32_bf16 v[16:19], v[180:183], v[218:221], v[16:19]
	v_mfma_f32_16x16x32_bf16 v[4:7], v[172:175], v[226:229], v[4:7]
	v_mfma_f32_16x16x32_bf16 v[0:3], v[180:183], v[226:229], v[0:3]
	s_setprio 0
	s_barrier
	s_add_i32 s36, 0, 0x18000
	s_add_i32 s37, 0, 0x1c000
	v_add_u32_e32 v164, s36, v141
	v_add_u32_e32 v180, s37, v141
	ds_read_b128 v[144:147], v164
	ds_read_b128 v[156:159], v164 offset:1024
	ds_read_b128 v[160:163], v164 offset:2048
	ds_read_b128 v[164:167], v164 offset:3072
	ds_read_b128 v[168:171], v180
	ds_read_b128 v[172:175], v180 offset:1024
	ds_read_b128 v[176:179], v180 offset:2048
	ds_read_b128 v[180:183], v180 offset:3072
	s_add_u32 s62, s62, 0x80000
	s_addc_u32 s63, s63, 0
	s_mov_b32 m0, s25
	v_lshl_add_u64 v[232:233], s[62:63], 0, v[132:133]
	ds_read_b128 v[184:187], v143 offset:32768
	ds_read_b128 v[188:191], v143 offset:33792
	ds_read_b128 v[206:209], v143 offset:34816
	ds_read_b128 v[210:213], v143 offset:35840
	ds_read_b128 v[214:217], v143 offset:36864
	ds_read_b128 v[218:221], v143 offset:37888
	ds_read_b128 v[222:225], v143 offset:38912
	ds_read_b128 v[226:229], v143 offset:39936
	global_load_lds_dwordx4 v[232:233], off
	v_lshl_add_u64 v[232:233], s[62:63], 0, v[130:131]
	s_mov_b32 m0, s57
	s_nop 0
	global_load_lds_dwordx4 v[232:233], off
	s_waitcnt vmcnt(8)
	s_waitcnt lgkmcnt(0)
	s_barrier
	s_setprio 1
	s_waitcnt lgkmcnt(0)
	v_mfma_f32_16x16x32_bf16 v[124:127], v[144:147], v[184:187], v[124:127]
	v_mfma_f32_16x16x32_bf16 v[120:123], v[160:163], v[184:187], v[120:123]
	v_mfma_f32_16x16x32_bf16 v[108:111], v[144:147], v[206:209], v[108:111]
	v_mfma_f32_16x16x32_bf16 v[104:107], v[160:163], v[206:209], v[104:107]
	v_mfma_f32_16x16x32_bf16 v[92:95], v[144:147], v[214:217], v[92:95]
	v_mfma_f32_16x16x32_bf16 v[88:91], v[160:163], v[214:217], v[88:91]
	v_mfma_f32_16x16x32_bf16 v[76:79], v[144:147], v[222:225], v[76:79]
	v_mfma_f32_16x16x32_bf16 v[72:75], v[160:163], v[222:225], v[72:75]
	v_mfma_f32_16x16x32_bf16 v[124:127], v[156:159], v[188:191], v[124:127]
	v_mfma_f32_16x16x32_bf16 v[120:123], v[164:167], v[188:191], v[120:123]
	v_mfma_f32_16x16x32_bf16 v[108:111], v[156:159], v[210:213], v[108:111]
	v_mfma_f32_16x16x32_bf16 v[104:107], v[164:167], v[210:213], v[104:107]
	v_mfma_f32_16x16x32_bf16 v[92:95], v[156:159], v[218:221], v[92:95]
	v_mfma_f32_16x16x32_bf16 v[88:91], v[164:167], v[218:221], v[88:91]
	v_mfma_f32_16x16x32_bf16 v[76:79], v[156:159], v[226:229], v[76:79]
	v_mfma_f32_16x16x32_bf16 v[72:75], v[164:167], v[226:229], v[72:75]
	v_mfma_f32_16x16x32_bf16 v[116:119], v[168:171], v[184:187], v[116:119]
	v_mfma_f32_16x16x32_bf16 v[112:115], v[176:179], v[184:187], v[112:115]
	v_mfma_f32_16x16x32_bf16 v[100:103], v[168:171], v[206:209], v[100:103]
	v_mfma_f32_16x16x32_bf16 v[96:99], v[176:179], v[206:209], v[96:99]
	v_mfma_f32_16x16x32_bf16 v[84:87], v[168:171], v[214:217], v[84:87]
	v_mfma_f32_16x16x32_bf16 v[80:83], v[176:179], v[214:217], v[80:83]
	v_mfma_f32_16x16x32_bf16 v[68:71], v[168:171], v[222:225], v[68:71]
	v_mfma_f32_16x16x32_bf16 v[64:67], v[176:179], v[222:225], v[64:67]
	v_mfma_f32_16x16x32_bf16 v[116:119], v[172:175], v[188:191], v[116:119]
	v_mfma_f32_16x16x32_bf16 v[112:115], v[180:183], v[188:191], v[112:115]
	v_mfma_f32_16x16x32_bf16 v[100:103], v[172:175], v[210:213], v[100:103]
	v_mfma_f32_16x16x32_bf16 v[96:99], v[180:183], v[210:213], v[96:99]
	v_mfma_f32_16x16x32_bf16 v[84:87], v[172:175], v[218:221], v[84:87]
	v_mfma_f32_16x16x32_bf16 v[80:83], v[180:183], v[218:221], v[80:83]
	v_mfma_f32_16x16x32_bf16 v[68:71], v[172:175], v[226:229], v[68:71]
	v_mfma_f32_16x16x32_bf16 v[64:67], v[180:183], v[226:229], v[64:67]
	s_setprio 0
	s_barrier
; #define PG8_STAGE(bufoff, gbase, voff) do { _Pragma("unroll") for (int _i = 0; _i < 2; ++_i) \
;         __builtin_amdgcn_global_load_lds((const unsigned*)((const char*)(gbase) + (voff)[_i]), (PG8_LAS unsigned*)(lds + (bufoff) + ldsw + _i * 8192), 16, 0, 0); } while (0)
; #define PG8_LDA(dst, b, h) do { _Pragma("unroll") for (int m = 0; m < 4; ++m) _Pragma("unroll") for (int k = 0; k < 2; ++k) dst[m][k] = *(const PG8_LAS bf16x8*)(lds + PG8_SA(b, h) + aoff + m * 2048 + k * 1024); } while (0)
; #define PG8_MMA(ai, bj, At, Bt) do { __builtin_amdgcn_s_setprio(1); _Pragma("unroll") for (int m = 0; m < 4; ++m) _Pragma("unroll") for (int n = 0; n < 2; ++n) _Pragma("unroll") for (int k = 0; k < 2; ++k) \
;         acc[ai][bj][m][n] = __builtin_amdgcn_mfma_f32_16x16x32_bf16(Bt[n][k], At[m][k], acc[ai][bj][m][n], 0, 0, 0); __builtin_amdgcn_s_setprio(0); } while (0)
; #define PG8_WAIT_V(n) asm volatile("s_waitcnt vmcnt(" #n ")" ::: "memory")
; #define PG8_WAIT_L(n) asm volatile("s_waitcnt lgkmcnt(" #n ")" ::: "memory")
; #define PG8_BAR __builtin_amdgcn_s_barrier()
; #define PG8_SCHED __builtin_amdgcn_sched_barrier(0)
; template <class Epi, class Sched, bool ALIGN_EPI = false, bool SP2 = false>
; __device__ __forceinline__ void gemm_phase(PG8_LAS unsigned char* lds, const Gemm g, const Sched& S, const Epi& E, int wave_s) {
;     ...
;         for (int t = 0; t < nt; t += 2) {
;             const bool last = (t == nt - 2);
;             const char* a1 = cA + (size_t)(t + 1) * kstep;
;             const char* a2 = last ? nA : cA + (size_t)(t + 2) * kstep; const char* b2 = last ? nB : cB + (size_t)(t + 2) * kstep;
;     ...
;             PG8_LDA(At, 1, 1); PG8_STAGE(PG8_SB(1, 0), b3, voffB); PG8_STAGE(PG8_SB(1, 1), b3 + hstep, voffB); PG8_STAGE(PG8_SA(1, 0), a3, voffA);
;             PG8_WAIT_V(8); PG8_WAIT_L(0); PG8_BAR; PG8_MMA(1, 0, At, B0); PG8_MMA(1, 1, At, B1); PG8_BAR; PG8_SCHED;
	s_add_i32 s36, s36, s18
	v_lshl_add_u64 v[138:139], v[138:139], 0, s[34:35]
	s_mov_b32 m0, s36
	ds_read_b128 v[184:187], v143 offset:49152
	ds_read_b128 v[188:191], v143 offset:50176
	ds_read_b128 v[206:209], v143 offset:51200
	ds_read_b128 v[210:213], v143 offset:52224
	ds_read_b128 v[214:217], v143 offset:53248
	ds_read_b128 v[218:221], v143 offset:54272
	ds_read_b128 v[222:225], v143 offset:55296
	ds_read_b128 v[226:229], v143 offset:56320
	global_load_lds_dwordx4 v[138:139], off
	s_add_i32 m0, s36, 0x2000
	s_add_u32 s60, s60, 0x80080
	v_lshl_add_u64 v[138:139], v[150:151], 0, s[34:35]
	s_addc_u32 s61, s61, 0
	s_add_i32 s36, s37, s18
	global_load_lds_dwordx4 v[138:139], off
	v_lshl_add_u64 v[138:139], s[60:61], 0, v[148:149]
	s_mov_b32 m0, s36
	s_nop 0
	global_load_lds_dwordx4 v[138:139], off
	v_lshl_add_u64 v[138:139], s[60:61], 0, v[128:129]
	s_add_i32 m0, s36, 0x2000
	s_nop 0
	global_load_lds_dwordx4 v[138:139], off
	v_lshl_add_u64 v[138:139], v[152:153], 0, s[34:35]
	s_mov_b32 m0, s38
	s_nop 0
	global_load_lds_dwordx4 v[138:139], off
	v_lshl_add_u64 v[138:139], v[230:231], 0, s[34:35]
	s_mov_b32 m0, s39
	s_nop 0
	global_load_lds_dwordx4 v[138:139], off
	s_waitcnt vmcnt(8)
	s_waitcnt lgkmcnt(0)
	s_barrier
	s_setprio 1
	s_waitcnt lgkmcnt(0)
	v_mfma_f32_16x16x32_bf16 v[60:63], v[144:147], v[184:187], v[60:63]
	v_mfma_f32_16x16x32_bf16 v[56:59], v[160:163], v[184:187], v[56:59]
	v_mfma_f32_16x16x32_bf16 v[44:47], v[144:147], v[206:209], v[44:47]
	v_mfma_f32_16x16x32_bf16 v[40:43], v[160:163], v[206:209], v[40:43]
	v_mfma_f32_16x16x32_bf16 v[28:31], v[144:147], v[214:217], v[28:31]
	v_mfma_f32_16x16x32_bf16 v[24:27], v[160:163], v[214:217], v[24:27]
	v_mfma_f32_16x16x32_bf16 v[12:15], v[144:147], v[222:225], v[12:15]
	v_mfma_f32_16x16x32_bf16 v[8:11], v[160:163], v[222:225], v[8:11]
	v_mfma_f32_16x16x32_bf16 v[60:63], v[156:159], v[188:191], v[60:63]
	v_mfma_f32_16x16x32_bf16 v[56:59], v[164:167], v[188:191], v[56:59]
	v_mfma_f32_16x16x32_bf16 v[44:47], v[156:159], v[210:213], v[44:47]
	v_mfma_f32_16x16x32_bf16 v[40:43], v[164:167], v[210:213], v[40:43]
	v_mfma_f32_16x16x32_bf16 v[28:31], v[156:159], v[218:221], v[28:31]
	v_mfma_f32_16x16x32_bf16 v[24:27], v[164:167], v[218:221], v[24:27]
	v_mfma_f32_16x16x32_bf16 v[12:15], v[156:159], v[226:229], v[12:15]
	v_mfma_f32_16x16x32_bf16 v[8:11], v[164:167], v[226:229], v[8:11]
	v_mfma_f32_16x16x32_bf16 v[52:55], v[168:171], v[184:187], v[52:55]
	v_mfma_f32_16x16x32_bf16 v[48:51], v[176:179], v[184:187], v[48:51]
	v_mfma_f32_16x16x32_bf16 v[36:39], v[168:171], v[206:209], v[36:39]
	v_mfma_f32_16x16x32_bf16 v[32:35], v[176:179], v[206:209], v[32:35]
	v_mfma_f32_16x16x32_bf16 v[20:23], v[168:171], v[214:217], v[20:23]
	v_mfma_f32_16x16x32_bf16 v[16:19], v[176:179], v[214:217], v[16:19]
	v_mfma_f32_16x16x32_bf16 v[4:7], v[168:171], v[222:225], v[4:7]
	v_mfma_f32_16x16x32_bf16 v[0:3], v[176:179], v[222:225], v[0:3]
	v_mfma_f32_16x16x32_bf16 v[52:55], v[172:175], v[188:191], v[52:55]
	v_mfma_f32_16x16x32_bf16 v[48:51], v[180:183], v[188:191], v[48:51]
	v_mfma_f32_16x16x32_bf16 v[36:39], v[172:175], v[210:213], v[36:39]
	v_mfma_f32_16x16x32_bf16 v[32:35], v[180:183], v[210:213], v[32:35]
	v_mfma_f32_16x16x32_bf16 v[20:23], v[172:175], v[218:221], v[20:23]
	v_mfma_f32_16x16x32_bf16 v[16:19], v[180:183], v[218:221], v[16:19]
	v_mfma_f32_16x16x32_bf16 v[4:7], v[172:175], v[226:229], v[4:7]
	v_mfma_f32_16x16x32_bf16 v[0:3], v[180:183], v[226:229], v[0:3]
	s_setprio 0
	s_barrier
	s_add_i32 s49, s49, 2
	s_add_u32 s58, s58, 0x100
	s_addc_u32 s59, s59, 0
	s_add_u32 s29, s29, 0x100
	s_addc_u32 s47, s47, 0
	s_cmp_gt_u32 s49, 29
	s_cbranch_scc0 .LBB0_453
	s_and_b64 vcc, exec, s[44:45]
	s_cbranch_vccz .LBB0_456
	s_barrier

; #define PG8_STAGE(bufoff, gbase, voff) do { _Pragma("unroll") for (int _i = 0; _i < 2; ++_i) \
;         __builtin_amdgcn_global_load_lds((const unsigned*)((const char*)(gbase) + (voff)[_i]), (PG8_LAS unsigned*)(lds + (bufoff) + ldsw + _i * 8192), 16, 0, 0); } while (0)
; #define PG8_LDA(dst, b, h) do { _Pragma("unroll") for (int m = 0; m < 4; ++m) _Pragma("unroll") for (int k = 0; k < 2; ++k) dst[m][k] = *(const PG8_LAS bf16x8*)(lds + PG8_SA(b, h) + aoff + m * 2048 + k * 1024); } while (0)
; #define PG8_LDB(dst, b, h) do { _Pragma("unroll") for (int n = 0; n < 2; ++n) _Pragma("unroll") for (int k = 0; k < 2; ++k) dst[n][k] = *(const PG8_LAS bf16x8*)(lds + PG8_SB(b, h) + boff + n * 2048 + k * 1024); } while (0)
; #define PG8_MMA(ai, bj, At, Bt) do { __builtin_amdgcn_s_setprio(1); _Pragma("unroll") for (int m = 0; m < 4; ++m) _Pragma("unroll") for (int n = 0; n < 2; ++n) _Pragma("unroll") for (int k = 0; k < 2; ++k) \
;         acc[ai][bj][m][n] = __builtin_amdgcn_mfma_f32_16x16x32_bf16(Bt[n][k], At[m][k], acc[ai][bj][m][n], 0, 0, 0); __builtin_amdgcn_s_setprio(0); } while (0)
; #define PG8_WAIT_V(n) asm volatile("s_waitcnt vmcnt(" #n ")" ::: "memory")
; #define PG8_WAIT_L(n) asm volatile("s_waitcnt lgkmcnt(" #n ")" ::: "memory")
; template <class Epi, class Sched, bool ALIGN_EPI = false, bool SP2 = false>
; __device__ __forceinline__ void gemm_phase(PG8_LAS unsigned char* lds, const Gemm g, const Sched& S, const Epi& E, int wave_s) {
;     ...
;             const bool last = (t == nt - 2);
;             const char* a1 = cA + (size_t)(t + 1) * kstep;
;             const char* a2 = last ? nA : cA + (size_t)(t + 2) * kstep; const char* b2 = last ? nB : cB + (size_t)(t + 2) * kstep;
;             const char* a3 = a2 + kstep; const char* b3 = b2 + kstep;
;             if (last && has_next) S.a_ready(nxt);
;             if constexpr (SP2) {
;             PG8_LDB(B0, 0, 0); PG8_LDB(B1, 0, 1); PG8_SCHED; PG8_LDA(At, 0, 0); PG8_STAGE(PG8_SA(1, 1), a1 + hstep, voffA);
;             PG8_WAIT_V(8); PG8_WAIT_L(0); PG8_BAR; PG8_MMA(0, 0, At, B0); PG8_MMA(0, 1, At, B1); PG8_BAR; PG8_SCHED;
;             PG8_LDA(At, 0, 1); PG8_STAGE(PG8_SB(0, 0), b2, voffB); PG8_STAGE(PG8_SB(0, 1), b2 + hstep, voffB); PG8_STAGE(PG8_SA(0, 0), a2, voffA);
;             PG8_WAIT_V(8); PG8_WAIT_L(0); PG8_BAR; PG8_MMA(1, 0, At, B0); PG8_MMA(1, 1, At, B1); PG8_BAR; PG8_SCHED;
.LBB0_469:
	s_add_u32 s36, s60, 0xfff80080
	s_addc_u32 s37, s61, -1
	s_add_i32 s79, 0, 0x10000
	s_cmp_eq_u32 s78, 28
	s_cselect_b32 s65, s22, s37
	s_cselect_b32 s64, s23, s36
	v_add_u32_e32 v138, s79, v141
	s_cselect_b32 s63, s5, s53
	s_cselect_b32 s62, s29, s49
	s_add_i32 s36, 0, 0x14000
	ds_read_b128 v[144:147], v138
	ds_read_b128 v[156:159], v138 offset:1024
	ds_read_b128 v[160:163], v138 offset:2048
	ds_read_b128 v[164:167], v138 offset:3072
	v_add_u32_e32 v138, s36, v141
	ds_read_b128 v[168:171], v138
	ds_read_b128 v[172:175], v138 offset:1024
	ds_read_b128 v[176:179], v138 offset:2048
	ds_read_b128 v[180:183], v138 offset:3072
	v_lshl_add_u64 v[138:139], s[60:61], 0, v[134:135]
	s_add_i32 m0, s38, 0xc000
	ds_read_b128 v[184:187], v143
	ds_read_b128 v[188:191], v143 offset:1024
	ds_read_b128 v[206:209], v143 offset:2048
	ds_read_b128 v[210:213], v143 offset:3072
	ds_read_b128 v[214:217], v143 offset:4096
	ds_read_b128 v[218:221], v143 offset:5120
	ds_read_b128 v[222:225], v143 offset:6144
	ds_read_b128 v[226:229], v143 offset:7168
	global_load_lds_dwordx4 v[138:139], off
	v_lshl_add_u64 v[138:139], s[60:61], 0, v[136:137]
	s_add_i32 m0, s38, 0xe000
	s_nop 0
	global_load_lds_dwordx4 v[138:139], off
	s_waitcnt vmcnt(8)
	s_waitcnt lgkmcnt(0)
	s_barrier
	s_setprio 1
	s_waitcnt lgkmcnt(0)
	v_mfma_f32_16x16x32_bf16 v[124:127], v[144:147], v[184:187], v[124:127]
	v_mfma_f32_16x16x32_bf16 v[120:123], v[160:163], v[184:187], v[120:123]
	v_mfma_f32_16x16x32_bf16 v[108:111], v[144:147], v[206:209], v[108:111]
	v_mfma_f32_16x16x32_bf16 v[104:107], v[160:163], v[206:209], v[104:107]
	v_mfma_f32_16x16x32_bf16 v[92:95], v[144:147], v[214:217], v[92:95]
	v_mfma_f32_16x16x32_bf16 v[88:91], v[160:163], v[214:217], v[88:91]
	v_mfma_f32_16x16x32_bf16 v[76:79], v[144:147], v[222:225], v[76:79]
	v_mfma_f32_16x16x32_bf16 v[72:75], v[160:163], v[222:225], v[72:75]
	v_mfma_f32_16x16x32_bf16 v[124:127], v[156:159], v[188:191], v[124:127]
	v_mfma_f32_16x16x32_bf16 v[120:123], v[164:167], v[188:191], v[120:123]
	v_mfma_f32_16x16x32_bf16 v[108:111], v[156:159], v[210:213], v[108:111]
	v_mfma_f32_16x16x32_bf16 v[104:107], v[164:167], v[210:213], v[104:107]
	v_mfma_f32_16x16x32_bf16 v[92:95], v[156:159], v[218:221], v[92:95]
	v_mfma_f32_16x16x32_bf16 v[88:91], v[164:167], v[218:221], v[88:91]
	v_mfma_f32_16x16x32_bf16 v[76:79], v[156:159], v[226:229], v[76:79]
	v_mfma_f32_16x16x32_bf16 v[72:75], v[164:167], v[226:229], v[72:75]
	v_mfma_f32_16x16x32_bf16 v[116:119], v[168:171], v[184:187], v[116:119]
	v_mfma_f32_16x16x32_bf16 v[112:115], v[176:179], v[184:187], v[112:115]
	v_mfma_f32_16x16x32_bf16 v[100:103], v[168:171], v[206:209], v[100:103]
	v_mfma_f32_16x16x32_bf16 v[96:99], v[176:179], v[206:209], v[96:99]
	v_mfma_f32_16x16x32_bf16 v[84:87], v[168:171], v[214:217], v[84:87]
	v_mfma_f32_16x16x32_bf16 v[80:83], v[176:179], v[214:217], v[80:83]
	v_mfma_f32_16x16x32_bf16 v[68:71], v[168:171], v[222:225], v[68:71]
	v_mfma_f32_16x16x32_bf16 v[64:67], v[176:179], v[222:225], v[64:67]
	v_mfma_f32_16x16x32_bf16 v[116:119], v[172:175], v[188:191], v[116:119]
	v_mfma_f32_16x16x32_bf16 v[112:115], v[180:183], v[188:191], v[112:115]
	v_mfma_f32_16x16x32_bf16 v[100:103], v[172:175], v[210:213], v[100:103]
	v_mfma_f32_16x16x32_bf16 v[96:99], v[180:183], v[210:213], v[96:99]
	v_mfma_f32_16x16x32_bf16 v[84:87], v[172:175], v[218:221], v[84:87]
	v_mfma_f32_16x16x32_bf16 v[80:83], v[180:183], v[218:221], v[80:83]
	v_mfma_f32_16x16x32_bf16 v[68:71], v[172:175], v[226:229], v[68:71]
	v_mfma_f32_16x16x32_bf16 v[64:67], v[180:183], v[226:229], v[64:67]
	s_setprio 0
	s_barrier
	s_add_i32 s37, s79, s25
	v_lshl_add_u64 v[138:139], s[62:63], 0, v[148:149]
	s_mov_b32 m0, s37
	ds_read_b128 v[184:187], v143 offset:16384
	ds_read_b128 v[188:191], v143 offset:17408
	ds_read_b128 v[206:209], v143 offset:18432
	ds_read_b128 v[210:213], v143 offset:19456
	ds_read_b128 v[214:217], v143 offset:20480
	ds_read_b128 v[218:221], v143 offset:21504
	ds_read_b128 v[222:225], v143 offset:22528
	ds_read_b128 v[226:229], v143 offset:23552
	global_load_lds_dwordx4 v[138:139], off
	s_add_i32 m0, s37, 0x2000
	s_add_u32 s84, s62, 0x80000
	v_lshl_add_u64 v[150:151], s[62:63], 0, v[128:129]
	s_addc_u32 s85, s63, 0
	s_add_i32 s36, s36, s25
	global_load_lds_dwordx4 v[150:151], off
	v_lshl_add_u64 v[152:153], s[84:85], 0, v[148:149]
	s_mov_b32 m0, s36
	v_lshl_add_u64 v[230:231], s[64:65], 0, v[130:131]
	global_load_lds_dwordx4 v[152:153], off
	v_lshl_add_u64 v[152:153], s[84:85], 0, v[128:129]
	s_add_i32 m0, s36, 0x2000
	s_nop 0
	global_load_lds_dwordx4 v[152:153], off
	v_lshl_add_u64 v[152:153], s[64:65], 0, v[132:133]
	s_mov_b32 m0, s38
	s_nop 0
	global_load_lds_dwordx4 v[152:153], off
	s_mov_b32 m0, s39
	s_nop 0
	global_load_lds_dwordx4 v[230:231], off
	s_waitcnt vmcnt(8)
	s_waitcnt lgkmcnt(0)
	s_barrier
; #define PG8_STAGE(bufoff, gbase, voff) do { _Pragma("unroll") for (int _i = 0; _i < 2; ++_i) \
;         __builtin_amdgcn_global_load_lds((const unsigned*)((const char*)(gbase) + (voff)[_i]), (PG8_LAS unsigned*)(lds + (bufoff) + ldsw + _i * 8192), 16, 0, 0); } while (0)
; #define PG8_LDA(dst, b, h) do { _Pragma("unroll") for (int m = 0; m < 4; ++m) _Pragma("unroll") for (int k = 0; k < 2; ++k) dst[m][k] = *(const PG8_LAS bf16x8*)(lds + PG8_SA(b, h) + aoff + m * 2048 + k * 1024); } while (0)
; #define PG8_LDB(dst, b, h) do { _Pragma("unroll") for (int n = 0; n < 2; ++n) _Pragma("unroll") for (int k = 0; k < 2; ++k) dst[n][k] = *(const PG8_LAS bf16x8*)(lds + PG8_SB(b, h) + boff + n * 2048 + k * 1024); } while (0)
; #define PG8_MMA(ai, bj, At, Bt) do { __builtin_amdgcn_s_setprio(1); _Pragma("unroll") for (int m = 0; m < 4; ++m) _Pragma("unroll") for (int n = 0; n < 2; ++n) _Pragma("unroll") for (int k = 0; k < 2; ++k) \
;         acc[ai][bj][m][n] = __builtin_amdgcn_mfma_f32_16x16x32_bf16(Bt[n][k], At[m][k], acc[ai][bj][m][n], 0, 0, 0); __builtin_amdgcn_s_setprio(0); } while (0)
; #define PG8_WAIT_V(n) asm volatile("s_waitcnt vmcnt(" #n ")" ::: "memory")
; #define PG8_WAIT_L(n) asm volatile("s_waitcnt lgkmcnt(" #n ")" ::: "memory")
; #define PG8_BAR __builtin_amdgcn_s_barrier()
; #define PG8_SCHED __builtin_amdgcn_sched_barrier(0)
; template <class Epi, class Sched, bool ALIGN_EPI = false, bool SP2 = false>
; __device__ __forceinline__ void gemm_phase(PG8_LAS unsigned char* lds, const Gemm g, const Sched& S, const Epi& E, int wave_s) {
;     ...
;             PG8_WAIT_V(8); PG8_WAIT_L(0); PG8_BAR; PG8_MMA(1, 0, At, B0); PG8_MMA(1, 1, At, B1); PG8_BAR; PG8_SCHED;
;             PG8_LDB(B0, 1, 0); PG8_LDB(B1, 1, 1); PG8_SCHED; PG8_LDA(At, 1, 0); PG8_STAGE(PG8_SA(0, 1), a2 + hstep, voffA);
;             PG8_WAIT_V(8); PG8_WAIT_L(0); PG8_BAR; PG8_MMA(0, 0, At, B0); PG8_MMA(0, 1, At, B1); PG8_BAR; PG8_SCHED;
	s_setprio 1
	s_waitcnt lgkmcnt(0)
	v_mfma_f32_16x16x32_bf16 v[60:63], v[144:147], v[184:187], v[60:63]
	v_mfma_f32_16x16x32_bf16 v[56:59], v[160:163], v[184:187], v[56:59]
	v_mfma_f32_16x16x32_bf16 v[44:47], v[144:147], v[206:209], v[44:47]
	v_mfma_f32_16x16x32_bf16 v[40:43], v[160:163], v[206:209], v[40:43]
	v_mfma_f32_16x16x32_bf16 v[28:31], v[144:147], v[214:217], v[28:31]
	v_mfma_f32_16x16x32_bf16 v[24:27], v[160:163], v[214:217], v[24:27]
	v_mfma_f32_16x16x32_bf16 v[12:15], v[144:147], v[222:225], v[12:15]
	v_mfma_f32_16x16x32_bf16 v[8:11], v[160:163], v[222:225], v[8:11]
	v_mfma_f32_16x16x32_bf16 v[60:63], v[156:159], v[188:191], v[60:63]
	v_mfma_f32_16x16x32_bf16 v[56:59], v[164:167], v[188:191], v[56:59]
	v_mfma_f32_16x16x32_bf16 v[44:47], v[156:159], v[210:213], v[44:47]
	v_mfma_f32_16x16x32_bf16 v[40:43], v[164:167], v[210:213], v[40:43]
	v_mfma_f32_16x16x32_bf16 v[28:31], v[156:159], v[218:221], v[28:31]
	v_mfma_f32_16x16x32_bf16 v[24:27], v[164:167], v[218:221], v[24:27]
	v_mfma_f32_16x16x32_bf16 v[12:15], v[156:159], v[226:229], v[12:15]
	v_mfma_f32_16x16x32_bf16 v[8:11], v[164:167], v[226:229], v[8:11]
	v_mfma_f32_16x16x32_bf16 v[52:55], v[168:171], v[184:187], v[52:55]
	v_mfma_f32_16x16x32_bf16 v[48:51], v[176:179], v[184:187], v[48:51]
	v_mfma_f32_16x16x32_bf16 v[36:39], v[168:171], v[206:209], v[36:39]
	v_mfma_f32_16x16x32_bf16 v[32:35], v[176:179], v[206:209], v[32:35]
	v_mfma_f32_16x16x32_bf16 v[20:23], v[168:171], v[214:217], v[20:23]
	v_mfma_f32_16x16x32_bf16 v[16:19], v[176:179], v[214:217], v[16:19]
	v_mfma_f32_16x16x32_bf16 v[4:7], v[168:171], v[222:225], v[4:7]
	v_mfma_f32_16x16x32_bf16 v[0:3], v[176:179], v[222:225], v[0:3]
	v_mfma_f32_16x16x32_bf16 v[52:55], v[172:175], v[188:191], v[52:55]
	v_mfma_f32_16x16x32_bf16 v[48:51], v[180:183], v[188:191], v[48:51]
	v_mfma_f32_16x16x32_bf16 v[36:39], v[172:175], v[210:213], v[36:39]
	v_mfma_f32_16x16x32_bf16 v[32:35], v[180:183], v[210:213], v[32:35]
	v_mfma_f32_16x16x32_bf16 v[20:23], v[172:175], v[218:221], v[20:23]
	v_mfma_f32_16x16x32_bf16 v[16:19], v[180:183], v[218:221], v[16:19]
	v_mfma_f32_16x16x32_bf16 v[4:7], v[172:175], v[226:229], v[4:7]
	v_mfma_f32_16x16x32_bf16 v[0:3], v[180:183], v[226:229], v[0:3]
	s_setprio 0
	s_barrier
	s_add_i32 s36, 0, 0x18000
	s_add_i32 s37, 0, 0x1c000
	v_add_u32_e32 v164, s36, v141
	v_add_u32_e32 v180, s37, v141
	ds_read_b128 v[144:147], v164
	ds_read_b128 v[156:159], v164 offset:1024
	ds_read_b128 v[160:163], v164 offset:2048
	ds_read_b128 v[164:167], v164 offset:3072
	ds_read_b128 v[168:171], v180
	ds_read_b128 v[172:175], v180 offset:1024
	ds_read_b128 v[176:179], v180 offset:2048
	ds_read_b128 v[180:183], v180 offset:3072
	s_add_u32 s64, s64, 0x80000
	s_addc_u32 s65, s65, 0
	s_mov_b32 m0, s59
	v_lshl_add_u64 v[232:233], s[64:65], 0, v[132:133]
	ds_read_b128 v[184:187], v143 offset:32768
	ds_read_b128 v[188:191], v143 offset:33792
	ds_read_b128 v[206:209], v143 offset:34816
	ds_read_b128 v[210:213], v143 offset:35840
	ds_read_b128 v[214:217], v143 offset:36864
	ds_read_b128 v[218:221], v143 offset:37888
	ds_read_b128 v[222:225], v143 offset:38912
	ds_read_b128 v[226:229], v143 offset:39936
	global_load_lds_dwordx4 v[232:233], off
	v_lshl_add_u64 v[232:233], s[64:65], 0, v[130:131]
	s_mov_b32 m0, s67
	s_nop 0
	global_load_lds_dwordx4 v[232:233], off
	s_waitcnt vmcnt(8)
	s_waitcnt lgkmcnt(0)
	s_barrier
	s_setprio 1
	s_waitcnt lgkmcnt(0)
	v_mfma_f32_16x16x32_bf16 v[124:127], v[144:147], v[184:187], v[124:127]
	v_mfma_f32_16x16x32_bf16 v[120:123], v[160:163], v[184:187], v[120:123]
	v_mfma_f32_16x16x32_bf16 v[108:111], v[144:147], v[206:209], v[108:111]
	v_mfma_f32_16x16x32_bf16 v[104:107], v[160:163], v[206:209], v[104:107]
	v_mfma_f32_16x16x32_bf16 v[92:95], v[144:147], v[214:217], v[92:95]
	v_mfma_f32_16x16x32_bf16 v[88:91], v[160:163], v[214:217], v[88:91]
	v_mfma_f32_16x16x32_bf16 v[76:79], v[144:147], v[222:225], v[76:79]
	v_mfma_f32_16x16x32_bf16 v[72:75], v[160:163], v[222:225], v[72:75]
	v_mfma_f32_16x16x32_bf16 v[124:127], v[156:159], v[188:191], v[124:127]
	v_mfma_f32_16x16x32_bf16 v[120:123], v[164:167], v[188:191], v[120:123]
	v_mfma_f32_16x16x32_bf16 v[108:111], v[156:159], v[210:213], v[108:111]
	v_mfma_f32_16x16x32_bf16 v[104:107], v[164:167], v[210:213], v[104:107]
	v_mfma_f32_16x16x32_bf16 v[92:95], v[156:159], v[218:221], v[92:95]
	v_mfma_f32_16x16x32_bf16 v[88:91], v[164:167], v[218:221], v[88:91]
	v_mfma_f32_16x16x32_bf16 v[76:79], v[156:159], v[226:229], v[76:79]
	v_mfma_f32_16x16x32_bf16 v[72:75], v[164:167], v[226:229], v[72:75]
	v_mfma_f32_16x16x32_bf16 v[116:119], v[168:171], v[184:187], v[116:119]
	v_mfma_f32_16x16x32_bf16 v[112:115], v[176:179], v[184:187], v[112:115]
	v_mfma_f32_16x16x32_bf16 v[100:103], v[168:171], v[206:209], v[100:103]
	v_mfma_f32_16x16x32_bf16 v[96:99], v[176:179], v[206:209], v[96:99]
	v_mfma_f32_16x16x32_bf16 v[84:87], v[168:171], v[214:217], v[84:87]
	v_mfma_f32_16x16x32_bf16 v[80:83], v[176:179], v[214:217], v[80:83]
	v_mfma_f32_16x16x32_bf16 v[68:71], v[168:171], v[222:225], v[68:71]
	v_mfma_f32_16x16x32_bf16 v[64:67], v[176:179], v[222:225], v[64:67]
	v_mfma_f32_16x16x32_bf16 v[116:119], v[172:175], v[188:191], v[116:119]
	v_mfma_f32_16x16x32_bf16 v[112:115], v[180:183], v[188:191], v[112:115]
	v_mfma_f32_16x16x32_bf16 v[100:103], v[172:175], v[210:213], v[100:103]
	v_mfma_f32_16x16x32_bf16 v[96:99], v[180:183], v[210:213], v[96:99]
	v_mfma_f32_16x16x32_bf16 v[84:87], v[172:175], v[218:221], v[84:87]
	v_mfma_f32_16x16x32_bf16 v[80:83], v[180:183], v[218:221], v[80:83]
	v_mfma_f32_16x16x32_bf16 v[68:71], v[172:175], v[226:229], v[68:71]
	v_mfma_f32_16x16x32_bf16 v[64:67], v[180:183], v[226:229], v[64:67]
	s_setprio 0
	s_barrier
; #define PG8_STAGE(bufoff, gbase, voff) do { _Pragma("unroll") for (int _i = 0; _i < 2; ++_i) \
;         __builtin_amdgcn_global_load_lds((const unsigned*)((const char*)(gbase) + (voff)[_i]), (PG8_LAS unsigned*)(lds + (bufoff) + ldsw + _i * 8192), 16, 0, 0); } while (0)
; #define PG8_LDA(dst, b, h) do { _Pragma("unroll") for (int m = 0; m < 4; ++m) _Pragma("unroll") for (int k = 0; k < 2; ++k) dst[m][k] = *(const PG8_LAS bf16x8*)(lds + PG8_SA(b, h) + aoff + m * 2048 + k * 1024); } while (0)
; #define PG8_MMA(ai, bj, At, Bt) do { __builtin_amdgcn_s_setprio(1); _Pragma("unroll") for (int m = 0; m < 4; ++m) _Pragma("unroll") for (int n = 0; n < 2; ++n) _Pragma("unroll") for (int k = 0; k < 2; ++k) \
;         acc[ai][bj][m][n] = __builtin_amdgcn_mfma_f32_16x16x32_bf16(Bt[n][k], At[m][k], acc[ai][bj][m][n], 0, 0, 0); __builtin_amdgcn_s_setprio(0); } while (0)
; #define PG8_WAIT_V(n) asm volatile("s_waitcnt vmcnt(" #n ")" ::: "memory")
; #define PG8_WAIT_L(n) asm volatile("s_waitcnt lgkmcnt(" #n ")" ::: "memory")
; #define PG8_BAR __builtin_amdgcn_s_barrier()
; #define PG8_SCHED __builtin_amdgcn_sched_barrier(0)
; template <class Epi, class Sched, bool ALIGN_EPI = false, bool SP2 = false>
; __device__ __forceinline__ void gemm_phase(PG8_LAS unsigned char* lds, const Gemm g, const Sched& S, const Epi& E, int wave_s) {
;     ...
;         for (int t = 0; t < nt; t += 2) {
;             const bool last = (t == nt - 2);
;             const char* a1 = cA + (size_t)(t + 1) * kstep;
;             const char* a2 = last ? nA : cA + (size_t)(t + 2) * kstep; const char* b2 = last ? nB : cB + (size_t)(t + 2) * kstep;
;     ...
;             PG8_LDA(At, 1, 1); PG8_STAGE(PG8_SB(1, 0), b3, voffB); PG8_STAGE(PG8_SB(1, 1), b3 + hstep, voffB); PG8_STAGE(PG8_SA(1, 0), a3, voffA);
;             PG8_WAIT_V(8); PG8_WAIT_L(0); PG8_BAR; PG8_MMA(1, 0, At, B0); PG8_MMA(1, 1, At, B1); PG8_BAR; PG8_SCHED;
	s_add_i32 s36, s36, s25
	v_lshl_add_u64 v[138:139], v[138:139], 0, s[34:35]
	s_mov_b32 m0, s36
	ds_read_b128 v[184:187], v143 offset:49152
	ds_read_b128 v[188:191], v143 offset:50176
	ds_read_b128 v[206:209], v143 offset:51200
	ds_read_b128 v[210:213], v143 offset:52224
	ds_read_b128 v[214:217], v143 offset:53248
	ds_read_b128 v[218:221], v143 offset:54272
	ds_read_b128 v[222:225], v143 offset:55296
	ds_read_b128 v[226:229], v143 offset:56320
	global_load_lds_dwordx4 v[138:139], off
	s_add_i32 m0, s36, 0x2000
	s_add_u32 s62, s62, 0x80080
	v_lshl_add_u64 v[138:139], v[150:151], 0, s[34:35]
	s_addc_u32 s63, s63, 0
	s_add_i32 s36, s37, s25
	global_load_lds_dwordx4 v[138:139], off
	v_lshl_add_u64 v[138:139], s[62:63], 0, v[148:149]
	s_mov_b32 m0, s36
	s_nop 0
	global_load_lds_dwordx4 v[138:139], off
	v_lshl_add_u64 v[138:139], s[62:63], 0, v[128:129]
	s_add_i32 m0, s36, 0x2000
	s_nop 0
	global_load_lds_dwordx4 v[138:139], off
	v_lshl_add_u64 v[138:139], v[152:153], 0, s[34:35]
	s_mov_b32 m0, s75
	s_nop 0
	global_load_lds_dwordx4 v[138:139], off
	v_lshl_add_u64 v[138:139], v[230:231], 0, s[34:35]
	s_mov_b32 m0, s76
	s_nop 0
	global_load_lds_dwordx4 v[138:139], off
	s_waitcnt vmcnt(8)
	s_waitcnt lgkmcnt(0)
	s_barrier
	s_setprio 1
	s_waitcnt lgkmcnt(0)
	v_mfma_f32_16x16x32_bf16 v[60:63], v[144:147], v[184:187], v[60:63]
	v_mfma_f32_16x16x32_bf16 v[56:59], v[160:163], v[184:187], v[56:59]
	v_mfma_f32_16x16x32_bf16 v[44:47], v[144:147], v[206:209], v[44:47]
	v_mfma_f32_16x16x32_bf16 v[40:43], v[160:163], v[206:209], v[40:43]
	v_mfma_f32_16x16x32_bf16 v[28:31], v[144:147], v[214:217], v[28:31]
	v_mfma_f32_16x16x32_bf16 v[24:27], v[160:163], v[214:217], v[24:27]
	v_mfma_f32_16x16x32_bf16 v[12:15], v[144:147], v[222:225], v[12:15]
	v_mfma_f32_16x16x32_bf16 v[8:11], v[160:163], v[222:225], v[8:11]
	v_mfma_f32_16x16x32_bf16 v[60:63], v[156:159], v[188:191], v[60:63]
	v_mfma_f32_16x16x32_bf16 v[56:59], v[164:167], v[188:191], v[56:59]
	v_mfma_f32_16x16x32_bf16 v[44:47], v[156:159], v[210:213], v[44:47]
	v_mfma_f32_16x16x32_bf16 v[40:43], v[164:167], v[210:213], v[40:43]
	v_mfma_f32_16x16x32_bf16 v[28:31], v[156:159], v[218:221], v[28:31]
	v_mfma_f32_16x16x32_bf16 v[24:27], v[164:167], v[218:221], v[24:27]
	v_mfma_f32_16x16x32_bf16 v[12:15], v[156:159], v[226:229], v[12:15]
	v_mfma_f32_16x16x32_bf16 v[8:11], v[164:167], v[226:229], v[8:11]
	v_mfma_f32_16x16x32_bf16 v[52:55], v[168:171], v[184:187], v[52:55]
	v_mfma_f32_16x16x32_bf16 v[48:51], v[176:179], v[184:187], v[48:51]
	v_mfma_f32_16x16x32_bf16 v[36:39], v[168:171], v[206:209], v[36:39]
	v_mfma_f32_16x16x32_bf16 v[32:35], v[176:179], v[206:209], v[32:35]
	v_mfma_f32_16x16x32_bf16 v[20:23], v[168:171], v[214:217], v[20:23]
	v_mfma_f32_16x16x32_bf16 v[16:19], v[176:179], v[214:217], v[16:19]
	v_mfma_f32_16x16x32_bf16 v[4:7], v[168:171], v[222:225], v[4:7]
	v_mfma_f32_16x16x32_bf16 v[0:3], v[176:179], v[222:225], v[0:3]
	v_mfma_f32_16x16x32_bf16 v[52:55], v[172:175], v[188:191], v[52:55]
	v_mfma_f32_16x16x32_bf16 v[48:51], v[180:183], v[188:191], v[48:51]
	v_mfma_f32_16x16x32_bf16 v[36:39], v[172:175], v[210:213], v[36:39]
	v_mfma_f32_16x16x32_bf16 v[32:35], v[180:183], v[210:213], v[32:35]
	v_mfma_f32_16x16x32_bf16 v[20:23], v[172:175], v[218:221], v[20:23]
	v_mfma_f32_16x16x32_bf16 v[16:19], v[180:183], v[218:221], v[16:19]
	v_mfma_f32_16x16x32_bf16 v[4:7], v[172:175], v[226:229], v[4:7]
	v_mfma_f32_16x16x32_bf16 v[0:3], v[180:183], v[226:229], v[0:3]
	s_setprio 0
	s_barrier
	s_add_i32 s78, s78, 2
	s_add_u32 s60, s60, 0x100
	s_addc_u32 s61, s61, 0
	s_add_u32 s49, s49, 0x100
	s_addc_u32 s53, s53, 0
	s_cmp_gt_u32 s78, 29
	s_cbranch_scc0 .LBB0_469
	s_and_b64 vcc, exec, s[46:47]
	s_cbranch_vccz .LBB0_472
	s_barrier

; #define PG8_STAGE(bufoff, gbase, voff) do { _Pragma("unroll") for (int _i = 0; _i < 2; ++_i) \
;         __builtin_amdgcn_global_load_lds((const unsigned*)((const char*)(gbase) + (voff)[_i]), (PG8_LAS unsigned*)(lds + (bufoff) + ldsw + _i * 8192), 16, 0, 0); } while (0)
; #define PG8_LDA(dst, b, h) do { _Pragma("unroll") for (int m = 0; m < 4; ++m) _Pragma("unroll") for (int k = 0; k < 2; ++k) dst[m][k] = *(const PG8_LAS bf16x8*)(lds + PG8_SA(b, h) + aoff + m * 2048 + k * 1024); } while (0)
; #define PG8_LDB(dst, b, h) do { _Pragma("unroll") for (int n = 0; n < 2; ++n) _Pragma("unroll") for (int k = 0; k < 2; ++k) dst[n][k] = *(const PG8_LAS bf16x8*)(lds + PG8_SB(b, h) + boff + n * 2048 + k * 1024); } while (0)
; #define PG8_MMA(ai, bj, At, Bt) do { __builtin_amdgcn_s_setprio(1); _Pragma("unroll") for (int m = 0; m < 4; ++m) _Pragma("unroll") for (int n = 0; n < 2; ++n) _Pragma("unroll") for (int k = 0; k < 2; ++k) \
;         acc[ai][bj][m][n] = __builtin_amdgcn_mfma_f32_16x16x32_bf16(Bt[n][k], At[m][k], acc[ai][bj][m][n], 0, 0, 0); __builtin_amdgcn_s_setprio(0); } while (0)
; #define PG8_WAIT_V(n) asm volatile("s_waitcnt vmcnt(" #n ")" ::: "memory")
; #define PG8_WAIT_L(n) asm volatile("s_waitcnt lgkmcnt(" #n ")" ::: "memory")
; #define PG8_BAR __builtin_amdgcn_s_barrier()
; #define PG8_SCHED __builtin_amdgcn_sched_barrier(0)
; template <class Epi, class Sched, bool ALIGN_EPI = false, bool SP2 = false>
; __device__ __forceinline__ void gemm_phase(PG8_LAS unsigned char* lds, const Gemm g, const Sched& S, const Epi& E, int wave_s) {
;     ...
;         const bool has_next = S.next(ui + 1, nxt);
;         const char* nA = has_next ? (const char*)g.A + (size_t)nxt.pm * tstep : cA; const char* nB = has_next ? (const char*)g.Bt + (size_t)nxt.pn * tstep : cB;
;     ...
;             PG8_LDB(B0, 0, 0); PG8_LDB(B1, 0, 1); PG8_SCHED; PG8_LDA(At, 0, 0); PG8_STAGE(PG8_SA(1, 1), a1 + hstep, voffA);
;             PG8_WAIT_V(8); PG8_WAIT_L(0); PG8_BAR; PG8_MMA(0, 0, At, B0); PG8_MMA(0, 1, At, B1); PG8_BAR; PG8_SCHED;
.LBB0_488:
	s_ashr_i32 s57, s56, 31
	s_lshl_b64 s[22:23], s[56:57], 17
	s_add_u32 s58, s9, s22
	s_addc_u32 s59, s11, s23
	s_and_b64 s[22:23], s[40:41], exec
	s_cselect_b32 vcc_hi, s59, s65
	s_cselect_b32 vcc_lo, s58, s64
	s_ashr_i32 s55, s54, 31
	s_lshl_b64 s[22:23], s[54:55], 17
	s_add_u32 s60, s24, s22
	s_addc_u32 s61, s25, s23
	s_and_b64 s[22:23], s[40:41], exec
	s_cselect_b32 s75, s61, s67
	s_cselect_b32 s74, s60, s66
	s_add_i32 s29, 0, 0x10000
	s_add_i32 s28, 0, 0x14000
	v_add_u32_e32 v205, s29, v135
	v_add_u32_e32 v226, s28, v135
	ds_read_b128 v[4:7], v205
	ds_read_b128 v[8:11], v205 offset:1024
	ds_read_b128 v[12:15], v205 offset:2048
	ds_read_b128 v[16:19], v205 offset:3072
	ds_read_b128 v[20:23], v226
	ds_read_b128 v[24:27], v226 offset:1024
	ds_read_b128 v[28:31], v226 offset:2048
	ds_read_b128 v[32:35], v226 offset:3072
	v_mov_b32_e32 v1, v0
	v_mov_b32_e32 v2, v0
	v_mov_b32_e32 v3, v0
	s_add_u32 s22, s64, 0x10080
	s_addc_u32 s23, s65, 0
	s_add_i32 s55, s19, 0xc000
	v_lshl_add_u64 v[68:69], s[22:23], 0, v[148:149]
	s_mov_b32 m0, s55
	s_add_i32 s5, s19, 0xe000
	ds_read_b128 v[36:39], v137
	ds_read_b128 v[40:43], v137 offset:1024
	ds_read_b128 v[44:47], v137 offset:2048
	ds_read_b128 v[48:51], v137 offset:3072
	ds_read_b128 v[52:55], v137 offset:4096
	ds_read_b128 v[56:59], v137 offset:5120
	ds_read_b128 v[60:63], v137 offset:6144
	ds_read_b128 v[64:67], v137 offset:7168
	global_load_lds_dwordx4 v[68:69], off
	v_lshl_add_u64 v[68:69], s[22:23], 0, v[128:129]
	s_mov_b32 m0, s5
	s_nop 0
	global_load_lds_dwordx4 v[68:69], off
	s_waitcnt vmcnt(8)
	s_waitcnt lgkmcnt(0)
	s_barrier
	s_setprio 1
	s_waitcnt lgkmcnt(0)
	v_mfma_f32_16x16x32_bf16 v[68:71], v[4:7], v[36:39], v[0:3]
	v_mfma_f32_16x16x32_bf16 v[72:75], v[12:15], v[36:39], v[0:3]
	v_mfma_f32_16x16x32_bf16 v[76:79], v[4:7], v[44:47], v[0:3]
	v_mfma_f32_16x16x32_bf16 v[80:83], v[12:15], v[44:47], v[0:3]
	v_mfma_f32_16x16x32_bf16 v[84:87], v[4:7], v[52:55], v[0:3]
	v_mfma_f32_16x16x32_bf16 v[88:91], v[12:15], v[52:55], v[0:3]
	v_mfma_f32_16x16x32_bf16 v[92:95], v[4:7], v[60:63], v[0:3]
	v_mfma_f32_16x16x32_bf16 v[96:99], v[12:15], v[60:63], v[0:3]
	v_mfma_f32_16x16x32_bf16 v[68:71], v[8:11], v[40:43], v[68:71]
	v_mfma_f32_16x16x32_bf16 v[72:75], v[16:19], v[40:43], v[72:75]
	v_mfma_f32_16x16x32_bf16 v[76:79], v[8:11], v[48:51], v[76:79]
	v_mfma_f32_16x16x32_bf16 v[80:83], v[16:19], v[48:51], v[80:83]
	v_mfma_f32_16x16x32_bf16 v[84:87], v[8:11], v[56:59], v[84:87]
	v_mfma_f32_16x16x32_bf16 v[88:91], v[16:19], v[56:59], v[88:91]
	v_mfma_f32_16x16x32_bf16 v[92:95], v[8:11], v[64:67], v[92:95]
	v_mfma_f32_16x16x32_bf16 v[96:99], v[16:19], v[64:67], v[96:99]
	v_mfma_f32_16x16x32_bf16 v[100:103], v[20:23], v[36:39], v[0:3]
	v_mfma_f32_16x16x32_bf16 v[36:39], v[28:31], v[36:39], v[0:3]
	v_mfma_f32_16x16x32_bf16 v[100:103], v[24:27], v[40:43], v[100:103]
	v_mfma_f32_16x16x32_bf16 v[36:39], v[32:35], v[40:43], v[36:39]
	v_mfma_f32_16x16x32_bf16 v[40:43], v[20:23], v[44:47], v[0:3]
	v_mfma_f32_16x16x32_bf16 v[44:47], v[28:31], v[44:47], v[0:3]
	v_mfma_f32_16x16x32_bf16 v[40:43], v[24:27], v[48:51], v[40:43]
	v_mfma_f32_16x16x32_bf16 v[44:47], v[32:35], v[48:51], v[44:47]
	v_mfma_f32_16x16x32_bf16 v[48:51], v[20:23], v[52:55], v[0:3]
	v_mfma_f32_16x16x32_bf16 v[52:55], v[28:31], v[52:55], v[0:3]
	v_mfma_f32_16x16x32_bf16 v[48:51], v[24:27], v[56:59], v[48:51]
	v_mfma_f32_16x16x32_bf16 v[52:55], v[32:35], v[56:59], v[52:55]
	v_mfma_f32_16x16x32_bf16 v[56:59], v[20:23], v[60:63], v[0:3]
	v_mfma_f32_16x16x32_bf16 v[60:63], v[28:31], v[60:63], v[0:3]
	v_mfma_f32_16x16x32_bf16 v[56:59], v[24:27], v[64:67], v[56:59]
	v_mfma_f32_16x16x32_bf16 v[60:63], v[32:35], v[64:67], v[60:63]
	s_setprio 0
	s_barrier
	s_add_i32 s29, s29, s18
	v_lshl_add_u64 v[146:147], s[66:67], 0, v[148:149]
	s_mov_b64 s[36:37], 0x100
	s_add_i32 s22, s29, 0x2000
	v_lshl_add_u64 v[138:139], v[146:147], 0, s[36:37]
	s_mov_b32 m0, s29
	v_lshl_add_u64 v[150:151], s[66:67], 0, v[128:129]
	s_add_u32 s84, s66, 0x10100
	ds_read_b128 v[64:67], v137 offset:16384
	ds_read_b128 v[104:107], v137 offset:17408
	ds_read_b128 v[108:111], v137 offset:18432
	ds_read_b128 v[112:115], v137 offset:19456
	ds_read_b128 v[116:119], v137 offset:20480
	ds_read_b128 v[120:123], v137 offset:21504
	ds_read_b128 v[124:127], v137 offset:22528
	ds_read_b128 v[130:133], v137 offset:23552
	global_load_lds_dwordx4 v[138:139], off
	v_lshl_add_u64 v[138:139], v[150:151], 0, s[36:37]
	s_mov_b32 m0, s22
	s_addc_u32 s85, s67, 0
	s_add_i32 s23, s28, s18
	global_load_lds_dwordx4 v[138:139], off
	v_lshl_add_u64 v[138:139], s[84:85], 0, v[148:149]
	s_mov_b32 m0, s23
	s_add_i32 s28, s23, 0x2000
	global_load_lds_dwordx4 v[138:139], off
	v_lshl_add_u64 v[138:139], s[84:85], 0, v[128:129]
	s_mov_b32 m0, s28
	v_lshl_add_u64 v[152:153], s[64:65], 0, v[148:149]
	global_load_lds_dwordx4 v[138:139], off
	v_lshl_add_u64 v[138:139], v[152:153], 0, s[36:37]
	s_mov_b32 m0, s19
	v_lshl_add_u64 v[222:223], s[64:65], 0, v[128:129]
	global_load_lds_dwordx4 v[138:139], off
	v_lshl_add_u64 v[138:139], v[222:223], 0, s[36:37]
	s_mov_b32 m0, s63
	s_nop 0
	global_load_lds_dwordx4 v[138:139], off
	s_waitcnt vmcnt(8)
	s_waitcnt lgkmcnt(0)
	s_barrier
; #define PG8_STAGE(bufoff, gbase, voff) do { _Pragma("unroll") for (int _i = 0; _i < 2; ++_i) \
;         __builtin_amdgcn_global_load_lds((const unsigned*)((const char*)(gbase) + (voff)[_i]), (PG8_LAS unsigned*)(lds + (bufoff) + ldsw + _i * 8192), 16, 0, 0); } while (0)
; #define PG8_LDA(dst, b, h) do { _Pragma("unroll") for (int m = 0; m < 4; ++m) _Pragma("unroll") for (int k = 0; k < 2; ++k) dst[m][k] = *(const PG8_LAS bf16x8*)(lds + PG8_SA(b, h) + aoff + m * 2048 + k * 1024); } while (0)
; #define PG8_LDB(dst, b, h) do { _Pragma("unroll") for (int n = 0; n < 2; ++n) _Pragma("unroll") for (int k = 0; k < 2; ++k) dst[n][k] = *(const PG8_LAS bf16x8*)(lds + PG8_SB(b, h) + boff + n * 2048 + k * 1024); } while (0)
; #define PG8_MMA(ai, bj, At, Bt) do { __builtin_amdgcn_s_setprio(1); _Pragma("unroll") for (int m = 0; m < 4; ++m) _Pragma("unroll") for (int n = 0; n < 2; ++n) _Pragma("unroll") for (int k = 0; k < 2; ++k) \
;         acc[ai][bj][m][n] = __builtin_amdgcn_mfma_f32_16x16x32_bf16(Bt[n][k], At[m][k], acc[ai][bj][m][n], 0, 0, 0); __builtin_amdgcn_s_setprio(0); } while (0)
; #define PG8_WAIT_V(n) asm volatile("s_waitcnt vmcnt(" #n ")" ::: "memory")
; #define PG8_WAIT_L(n) asm volatile("s_waitcnt lgkmcnt(" #n ")" ::: "memory")
; #define PG8_BAR __builtin_amdgcn_s_barrier()
; #define PG8_SCHED __builtin_amdgcn_sched_barrier(0)
; template <class Epi, class Sched, bool ALIGN_EPI = false, bool SP2 = false>
; __device__ __forceinline__ void gemm_phase(PG8_LAS unsigned char* lds, const Gemm g, const Sched& S, const Epi& E, int wave_s) {
;     ...
;             PG8_WAIT_V(8); PG8_WAIT_L(0); PG8_BAR; PG8_MMA(0, 0, At, B0); PG8_MMA(0, 1, At, B1); PG8_BAR; PG8_SCHED;
;             PG8_LDA(At, 0, 1); PG8_STAGE(PG8_SB(0, 0), b2, voffB); PG8_STAGE(PG8_SB(0, 1), b2 + hstep, voffB); PG8_STAGE(PG8_SA(0, 0), a2, voffA);
;             PG8_WAIT_V(8); PG8_WAIT_L(0); PG8_BAR; PG8_MMA(1, 0, At, B0); PG8_MMA(1, 1, At, B1); PG8_BAR; PG8_SCHED;
;             PG8_LDB(B0, 1, 0); PG8_LDB(B1, 1, 1); PG8_SCHED; PG8_LDA(At, 1, 0); PG8_STAGE(PG8_SA(0, 1), a2 + hstep, voffA);
;             PG8_WAIT_V(8); PG8_WAIT_L(0); PG8_BAR; PG8_MMA(0, 0, At, B0); PG8_MMA(0, 1, At, B1); PG8_BAR; PG8_SCHED;
	s_setprio 1
	s_waitcnt lgkmcnt(0)
	v_mfma_f32_16x16x32_bf16 v[138:141], v[4:7], v[64:67], v[0:3]
	v_mfma_f32_16x16x32_bf16 v[156:159], v[4:7], v[108:111], v[0:3]
	v_mfma_f32_16x16x32_bf16 v[164:167], v[4:7], v[116:119], v[0:3]
	v_mfma_f32_16x16x32_bf16 v[4:7], v[4:7], v[124:127], v[0:3]
	v_mfma_f32_16x16x32_bf16 v[138:141], v[8:11], v[104:107], v[138:141]
	v_mfma_f32_16x16x32_bf16 v[156:159], v[8:11], v[112:115], v[156:159]
	v_mfma_f32_16x16x32_bf16 v[164:167], v[8:11], v[120:123], v[164:167]
	v_mfma_f32_16x16x32_bf16 v[4:7], v[8:11], v[130:133], v[4:7]
	v_mfma_f32_16x16x32_bf16 v[8:11], v[12:15], v[124:127], v[0:3]
	v_mfma_f32_16x16x32_bf16 v[142:145], v[12:15], v[64:67], v[0:3]
	v_mfma_f32_16x16x32_bf16 v[160:163], v[12:15], v[108:111], v[0:3]
	v_mfma_f32_16x16x32_bf16 v[168:171], v[12:15], v[116:119], v[0:3]
	v_mfma_f32_16x16x32_bf16 v[8:11], v[16:19], v[130:133], v[8:11]
	v_mfma_f32_16x16x32_bf16 v[142:145], v[16:19], v[104:107], v[142:145]
	v_mfma_f32_16x16x32_bf16 v[160:163], v[16:19], v[112:115], v[160:163]
	v_mfma_f32_16x16x32_bf16 v[168:171], v[16:19], v[120:123], v[168:171]
	v_mfma_f32_16x16x32_bf16 v[12:15], v[20:23], v[64:67], v[0:3]
	v_mfma_f32_16x16x32_bf16 v[16:19], v[28:31], v[64:67], v[0:3]
	v_mfma_f32_16x16x32_bf16 v[12:15], v[24:27], v[104:107], v[12:15]
	v_mfma_f32_16x16x32_bf16 v[16:19], v[32:35], v[104:107], v[16:19]
	v_mfma_f32_16x16x32_bf16 v[64:67], v[20:23], v[108:111], v[0:3]
	v_mfma_f32_16x16x32_bf16 v[104:107], v[28:31], v[108:111], v[0:3]
	v_mfma_f32_16x16x32_bf16 v[64:67], v[24:27], v[112:115], v[64:67]
	v_mfma_f32_16x16x32_bf16 v[104:107], v[32:35], v[112:115], v[104:107]
	v_mfma_f32_16x16x32_bf16 v[108:111], v[20:23], v[116:119], v[0:3]
	v_mfma_f32_16x16x32_bf16 v[112:115], v[28:31], v[116:119], v[0:3]
	v_mfma_f32_16x16x32_bf16 v[20:23], v[20:23], v[124:127], v[0:3]
	v_mfma_f32_16x16x32_bf16 v[0:3], v[28:31], v[124:127], v[0:3]
	v_mfma_f32_16x16x32_bf16 v[108:111], v[24:27], v[120:123], v[108:111]
	v_mfma_f32_16x16x32_bf16 v[112:115], v[32:35], v[120:123], v[112:115]
	v_mfma_f32_16x16x32_bf16 v[20:23], v[24:27], v[130:133], v[20:23]
	v_mfma_f32_16x16x32_bf16 v[0:3], v[32:35], v[130:133], v[0:3]
	s_setprio 0
	s_barrier
	s_add_i32 s73, 0, 0x18000
	s_add_i32 s57, 0, 0x1c000
	v_add_u32_e32 v227, s73, v135
	v_add_u32_e32 v228, s57, v135
	ds_read_b128 v[24:27], v227
	ds_read_b128 v[28:31], v227 offset:1024
	ds_read_b128 v[32:35], v227 offset:2048
	ds_read_b128 v[116:119], v227 offset:3072
	ds_read_b128 v[120:123], v228
	ds_read_b128 v[124:127], v228 offset:1024
	ds_read_b128 v[130:133], v228 offset:2048
	ds_read_b128 v[172:175], v228 offset:3072
	s_add_u32 s84, s64, 0x10100
	s_addc_u32 s85, s65, 0
	s_mov_b32 m0, s78
	v_lshl_add_u64 v[224:225], s[84:85], 0, v[148:149]
	ds_read_b128 v[176:179], v137 offset:32768
	ds_read_b128 v[180:183], v137 offset:33792
	ds_read_b128 v[184:187], v137 offset:34816
	ds_read_b128 v[188:191], v137 offset:35840
	ds_read_b128 v[206:209], v137 offset:36864
	ds_read_b128 v[210:213], v137 offset:37888
	ds_read_b128 v[214:217], v137 offset:38912
	ds_read_b128 v[218:221], v137 offset:39936
	global_load_lds_dwordx4 v[224:225], off
	v_lshl_add_u64 v[224:225], s[84:85], 0, v[128:129]
	s_mov_b32 m0, s79
	s_nop 0
	global_load_lds_dwordx4 v[224:225], off
	s_waitcnt vmcnt(8)
	s_waitcnt lgkmcnt(0)
	s_barrier
	s_setprio 1
	s_waitcnt lgkmcnt(0)
	v_mfma_f32_16x16x32_bf16 v[68:71], v[24:27], v[176:179], v[68:71]
	v_mfma_f32_16x16x32_bf16 v[72:75], v[32:35], v[176:179], v[72:75]
	v_mfma_f32_16x16x32_bf16 v[76:79], v[24:27], v[184:187], v[76:79]
	v_mfma_f32_16x16x32_bf16 v[80:83], v[32:35], v[184:187], v[80:83]
	v_mfma_f32_16x16x32_bf16 v[84:87], v[24:27], v[206:209], v[84:87]
	v_mfma_f32_16x16x32_bf16 v[88:91], v[32:35], v[206:209], v[88:91]
	v_mfma_f32_16x16x32_bf16 v[92:95], v[24:27], v[214:217], v[92:95]
	v_mfma_f32_16x16x32_bf16 v[96:99], v[32:35], v[214:217], v[96:99]
	v_mfma_f32_16x16x32_bf16 v[68:71], v[28:31], v[180:183], v[68:71]
	v_mfma_f32_16x16x32_bf16 v[72:75], v[116:119], v[180:183], v[72:75]
	v_mfma_f32_16x16x32_bf16 v[76:79], v[28:31], v[188:191], v[76:79]
	v_mfma_f32_16x16x32_bf16 v[80:83], v[116:119], v[188:191], v[80:83]
	v_mfma_f32_16x16x32_bf16 v[84:87], v[28:31], v[210:213], v[84:87]
	v_mfma_f32_16x16x32_bf16 v[88:91], v[116:119], v[210:213], v[88:91]
	v_mfma_f32_16x16x32_bf16 v[92:95], v[28:31], v[218:221], v[92:95]
	v_mfma_f32_16x16x32_bf16 v[96:99], v[116:119], v[218:221], v[96:99]
	v_mfma_f32_16x16x32_bf16 v[100:103], v[120:123], v[176:179], v[100:103]
	v_mfma_f32_16x16x32_bf16 v[36:39], v[130:133], v[176:179], v[36:39]
	v_mfma_f32_16x16x32_bf16 v[40:43], v[120:123], v[184:187], v[40:43]
	v_mfma_f32_16x16x32_bf16 v[44:47], v[130:133], v[184:187], v[44:47]
	v_mfma_f32_16x16x32_bf16 v[48:51], v[120:123], v[206:209], v[48:51]
	v_mfma_f32_16x16x32_bf16 v[52:55], v[130:133], v[206:209], v[52:55]
	v_mfma_f32_16x16x32_bf16 v[56:59], v[120:123], v[214:217], v[56:59]
	v_mfma_f32_16x16x32_bf16 v[60:63], v[130:133], v[214:217], v[60:63]
	v_mfma_f32_16x16x32_bf16 v[100:103], v[124:127], v[180:183], v[100:103]
	v_mfma_f32_16x16x32_bf16 v[36:39], v[172:175], v[180:183], v[36:39]
	v_mfma_f32_16x16x32_bf16 v[40:43], v[124:127], v[188:191], v[40:43]
	v_mfma_f32_16x16x32_bf16 v[44:47], v[172:175], v[188:191], v[44:47]
	v_mfma_f32_16x16x32_bf16 v[48:51], v[124:127], v[210:213], v[48:51]
	v_mfma_f32_16x16x32_bf16 v[52:55], v[172:175], v[210:213], v[52:55]
	v_mfma_f32_16x16x32_bf16 v[56:59], v[124:127], v[218:221], v[56:59]
	v_mfma_f32_16x16x32_bf16 v[60:63], v[172:175], v[218:221], v[60:63]
	s_setprio 0
	s_barrier
; #define PG8_STAGE(bufoff, gbase, voff) do { _Pragma("unroll") for (int _i = 0; _i < 2; ++_i) \
;         __builtin_amdgcn_global_load_lds((const unsigned*)((const char*)(gbase) + (voff)[_i]), (PG8_LAS unsigned*)(lds + (bufoff) + ldsw + _i * 8192), 16, 0, 0); } while (0)
; #define PG8_LDA(dst, b, h) do { _Pragma("unroll") for (int m = 0; m < 4; ++m) _Pragma("unroll") for (int k = 0; k < 2; ++k) dst[m][k] = *(const PG8_LAS bf16x8*)(lds + PG8_SA(b, h) + aoff + m * 2048 + k * 1024); } while (0)
; #define PG8_LDB(dst, b, h) do { _Pragma("unroll") for (int n = 0; n < 2; ++n) _Pragma("unroll") for (int k = 0; k < 2; ++k) dst[n][k] = *(const PG8_LAS bf16x8*)(lds + PG8_SB(b, h) + boff + n * 2048 + k * 1024); } while (0)
; #define PG8_MMA(ai, bj, At, Bt) do { __builtin_amdgcn_s_setprio(1); _Pragma("unroll") for (int m = 0; m < 4; ++m) _Pragma("unroll") for (int n = 0; n < 2; ++n) _Pragma("unroll") for (int k = 0; k < 2; ++k) \
;         acc[ai][bj][m][n] = __builtin_amdgcn_mfma_f32_16x16x32_bf16(Bt[n][k], At[m][k], acc[ai][bj][m][n], 0, 0, 0); __builtin_amdgcn_s_setprio(0); } while (0)
; #define PG8_WAIT_V(n) asm volatile("s_waitcnt vmcnt(" #n ")" ::: "memory")
; #define PG8_WAIT_L(n) asm volatile("s_waitcnt lgkmcnt(" #n ")" ::: "memory")
; #define PG8_BAR __builtin_amdgcn_s_barrier()
; #define PG8_SCHED __builtin_amdgcn_sched_barrier(0)
; template <class Epi, class Sched, bool ALIGN_EPI = false, bool SP2 = false>
; __device__ __forceinline__ void gemm_phase(PG8_LAS unsigned char* lds, const Gemm g, const Sched& S, const Epi& E, int wave_s) {
;     ...
;             PG8_LDB(B0, 0, 0); PG8_LDB(B1, 0, 1); PG8_SCHED; PG8_LDA(At, 0, 0); PG8_STAGE(PG8_SA(1, 1), a1 + hstep, voffA);
;             PG8_WAIT_V(8); PG8_WAIT_L(0); PG8_BAR; PG8_MMA(0, 0, At, B0); PG8_MMA(0, 1, At, B1); PG8_BAR; PG8_SCHED;
;     ...
;             PG8_LDA(At, 1, 1); PG8_STAGE(PG8_SB(1, 0), b3, voffB); PG8_STAGE(PG8_SB(1, 1), b3 + hstep, voffB); PG8_STAGE(PG8_SA(1, 0), a3, voffA);
;             PG8_WAIT_V(8); PG8_WAIT_L(0); PG8_BAR; PG8_MMA(1, 0, At, B0); PG8_MMA(1, 1, At, B1); PG8_BAR; PG8_SCHED;
;     ...
;             PG8_LDB(B0, 0, 0); PG8_SCHED; PG8_LDA(At, 0, 0); PG8_STAGE(PG8_SA(1, 1), a1 + hstep, voffA);
	s_add_i32 s73, s73, s18
	s_mov_b64 s[36:37], 0x180
	s_add_i32 s39, s73, 0x2000
	v_lshl_add_u64 v[146:147], v[146:147], 0, s[36:37]
	s_mov_b32 m0, s73
	s_add_u32 s66, s66, 0x10180
	ds_read_b128 v[176:179], v137 offset:49152
	ds_read_b128 v[180:183], v137 offset:50176
	ds_read_b128 v[184:187], v137 offset:51200
	ds_read_b128 v[188:191], v137 offset:52224
	ds_read_b128 v[206:209], v137 offset:53248
	ds_read_b128 v[210:213], v137 offset:54272
	ds_read_b128 v[214:217], v137 offset:55296
	ds_read_b128 v[218:221], v137 offset:56320
	global_load_lds_dwordx4 v[146:147], off
	v_lshl_add_u64 v[146:147], v[150:151], 0, s[36:37]
	s_mov_b32 m0, s39
	s_addc_u32 s67, s67, 0
	s_add_i32 s57, s57, s18
	global_load_lds_dwordx4 v[146:147], off
	v_lshl_add_u64 v[146:147], s[66:67], 0, v[148:149]
	s_mov_b32 m0, s57
	s_nop 0
	global_load_lds_dwordx4 v[146:147], off
	v_lshl_add_u64 v[146:147], s[66:67], 0, v[128:129]
	s_add_i32 s66, s57, 0x2000
	s_mov_b32 m0, s66
	s_nop 0
	global_load_lds_dwordx4 v[146:147], off
	v_lshl_add_u64 v[146:147], v[152:153], 0, s[36:37]
	s_mov_b32 m0, s76
	s_nop 0
	global_load_lds_dwordx4 v[146:147], off
	v_lshl_add_u64 v[146:147], v[222:223], 0, s[36:37]
	s_mov_b32 m0, s77
	s_nop 0
	global_load_lds_dwordx4 v[146:147], off
	s_waitcnt vmcnt(8)
	s_waitcnt lgkmcnt(0)
	s_barrier
	s_setprio 1
	s_waitcnt lgkmcnt(0)
	v_mfma_f32_16x16x32_bf16 v[4:7], v[24:27], v[214:217], v[4:7]
	v_mfma_f32_16x16x32_bf16 v[8:11], v[32:35], v[214:217], v[8:11]
	v_mfma_f32_16x16x32_bf16 v[138:141], v[24:27], v[176:179], v[138:141]
	v_mfma_f32_16x16x32_bf16 v[142:145], v[32:35], v[176:179], v[142:145]
	v_mfma_f32_16x16x32_bf16 v[156:159], v[24:27], v[184:187], v[156:159]
	v_mfma_f32_16x16x32_bf16 v[160:163], v[32:35], v[184:187], v[160:163]
	v_mfma_f32_16x16x32_bf16 v[164:167], v[24:27], v[206:209], v[164:167]
	v_mfma_f32_16x16x32_bf16 v[168:171], v[32:35], v[206:209], v[168:171]
	v_mfma_f32_16x16x32_bf16 v[4:7], v[28:31], v[218:221], v[4:7]
	v_mfma_f32_16x16x32_bf16 v[8:11], v[116:119], v[218:221], v[8:11]
	v_mfma_f32_16x16x32_bf16 v[138:141], v[28:31], v[180:183], v[138:141]
	v_mfma_f32_16x16x32_bf16 v[142:145], v[116:119], v[180:183], v[142:145]
	v_mfma_f32_16x16x32_bf16 v[156:159], v[28:31], v[188:191], v[156:159]
	v_mfma_f32_16x16x32_bf16 v[160:163], v[116:119], v[188:191], v[160:163]
	v_mfma_f32_16x16x32_bf16 v[164:167], v[28:31], v[210:213], v[164:167]
	v_mfma_f32_16x16x32_bf16 v[168:171], v[116:119], v[210:213], v[168:171]
	v_mfma_f32_16x16x32_bf16 v[12:15], v[120:123], v[176:179], v[12:15]
	v_mfma_f32_16x16x32_bf16 v[16:19], v[130:133], v[176:179], v[16:19]
	v_mfma_f32_16x16x32_bf16 v[24:27], v[120:123], v[184:187], v[64:67]
	v_mfma_f32_16x16x32_bf16 v[28:31], v[130:133], v[184:187], v[104:107]
	v_mfma_f32_16x16x32_bf16 v[32:35], v[120:123], v[206:209], v[108:111]
	v_mfma_f32_16x16x32_bf16 v[64:67], v[130:133], v[206:209], v[112:115]
	v_mfma_f32_16x16x32_bf16 v[20:23], v[120:123], v[214:217], v[20:23]
	v_mfma_f32_16x16x32_bf16 v[0:3], v[130:133], v[214:217], v[0:3]
	v_mfma_f32_16x16x32_bf16 v[12:15], v[124:127], v[180:183], v[12:15]
	v_mfma_f32_16x16x32_bf16 v[16:19], v[172:175], v[180:183], v[16:19]
	v_mfma_f32_16x16x32_bf16 v[24:27], v[124:127], v[188:191], v[24:27]
	v_mfma_f32_16x16x32_bf16 v[28:31], v[172:175], v[188:191], v[28:31]
	v_mfma_f32_16x16x32_bf16 v[32:35], v[124:127], v[210:213], v[32:35]
	v_mfma_f32_16x16x32_bf16 v[64:67], v[172:175], v[210:213], v[64:67]
	v_mfma_f32_16x16x32_bf16 v[20:23], v[124:127], v[218:221], v[20:23]
	v_mfma_f32_16x16x32_bf16 v[0:3], v[172:175], v[218:221], v[0:3]
	s_setprio 0
	s_barrier
	ds_read_b128 v[104:107], v205
	ds_read_b128 v[108:111], v205 offset:1024
	ds_read_b128 v[112:115], v205 offset:2048
	ds_read_b128 v[116:119], v205 offset:3072
	ds_read_b128 v[120:123], v226
	ds_read_b128 v[124:127], v226 offset:1024
	ds_read_b128 v[130:133], v226 offset:2048
	ds_read_b128 v[172:175], v226 offset:3072
	s_add_u32 s64, s64, 0x10180
	s_addc_u32 s65, s65, 0
	s_mov_b32 m0, s55
	v_lshl_add_u64 v[146:147], s[64:65], 0, v[148:149]
	ds_read_b128 v[176:179], v137
	ds_read_b128 v[180:183], v137 offset:1024
	ds_read_b128 v[184:187], v137 offset:2048
	ds_read_b128 v[188:191], v137 offset:3072
	ds_read_b128 v[206:209], v137 offset:4096
	ds_read_b128 v[210:213], v137 offset:5120
	ds_read_b128 v[214:217], v137 offset:6144
	ds_read_b128 v[218:221], v137 offset:7168
	global_load_lds_dwordx4 v[146:147], off
	v_lshl_add_u64 v[146:147], s[64:65], 0, v[128:129]
	s_mov_b32 m0, s5
	s_nop 0
	global_load_lds_dwordx4 v[146:147], off
	s_waitcnt vmcnt(8)
	s_waitcnt lgkmcnt(0)
	s_barrier
; #define PG8_STAGE(bufoff, gbase, voff) do { _Pragma("unroll") for (int _i = 0; _i < 2; ++_i) \
;         __builtin_amdgcn_global_load_lds((const unsigned*)((const char*)(gbase) + (voff)[_i]), (PG8_LAS unsigned*)(lds + (bufoff) + ldsw + _i * 8192), 16, 0, 0); } while (0)
; #define PG8_LDA(dst, b, h) do { _Pragma("unroll") for (int m = 0; m < 4; ++m) _Pragma("unroll") for (int k = 0; k < 2; ++k) dst[m][k] = *(const PG8_LAS bf16x8*)(lds + PG8_SA(b, h) + aoff + m * 2048 + k * 1024); } while (0)
; #define PG8_LDB(dst, b, h) do { _Pragma("unroll") for (int n = 0; n < 2; ++n) _Pragma("unroll") for (int k = 0; k < 2; ++k) dst[n][k] = *(const PG8_LAS bf16x8*)(lds + PG8_SB(b, h) + boff + n * 2048 + k * 1024); } while (0)
; #define PG8_MMA(ai, bj, At, Bt) do { __builtin_amdgcn_s_setprio(1); _Pragma("unroll") for (int m = 0; m < 4; ++m) _Pragma("unroll") for (int n = 0; n < 2; ++n) _Pragma("unroll") for (int k = 0; k < 2; ++k) \
;         acc[ai][bj][m][n] = __builtin_amdgcn_mfma_f32_16x16x32_bf16(Bt[n][k], At[m][k], acc[ai][bj][m][n], 0, 0, 0); __builtin_amdgcn_s_setprio(0); } while (0)
; #define PG8_WAIT_V(n) asm volatile("s_waitcnt vmcnt(" #n ")" ::: "memory")
; #define PG8_WAIT_L(n) asm volatile("s_waitcnt lgkmcnt(" #n ")" ::: "memory")
; #define PG8_BAR __builtin_amdgcn_s_barrier()
; #define PG8_SCHED __builtin_amdgcn_sched_barrier(0)
; template <class Epi, class Sched, bool ALIGN_EPI = false, bool SP2 = false>
; __device__ __forceinline__ void gemm_phase(PG8_LAS unsigned char* lds, const Gemm g, const Sched& S, const Epi& E, int wave_s) {
;     ...
;             PG8_LDB(B0, 0, 0); PG8_LDB(B1, 0, 1); PG8_SCHED; PG8_LDA(At, 0, 0); PG8_STAGE(PG8_SA(1, 1), a1 + hstep, voffA);
;             PG8_WAIT_V(8); PG8_WAIT_L(0); PG8_BAR; PG8_MMA(0, 0, At, B0); PG8_MMA(0, 1, At, B1); PG8_BAR; PG8_SCHED;
;             PG8_LDA(At, 0, 1); PG8_STAGE(PG8_SB(0, 0), b2, voffB); PG8_STAGE(PG8_SB(0, 1), b2 + hstep, voffB); PG8_STAGE(PG8_SA(0, 0), a2, voffA);
;             PG8_WAIT_V(8); PG8_WAIT_L(0); PG8_BAR; PG8_MMA(1, 0, At, B0); PG8_MMA(1, 1, At, B1); PG8_BAR; PG8_SCHED;
;             PG8_LDB(B0, 1, 0); PG8_LDB(B1, 1, 1); PG8_SCHED; PG8_LDA(At, 1, 0); PG8_STAGE(PG8_SA(0, 1), a2 + hstep, voffA);
;             PG8_WAIT_V(8); PG8_WAIT_L(0); PG8_BAR; PG8_MMA(0, 0, At, B0); PG8_MMA(0, 1, At, B1); PG8_BAR; PG8_SCHED;
	s_setprio 1
	s_waitcnt lgkmcnt(0)
	v_mfma_f32_16x16x32_bf16 v[92:95], v[104:107], v[214:217], v[92:95]
	v_mfma_f32_16x16x32_bf16 v[68:71], v[104:107], v[176:179], v[68:71]
	v_mfma_f32_16x16x32_bf16 v[72:75], v[112:115], v[176:179], v[72:75]
	v_mfma_f32_16x16x32_bf16 v[76:79], v[104:107], v[184:187], v[76:79]
	v_mfma_f32_16x16x32_bf16 v[80:83], v[112:115], v[184:187], v[80:83]
	v_mfma_f32_16x16x32_bf16 v[84:87], v[104:107], v[206:209], v[84:87]
	v_mfma_f32_16x16x32_bf16 v[88:91], v[112:115], v[206:209], v[88:91]
	v_mfma_f32_16x16x32_bf16 v[222:225], v[108:111], v[218:221], v[92:95]
	v_mfma_f32_16x16x32_bf16 v[92:95], v[112:115], v[214:217], v[96:99]
	v_mfma_f32_16x16x32_bf16 v[68:71], v[108:111], v[180:183], v[68:71]
	v_mfma_f32_16x16x32_bf16 v[72:75], v[116:119], v[180:183], v[72:75]
	v_mfma_f32_16x16x32_bf16 v[76:79], v[108:111], v[188:191], v[76:79]
	v_mfma_f32_16x16x32_bf16 v[80:83], v[116:119], v[188:191], v[80:83]
	v_mfma_f32_16x16x32_bf16 v[84:87], v[108:111], v[210:213], v[84:87]
	v_mfma_f32_16x16x32_bf16 v[88:91], v[116:119], v[210:213], v[88:91]
	v_mfma_f32_16x16x32_bf16 v[96:99], v[116:119], v[218:221], v[92:95]
	v_mfma_f32_16x16x32_bf16 v[92:95], v[120:123], v[176:179], v[100:103]
	v_mfma_f32_16x16x32_bf16 v[36:39], v[130:133], v[176:179], v[36:39]
	v_mfma_f32_16x16x32_bf16 v[40:43], v[120:123], v[184:187], v[40:43]
	v_mfma_f32_16x16x32_bf16 v[44:47], v[130:133], v[184:187], v[44:47]
	v_mfma_f32_16x16x32_bf16 v[48:51], v[120:123], v[206:209], v[48:51]
	v_mfma_f32_16x16x32_bf16 v[52:55], v[130:133], v[206:209], v[52:55]
	v_mfma_f32_16x16x32_bf16 v[56:59], v[120:123], v[214:217], v[56:59]
	v_mfma_f32_16x16x32_bf16 v[60:63], v[130:133], v[214:217], v[60:63]
	v_mfma_f32_16x16x32_bf16 v[100:103], v[124:127], v[180:183], v[92:95]
	v_mfma_f32_16x16x32_bf16 v[36:39], v[172:175], v[180:183], v[36:39]
	v_mfma_f32_16x16x32_bf16 v[40:43], v[124:127], v[188:191], v[40:43]
	v_mfma_f32_16x16x32_bf16 v[44:47], v[172:175], v[188:191], v[44:47]
	v_mfma_f32_16x16x32_bf16 v[48:51], v[124:127], v[210:213], v[48:51]
	v_mfma_f32_16x16x32_bf16 v[52:55], v[172:175], v[210:213], v[52:55]
	v_mfma_f32_16x16x32_bf16 v[56:59], v[124:127], v[218:221], v[56:59]
	v_mfma_f32_16x16x32_bf16 v[60:63], v[172:175], v[218:221], v[60:63]
	s_setprio 0
	s_barrier
	s_mov_b32 m0, s29
	v_lshl_add_u64 v[146:147], s[74:75], 0, v[148:149]
	s_add_u32 s64, s74, 0x10000
	ds_read_b128 v[92:95], v137 offset:16384
	ds_read_b128 v[176:179], v137 offset:17408
	ds_read_b128 v[180:183], v137 offset:18432
	ds_read_b128 v[184:187], v137 offset:19456
	ds_read_b128 v[188:191], v137 offset:20480
	ds_read_b128 v[206:209], v137 offset:21504
	ds_read_b128 v[210:213], v137 offset:22528
	ds_read_b128 v[214:217], v137 offset:23552
	global_load_lds_dwordx4 v[146:147], off
	v_lshl_add_u64 v[150:151], s[74:75], 0, v[128:129]
	s_mov_b32 m0, s22
	s_addc_u32 s65, s75, 0
	global_load_lds_dwordx4 v[150:151], off
	v_lshl_add_u64 v[152:153], s[64:65], 0, v[148:149]
	s_mov_b32 m0, s23
	v_lshl_add_u64 v[250:251], vcc, 0, v[128:129]
	global_load_lds_dwordx4 v[152:153], off
	v_lshl_add_u64 v[152:153], s[64:65], 0, v[128:129]
	s_mov_b32 m0, s28
	s_nop 0
	global_load_lds_dwordx4 v[152:153], off
	v_lshl_add_u64 v[152:153], vcc, 0, v[148:149]
	s_mov_b32 m0, s19
	s_nop 0
	global_load_lds_dwordx4 v[152:153], off
	s_mov_b32 m0, s63
	s_nop 0
	global_load_lds_dwordx4 v[250:251], off
	s_waitcnt vmcnt(8)
	s_waitcnt lgkmcnt(0)
	s_barrier
	s_setprio 1
	s_waitcnt lgkmcnt(0)
	v_mfma_f32_16x16x32_bf16 v[4:7], v[104:107], v[210:213], v[4:7]
	v_mfma_f32_16x16x32_bf16 v[8:11], v[112:115], v[210:213], v[8:11]
	v_mfma_f32_16x16x32_bf16 v[138:141], v[104:107], v[92:95], v[138:141]
	v_mfma_f32_16x16x32_bf16 v[142:145], v[112:115], v[92:95], v[142:145]
	v_mfma_f32_16x16x32_bf16 v[156:159], v[104:107], v[180:183], v[156:159]
	v_mfma_f32_16x16x32_bf16 v[160:163], v[112:115], v[180:183], v[160:163]
	v_mfma_f32_16x16x32_bf16 v[164:167], v[104:107], v[188:191], v[164:167]
	v_mfma_f32_16x16x32_bf16 v[168:171], v[112:115], v[188:191], v[168:171]
	v_mfma_f32_16x16x32_bf16 v[4:7], v[108:111], v[214:217], v[4:7]
	v_mfma_f32_16x16x32_bf16 v[8:11], v[116:119], v[214:217], v[8:11]
	v_mfma_f32_16x16x32_bf16 v[138:141], v[108:111], v[176:179], v[138:141]
	v_mfma_f32_16x16x32_bf16 v[142:145], v[116:119], v[176:179], v[142:145]
	v_mfma_f32_16x16x32_bf16 v[156:159], v[108:111], v[184:187], v[156:159]
	v_mfma_f32_16x16x32_bf16 v[160:163], v[116:119], v[184:187], v[160:163]
	v_mfma_f32_16x16x32_bf16 v[164:167], v[108:111], v[206:209], v[164:167]
	v_mfma_f32_16x16x32_bf16 v[168:171], v[116:119], v[206:209], v[168:171]
	v_mfma_f32_16x16x32_bf16 v[12:15], v[120:123], v[92:95], v[12:15]
	v_mfma_f32_16x16x32_bf16 v[218:221], v[124:127], v[176:179], v[12:15]
	v_mfma_f32_16x16x32_bf16 v[12:15], v[130:133], v[92:95], v[16:19]
	v_mfma_f32_16x16x32_bf16 v[16:19], v[172:175], v[176:179], v[12:15]
	v_mfma_f32_16x16x32_bf16 v[12:15], v[120:123], v[180:183], v[24:27]
	v_mfma_f32_16x16x32_bf16 v[176:179], v[124:127], v[184:187], v[12:15]
	v_mfma_f32_16x16x32_bf16 v[12:15], v[130:133], v[180:183], v[28:31]
	v_mfma_f32_16x16x32_bf16 v[180:183], v[172:175], v[184:187], v[12:15]
	v_mfma_f32_16x16x32_bf16 v[12:15], v[120:123], v[188:191], v[32:35]
	v_mfma_f32_16x16x32_bf16 v[184:187], v[124:127], v[206:209], v[12:15]
	v_mfma_f32_16x16x32_bf16 v[12:15], v[130:133], v[188:191], v[64:67]
	v_mfma_f32_16x16x32_bf16 v[0:3], v[130:133], v[210:213], v[0:3]
	v_mfma_f32_16x16x32_bf16 v[188:191], v[172:175], v[206:209], v[12:15]
	v_mfma_f32_16x16x32_bf16 v[12:15], v[120:123], v[210:213], v[20:23]
	v_mfma_f32_16x16x32_bf16 v[0:3], v[172:175], v[214:217], v[0:3]
	v_mfma_f32_16x16x32_bf16 v[206:209], v[124:127], v[214:217], v[12:15]
	s_setprio 0
	s_barrier
; #define PG8_STAGE(bufoff, gbase, voff) do { _Pragma("unroll") for (int _i = 0; _i < 2; ++_i) \
;         __builtin_amdgcn_global_load_lds((const unsigned*)((const char*)(gbase) + (voff)[_i]), (PG8_LAS unsigned*)(lds + (bufoff) + ldsw + _i * 8192), 16, 0, 0); } while (0)
; #define PG8_LDA(dst, b, h) do { _Pragma("unroll") for (int m = 0; m < 4; ++m) _Pragma("unroll") for (int k = 0; k < 2; ++k) dst[m][k] = *(const PG8_LAS bf16x8*)(lds + PG8_SA(b, h) + aoff + m * 2048 + k * 1024); } while (0)
; #define PG8_LDB(dst, b, h) do { _Pragma("unroll") for (int n = 0; n < 2; ++n) _Pragma("unroll") for (int k = 0; k < 2; ++k) dst[n][k] = *(const PG8_LAS bf16x8*)(lds + PG8_SB(b, h) + boff + n * 2048 + k * 1024); } while (0)
; #define PG8_MMA(ai, bj, At, Bt) do { __builtin_amdgcn_s_setprio(1); _Pragma("unroll") for (int m = 0; m < 4; ++m) _Pragma("unroll") for (int n = 0; n < 2; ++n) _Pragma("unroll") for (int k = 0; k < 2; ++k) \
;         acc[ai][bj][m][n] = __builtin_amdgcn_mfma_f32_16x16x32_bf16(Bt[n][k], At[m][k], acc[ai][bj][m][n], 0, 0, 0); __builtin_amdgcn_s_setprio(0); } while (0)
; #define PG8_WAIT_V(n) asm volatile("s_waitcnt vmcnt(" #n ")" ::: "memory")
; #define PG8_WAIT_L(n) asm volatile("s_waitcnt lgkmcnt(" #n ")" ::: "memory")
; #define PG8_BAR __builtin_amdgcn_s_barrier()
; #define PG8_SCHED __builtin_amdgcn_sched_barrier(0)
; template <class Epi, class Sched, bool ALIGN_EPI = false, bool SP2 = false>
; __device__ __forceinline__ void gemm_phase(PG8_LAS unsigned char* lds, const Gemm g, const Sched& S, const Epi& E, int wave_s) {
;     ...
;             PG8_LDB(B0, 1, 0); PG8_LDB(B1, 1, 1); PG8_SCHED; PG8_LDA(At, 1, 0); PG8_STAGE(PG8_SA(0, 1), a2 + hstep, voffA);
;             PG8_WAIT_V(8); PG8_WAIT_L(0); PG8_BAR; PG8_MMA(0, 0, At, B0); PG8_MMA(0, 1, At, B1); PG8_BAR; PG8_SCHED;
;             PG8_LDA(At, 1, 1); PG8_STAGE(PG8_SB(1, 0), b3, voffB); PG8_STAGE(PG8_SB(1, 1), b3 + hstep, voffB); PG8_STAGE(PG8_SA(1, 0), a3, voffA);
;             PG8_WAIT_V(8); PG8_WAIT_L(0); PG8_BAR; PG8_MMA(1, 0, At, B0); PG8_MMA(1, 1, At, B1); PG8_BAR; PG8_SCHED;
	s_nop 3
	ds_read_b128 v[12:15], v227
	ds_read_b128 v[20:23], v227 offset:1024
	ds_read_b128 v[32:35], v227 offset:2048
	ds_read_b128 v[130:133], v227 offset:3072
	ds_read_b128 v[172:175], v228
	ds_read_b128 v[210:213], v228 offset:1024
	ds_read_b128 v[214:217], v228 offset:2048
	ds_read_b128 v[226:229], v228 offset:3072
	s_add_u32 s22, vcc_lo, 0x10000
	s_addc_u32 s23, vcc_hi, 0
	s_mov_b32 m0, s78
	v_lshl_add_u64 v[92:93], s[22:23], 0, v[148:149]
	ds_read_b128 v[24:27], v137 offset:32768
	ds_read_b128 v[28:31], v137 offset:33792
	ds_read_b128 v[64:67], v137 offset:34816
	ds_read_b128 v[230:233], v137 offset:35840
	ds_read_b128 v[234:237], v137 offset:36864
	ds_read_b128 v[238:241], v137 offset:37888
	ds_read_b128 v[242:245], v137 offset:38912
	ds_read_b128 v[246:249], v137 offset:39936
	global_load_lds_dwordx4 v[92:93], off
	v_lshl_add_u64 v[92:93], s[22:23], 0, v[128:129]
	s_mov_b32 m0, s79
	s_nop 0
	global_load_lds_dwordx4 v[92:93], off
	s_waitcnt vmcnt(8)
	s_waitcnt lgkmcnt(0)
	s_barrier
	s_setprio 1
	s_waitcnt lgkmcnt(0)
	v_mfma_f32_16x16x32_bf16 v[68:71], v[12:15], v[24:27], v[68:71]
	v_mfma_f32_16x16x32_bf16 v[124:127], v[20:23], v[28:31], v[68:71]
	v_mfma_f32_16x16x32_bf16 v[68:71], v[32:35], v[24:27], v[72:75]
	v_mfma_f32_16x16x32_bf16 v[120:123], v[130:133], v[28:31], v[68:71]
	v_mfma_f32_16x16x32_bf16 v[68:71], v[12:15], v[64:67], v[76:79]
	v_mfma_f32_16x16x32_bf16 v[108:111], v[20:23], v[230:233], v[68:71]
	v_mfma_f32_16x16x32_bf16 v[68:71], v[32:35], v[64:67], v[80:83]
	v_mfma_f32_16x16x32_bf16 v[104:107], v[130:133], v[230:233], v[68:71]
	v_mfma_f32_16x16x32_bf16 v[68:71], v[12:15], v[234:237], v[84:87]
	v_mfma_f32_16x16x32_bf16 v[92:95], v[20:23], v[238:241], v[68:71]
	v_mfma_f32_16x16x32_bf16 v[68:71], v[32:35], v[234:237], v[88:91]
	v_mfma_f32_16x16x32_bf16 v[88:91], v[130:133], v[238:241], v[68:71]
	v_mfma_f32_16x16x32_bf16 v[68:71], v[12:15], v[242:245], v[222:225]
	v_mfma_f32_16x16x32_bf16 v[76:79], v[20:23], v[246:249], v[68:71]
	v_mfma_f32_16x16x32_bf16 v[68:71], v[32:35], v[242:245], v[96:99]
	v_mfma_f32_16x16x32_bf16 v[72:75], v[130:133], v[246:249], v[68:71]
	v_mfma_f32_16x16x32_bf16 v[68:71], v[172:175], v[24:27], v[100:103]
	v_mfma_f32_16x16x32_bf16 v[24:27], v[214:217], v[24:27], v[36:39]
	v_mfma_f32_16x16x32_bf16 v[112:115], v[226:229], v[28:31], v[24:27]
	v_mfma_f32_16x16x32_bf16 v[24:27], v[172:175], v[64:67], v[40:43]
	v_mfma_f32_16x16x32_bf16 v[100:103], v[210:213], v[230:233], v[24:27]
	v_mfma_f32_16x16x32_bf16 v[24:27], v[214:217], v[64:67], v[44:47]
	v_mfma_f32_16x16x32_bf16 v[96:99], v[226:229], v[230:233], v[24:27]
	v_mfma_f32_16x16x32_bf16 v[24:27], v[172:175], v[234:237], v[48:51]
	v_mfma_f32_16x16x32_bf16 v[84:87], v[210:213], v[238:241], v[24:27]
	v_mfma_f32_16x16x32_bf16 v[24:27], v[214:217], v[234:237], v[52:55]
	v_mfma_f32_16x16x32_bf16 v[80:83], v[226:229], v[238:241], v[24:27]
	v_mfma_f32_16x16x32_bf16 v[24:27], v[172:175], v[242:245], v[56:59]
	v_mfma_f32_16x16x32_bf16 v[116:119], v[210:213], v[28:31], v[68:71]
	v_mfma_f32_16x16x32_bf16 v[68:71], v[210:213], v[246:249], v[24:27]
	v_mfma_f32_16x16x32_bf16 v[24:27], v[214:217], v[242:245], v[60:63]
	v_mfma_f32_16x16x32_bf16 v[64:67], v[226:229], v[246:249], v[24:27]
	s_setprio 0
	s_barrier
	s_mov_b32 m0, s73
	s_nop 3
	v_lshl_add_u64 v[24:25], v[146:147], 0, s[34:35]
	s_add_u32 s22, s74, 0x10080
	ds_read_b128 v[36:39], v137 offset:49152
	ds_read_b128 v[48:51], v137 offset:50176
	ds_read_b128 v[222:225], v137 offset:51200
	ds_read_b128 v[230:233], v137 offset:52224
	ds_read_b128 v[234:237], v137 offset:53248
	ds_read_b128 v[238:241], v137 offset:54272
	ds_read_b128 v[242:245], v137 offset:55296
	ds_read_b128 v[246:249], v137 offset:56320
	global_load_lds_dwordx4 v[24:25], off
	v_lshl_add_u64 v[24:25], v[150:151], 0, s[34:35]
	s_mov_b32 m0, s39
	s_addc_u32 s23, s75, 0
	global_load_lds_dwordx4 v[24:25], off
	v_lshl_add_u64 v[24:25], s[22:23], 0, v[148:149]
	s_mov_b32 m0, s57
	s_nop 0
	global_load_lds_dwordx4 v[24:25], off
	v_lshl_add_u64 v[24:25], s[22:23], 0, v[128:129]
	s_mov_b32 m0, s66
	s_nop 0
	global_load_lds_dwordx4 v[24:25], off
	v_lshl_add_u64 v[24:25], v[152:153], 0, s[34:35]
	s_mov_b32 m0, s76
	s_nop 0
	global_load_lds_dwordx4 v[24:25], off
	v_lshl_add_u64 v[24:25], v[250:251], 0, s[34:35]
	s_mov_b32 m0, s77
	s_nop 0
	global_load_lds_dwordx4 v[24:25], off
	s_waitcnt vmcnt(8)
	s_waitcnt lgkmcnt(0)
	s_barrier
	s_setprio 1
	s_waitcnt lgkmcnt(0)
	v_mfma_f32_16x16x32_bf16 v[24:27], v[12:15], v[36:39], v[138:141]
	v_mfma_f32_16x16x32_bf16 v[60:63], v[20:23], v[48:51], v[24:27]
	v_mfma_f32_16x16x32_bf16 v[24:27], v[32:35], v[36:39], v[142:145]
	v_mfma_f32_16x16x32_bf16 v[56:59], v[130:133], v[48:51], v[24:27]
	v_mfma_f32_16x16x32_bf16 v[24:27], v[12:15], v[222:225], v[156:159]
	v_mfma_f32_16x16x32_bf16 v[44:47], v[20:23], v[230:233], v[24:27]
	v_mfma_f32_16x16x32_bf16 v[24:27], v[32:35], v[222:225], v[160:163]
	v_mfma_f32_16x16x32_bf16 v[40:43], v[130:133], v[230:233], v[24:27]
	v_mfma_f32_16x16x32_bf16 v[24:27], v[12:15], v[234:237], v[164:167]
	v_mfma_f32_16x16x32_bf16 v[4:7], v[12:15], v[242:245], v[4:7]
	v_mfma_f32_16x16x32_bf16 v[28:31], v[20:23], v[238:241], v[24:27]
	v_mfma_f32_16x16x32_bf16 v[24:27], v[32:35], v[234:237], v[168:171]
	v_mfma_f32_16x16x32_bf16 v[12:15], v[20:23], v[246:249], v[4:7]
	v_mfma_f32_16x16x32_bf16 v[4:7], v[32:35], v[242:245], v[8:11]
	v_mfma_f32_16x16x32_bf16 v[24:27], v[130:133], v[238:241], v[24:27]
	v_mfma_f32_16x16x32_bf16 v[8:11], v[130:133], v[246:249], v[4:7]
	v_mfma_f32_16x16x32_bf16 v[4:7], v[172:175], v[36:39], v[218:221]
	v_mfma_f32_16x16x32_bf16 v[52:55], v[210:213], v[48:51], v[4:7]
	v_mfma_f32_16x16x32_bf16 v[4:7], v[214:217], v[36:39], v[16:19]
	v_mfma_f32_16x16x32_bf16 v[48:51], v[226:229], v[48:51], v[4:7]
	v_mfma_f32_16x16x32_bf16 v[4:7], v[172:175], v[222:225], v[176:179]
	v_mfma_f32_16x16x32_bf16 v[36:39], v[210:213], v[230:233], v[4:7]
	v_mfma_f32_16x16x32_bf16 v[4:7], v[214:217], v[222:225], v[180:183]
	v_mfma_f32_16x16x32_bf16 v[32:35], v[226:229], v[230:233], v[4:7]
	v_mfma_f32_16x16x32_bf16 v[4:7], v[172:175], v[234:237], v[184:187]
	v_mfma_f32_16x16x32_bf16 v[20:23], v[210:213], v[238:241], v[4:7]
	v_mfma_f32_16x16x32_bf16 v[4:7], v[214:217], v[234:237], v[188:191]
	v_mfma_f32_16x16x32_bf16 v[16:19], v[226:229], v[238:241], v[4:7]
	v_mfma_f32_16x16x32_bf16 v[4:7], v[172:175], v[242:245], v[206:209]
	v_mfma_f32_16x16x32_bf16 v[0:3], v[214:217], v[242:245], v[0:3]
	v_mfma_f32_16x16x32_bf16 v[4:7], v[210:213], v[246:249], v[4:7]
	v_mfma_f32_16x16x32_bf16 v[0:3], v[226:229], v[246:249], v[0:3]
	s_setprio 0
	s_barrier
	s_andn2_b64 vcc, exec, s[48:49]
	s_cbranch_vccnz .LBB0_490
	s_barrier
